# loop-edge rotation (7.11): K-loop control + next-iteration pointer-select SALU moved from the load-segment head into the last MMA segment's MFMA gaps
# speedup vs baseline: 1.0001x; 1.0001x over previous
.LBB0_169:
	s_cmp_eq_u32 s64, 0
	s_cselect_b32 s0, s59, 0x5cc00000
	s_cselect_b32 s21, s60, 0x2fb00000
	s_add_u32 s0, s4, s0
	s_addc_u32 s28, s5, 0
	s_ashr_i32 s23, s22, 31
	s_lshl_b64 s[26:27], s[22:23], 21
	s_add_u32 s26, s0, s26
	s_addc_u32 s27, s28, s27
	s_and_b64 s[28:29], s[24:25], exec
	s_cselect_b32 s23, s27, s43
	s_cselect_b32 s41, s26, s42
	s_add_u32 s0, s4, s21
	s_addc_u32 s52, s5, 0
	s_ashr_i32 s21, s20, 31
	s_lshl_b64 s[28:29], s[20:21], 21
	s_add_u32 s28, s0, s28
	s_addc_u32 s29, s52, s29
	s_and_b64 s[52:53], s[24:25], exec
	s_cselect_b32 s21, s29, s51
	s_cselect_b32 s66, s28, s50
	s_add_u32 s42, s42, 0x100080
	s_addc_u32 s43, s43, 0
	s_add_u32 s67, s50, 0x100
	v_mov_b32_e32 v8, 0
	s_addc_u32 s68, s51, 0
	s_mov_b32 s70, -2
	v_mov_b32_e32 v9, 0
	v_mov_b64_e32 v[10:11], 0
	v_mov_b64_e32 v[12:13], 0
	v_mov_b64_e32 v[14:15], 0
	v_mov_b64_e32 v[24:25], 0
	v_mov_b64_e32 v[26:27], 0
	v_mov_b64_e32 v[28:29], 0
	v_mov_b64_e32 v[30:31], 0
	v_mov_b64_e32 v[40:41], 0
	v_mov_b64_e32 v[42:43], 0
	v_mov_b64_e32 v[44:45], 0
	v_mov_b64_e32 v[46:47], 0
	v_mov_b64_e32 v[56:57], 0
	v_mov_b64_e32 v[58:59], 0
	v_mov_b64_e32 v[60:61], 0
	v_mov_b64_e32 v[62:63], 0
	v_mov_b64_e32 v[16:17], 0
	v_mov_b64_e32 v[18:19], 0
	v_mov_b64_e32 v[20:21], 0
	v_mov_b64_e32 v[22:23], 0
	v_mov_b64_e32 v[32:33], 0
	v_mov_b64_e32 v[34:35], 0
	v_mov_b64_e32 v[36:37], 0
	v_mov_b64_e32 v[38:39], 0
	v_mov_b64_e32 v[48:49], 0
	v_mov_b64_e32 v[50:51], 0
	v_mov_b64_e32 v[52:53], 0
	v_mov_b64_e32 v[54:55], 0
	v_mov_b64_e32 v[64:65], 0
	v_mov_b64_e32 v[66:67], 0
	v_mov_b64_e32 v[68:69], 0
	v_mov_b64_e32 v[70:71], 0
	v_mov_b64_e32 v[72:73], 0
	v_mov_b64_e32 v[74:75], 0
	v_mov_b64_e32 v[76:77], 0
	v_mov_b64_e32 v[78:79], 0
	v_mov_b64_e32 v[88:89], 0
	v_mov_b64_e32 v[90:91], 0
	v_mov_b64_e32 v[92:93], 0
	v_mov_b64_e32 v[94:95], 0
	v_mov_b64_e32 v[104:105], 0
	v_mov_b64_e32 v[106:107], 0
	v_mov_b64_e32 v[108:109], 0
	v_mov_b64_e32 v[110:111], 0
	v_mov_b64_e32 v[120:121], 0
	v_mov_b64_e32 v[122:123], 0
	v_mov_b64_e32 v[124:125], 0
	v_mov_b64_e32 v[126:127], 0
	v_mov_b64_e32 v[80:81], 0
	v_mov_b64_e32 v[82:83], 0
	v_mov_b64_e32 v[84:85], 0
	v_mov_b64_e32 v[86:87], 0
	v_mov_b64_e32 v[96:97], 0
	v_mov_b64_e32 v[98:99], 0
	v_mov_b64_e32 v[100:101], 0
	v_mov_b64_e32 v[102:103], 0
	v_mov_b64_e32 v[112:113], 0
	v_mov_b64_e32 v[114:115], 0
	v_mov_b64_e32 v[116:117], 0
	v_mov_b64_e32 v[118:119], 0
	v_mov_b64_e32 v[128:129], 0
	v_mov_b64_e32 v[130:131], 0
	v_mov_b64_e32 v[132:133], 0
	v_mov_b64_e32 v[134:135], 0
	s_add_u32 s0, s42, 0xfff00080
	s_addc_u32 s50, s43, -1
	s_cmp_eq_u32 s70, 60
	s_cselect_b32 s53, s23, s50
	s_cselect_b32 s52, s41, s0
	s_cselect_b32 s51, s21, s68
	s_cselect_b32 s50, s66, s67
	s_add_i32 m0, s31, 0xc000
.LBB0_170:
	ds_read_b128 v[136:139], v191
	ds_read_b128 v[158:161], v191 offset:1024
	ds_read_b128 v[162:165], v191 offset:2048
	ds_read_b128 v[166:169], v191 offset:3072
	ds_read_b128 v[170:173], v192
	ds_read_b128 v[174:177], v192 offset:1024
	ds_read_b128 v[178:181], v192 offset:2048
	ds_read_b128 v[194:197], v192 offset:3072
	ds_read_b128 v[198:201], v193
	ds_read_b128 v[202:205], v193 offset:1024
	ds_read_b128 v[206:209], v193 offset:2048
	ds_read_b128 v[210:213], v193 offset:3072
	ds_read_b128 v[214:217], v193 offset:4096
	ds_read_b128 v[218:221], v193 offset:5120
	ds_read_b128 v[222:225], v193 offset:6144
	ds_read_b128 v[226:229], v193 offset:7168
	global_load_lds_dwordx4 v152, s[42:43]
	s_add_i32 m0, s31, 0xe000
	s_nop 0
	global_load_lds_dwordx4 v154, s[42:43]
	s_waitcnt vmcnt(8)
	s_waitcnt lgkmcnt(0)
	s_setprio 1
	s_barrier
	v_mfma_f32_16x16x32_bf16 v[132:135], v[136:139], v[198:201], v[132:135]
	v_mfma_f32_16x16x32_bf16 v[128:131], v[162:165], v[198:201], v[128:131]
	v_mfma_f32_16x16x32_bf16 v[116:119], v[136:139], v[206:209], v[116:119]
	v_mfma_f32_16x16x32_bf16 v[112:115], v[162:165], v[206:209], v[112:115]
	v_mfma_f32_16x16x32_bf16 v[100:103], v[136:139], v[214:217], v[100:103]
	v_mfma_f32_16x16x32_bf16 v[96:99], v[162:165], v[214:217], v[96:99]
	v_mfma_f32_16x16x32_bf16 v[84:87], v[136:139], v[222:225], v[84:87]
	v_mfma_f32_16x16x32_bf16 v[80:83], v[162:165], v[222:225], v[80:83]
	v_mfma_f32_16x16x32_bf16 v[132:135], v[158:161], v[202:205], v[132:135]
	v_mfma_f32_16x16x32_bf16 v[128:131], v[166:169], v[202:205], v[128:131]
	v_mfma_f32_16x16x32_bf16 v[116:119], v[158:161], v[210:213], v[116:119]
	v_mfma_f32_16x16x32_bf16 v[112:115], v[166:169], v[210:213], v[112:115]
	v_mfma_f32_16x16x32_bf16 v[100:103], v[158:161], v[218:221], v[100:103]
	v_mfma_f32_16x16x32_bf16 v[96:99], v[166:169], v[218:221], v[96:99]
	v_mfma_f32_16x16x32_bf16 v[84:87], v[158:161], v[226:229], v[84:87]
	v_mfma_f32_16x16x32_bf16 v[80:83], v[166:169], v[226:229], v[80:83]
	s_setprio 0
	s_setprio 1
	v_mfma_f32_16x16x32_bf16 v[124:127], v[170:173], v[198:201], v[124:127]
	v_mfma_f32_16x16x32_bf16 v[120:123], v[178:181], v[198:201], v[120:123]
	v_mfma_f32_16x16x32_bf16 v[108:111], v[170:173], v[206:209], v[108:111]
	v_mfma_f32_16x16x32_bf16 v[104:107], v[178:181], v[206:209], v[104:107]
	v_mfma_f32_16x16x32_bf16 v[92:95], v[170:173], v[214:217], v[92:95]
	v_mfma_f32_16x16x32_bf16 v[88:91], v[178:181], v[214:217], v[88:91]
	v_mfma_f32_16x16x32_bf16 v[76:79], v[170:173], v[222:225], v[76:79]
	v_mfma_f32_16x16x32_bf16 v[72:75], v[178:181], v[222:225], v[72:75]
	v_mfma_f32_16x16x32_bf16 v[124:127], v[174:177], v[202:205], v[124:127]
	v_mfma_f32_16x16x32_bf16 v[120:123], v[194:197], v[202:205], v[120:123]
	v_mfma_f32_16x16x32_bf16 v[108:111], v[174:177], v[210:213], v[108:111]
	v_mfma_f32_16x16x32_bf16 v[104:107], v[194:197], v[210:213], v[104:107]
	v_mfma_f32_16x16x32_bf16 v[92:95], v[174:177], v[218:221], v[92:95]
	v_mfma_f32_16x16x32_bf16 v[88:91], v[194:197], v[218:221], v[88:91]
	v_mfma_f32_16x16x32_bf16 v[76:79], v[174:177], v[226:229], v[76:79]
	v_mfma_f32_16x16x32_bf16 v[72:75], v[194:197], v[226:229], v[72:75]
	s_setprio 0
	s_barrier
	s_add_i32 s0, s61, s19
	s_mov_b32 m0, s0
	ds_read_b128 v[198:201], v193 offset:16384
	ds_read_b128 v[202:205], v193 offset:17408
	ds_read_b128 v[206:209], v193 offset:18432
	ds_read_b128 v[210:213], v193 offset:19456
	ds_read_b128 v[214:217], v193 offset:20480
	ds_read_b128 v[218:221], v193 offset:21504
	ds_read_b128 v[222:225], v193 offset:22528
	ds_read_b128 v[226:229], v193 offset:23552
	global_load_lds_dwordx4 v142, s[50:51]
	s_add_i32 m0, s0, 0x2000
	s_add_u32 s72, s50, 0x100000
	s_addc_u32 s73, s51, 0
	s_add_i32 s0, s62, s19
	global_load_lds_dwordx4 v146, s[50:51]
	s_mov_b32 m0, s0
	s_nop 0
	global_load_lds_dwordx4 v142, s[72:73]
	s_add_i32 m0, s0, 0x2000
	s_nop 0
	global_load_lds_dwordx4 v146, s[72:73]
	s_mov_b32 m0, s31
	s_nop 0
	global_load_lds_dwordx4 v140, s[52:53]
	s_mov_b32 m0, s35
	s_nop 0
	global_load_lds_dwordx4 v144, s[52:53]
	s_waitcnt vmcnt(8)
	s_waitcnt lgkmcnt(0)
	s_setprio 1
	s_barrier
	v_mfma_f32_16x16x32_bf16 v[68:71], v[136:139], v[198:201], v[68:71]
	v_mfma_f32_16x16x32_bf16 v[64:67], v[162:165], v[198:201], v[64:67]
	v_mfma_f32_16x16x32_bf16 v[52:55], v[136:139], v[206:209], v[52:55]
	v_mfma_f32_16x16x32_bf16 v[48:51], v[162:165], v[206:209], v[48:51]
	v_mfma_f32_16x16x32_bf16 v[36:39], v[136:139], v[214:217], v[36:39]
	v_mfma_f32_16x16x32_bf16 v[32:35], v[162:165], v[214:217], v[32:35]
	v_mfma_f32_16x16x32_bf16 v[20:23], v[136:139], v[222:225], v[20:23]
	v_mfma_f32_16x16x32_bf16 v[16:19], v[162:165], v[222:225], v[16:19]
	v_mfma_f32_16x16x32_bf16 v[68:71], v[158:161], v[202:205], v[68:71]
	v_mfma_f32_16x16x32_bf16 v[64:67], v[166:169], v[202:205], v[64:67]
	v_mfma_f32_16x16x32_bf16 v[52:55], v[158:161], v[210:213], v[52:55]
	v_mfma_f32_16x16x32_bf16 v[48:51], v[166:169], v[210:213], v[48:51]
	v_mfma_f32_16x16x32_bf16 v[36:39], v[158:161], v[218:221], v[36:39]
	v_mfma_f32_16x16x32_bf16 v[32:35], v[166:169], v[218:221], v[32:35]
	v_mfma_f32_16x16x32_bf16 v[20:23], v[158:161], v[226:229], v[20:23]
	v_mfma_f32_16x16x32_bf16 v[16:19], v[166:169], v[226:229], v[16:19]
	s_setprio 0
	s_setprio 1
	v_mfma_f32_16x16x32_bf16 v[60:63], v[170:173], v[198:201], v[60:63]
	v_mfma_f32_16x16x32_bf16 v[56:59], v[178:181], v[198:201], v[56:59]
	v_mfma_f32_16x16x32_bf16 v[44:47], v[170:173], v[206:209], v[44:47]
	v_mfma_f32_16x16x32_bf16 v[40:43], v[178:181], v[206:209], v[40:43]
	v_mfma_f32_16x16x32_bf16 v[28:31], v[170:173], v[214:217], v[28:31]
	v_mfma_f32_16x16x32_bf16 v[24:27], v[178:181], v[214:217], v[24:27]
	v_mfma_f32_16x16x32_bf16 v[12:15], v[170:173], v[222:225], v[12:15]
	v_mfma_f32_16x16x32_bf16 v[6:9], v[178:181], v[222:225], v[8:11]
	v_mfma_f32_16x16x32_bf16 v[60:63], v[174:177], v[202:205], v[60:63]
	v_mfma_f32_16x16x32_bf16 v[56:59], v[194:197], v[202:205], v[56:59]
	v_mfma_f32_16x16x32_bf16 v[44:47], v[174:177], v[210:213], v[44:47]
	v_mfma_f32_16x16x32_bf16 v[40:43], v[194:197], v[210:213], v[40:43]
	v_mfma_f32_16x16x32_bf16 v[28:31], v[174:177], v[218:221], v[28:31]
	v_mfma_f32_16x16x32_bf16 v[24:27], v[194:197], v[218:221], v[24:27]
	v_mfma_f32_16x16x32_bf16 v[12:15], v[174:177], v[226:229], v[12:15]
	v_mfma_f32_16x16x32_bf16 v[6:9], v[194:197], v[226:229], v[6:9]
	s_setprio 0
	s_barrier
	s_add_i32 s0, 0, 0x18000
	v_add_u32_e32 v5, s0, v1
	s_add_i32 s71, 0, 0x1c000
	ds_read_b128 v[136:139], v5
	ds_read_b128 v[158:161], v5 offset:1024
	ds_read_b128 v[162:165], v5 offset:2048
	ds_read_b128 v[166:169], v5 offset:3072
	v_add_u32_e32 v5, s71, v1
	ds_read_b128 v[170:173], v5
	ds_read_b128 v[174:177], v5 offset:1024
	ds_read_b128 v[178:181], v5 offset:2048
	ds_read_b128 v[194:197], v5 offset:3072
	s_add_u32 s98, s52, 0x100000
	s_addc_u32 s99, s53, 0
	s_mov_b32 m0, s45
	ds_read_b128 v[198:201], v193 offset:32768
	ds_read_b128 v[202:205], v193 offset:33792
	ds_read_b128 v[206:209], v193 offset:34816
	ds_read_b128 v[210:213], v193 offset:35840
	ds_read_b128 v[214:217], v193 offset:36864
	ds_read_b128 v[218:221], v193 offset:37888
	ds_read_b128 v[222:225], v193 offset:38912
	ds_read_b128 v[226:229], v193 offset:39936
	global_load_lds_dwordx4 v140, s[98:99]
	s_mov_b32 m0, s46
	s_nop 0
	global_load_lds_dwordx4 v144, s[98:99]
	s_waitcnt vmcnt(8)
	s_waitcnt lgkmcnt(0)
	s_setprio 1
	s_barrier
	v_mfma_f32_16x16x32_bf16 v[132:135], v[136:139], v[198:201], v[132:135]
	v_mfma_f32_16x16x32_bf16 v[128:131], v[162:165], v[198:201], v[128:131]
	v_mfma_f32_16x16x32_bf16 v[116:119], v[136:139], v[206:209], v[116:119]
	v_mfma_f32_16x16x32_bf16 v[112:115], v[162:165], v[206:209], v[112:115]
	v_mfma_f32_16x16x32_bf16 v[100:103], v[136:139], v[214:217], v[100:103]
	v_mfma_f32_16x16x32_bf16 v[96:99], v[162:165], v[214:217], v[96:99]
	v_mfma_f32_16x16x32_bf16 v[84:87], v[136:139], v[222:225], v[84:87]
	v_mfma_f32_16x16x32_bf16 v[80:83], v[162:165], v[222:225], v[80:83]
	v_mfma_f32_16x16x32_bf16 v[132:135], v[158:161], v[202:205], v[132:135]
	v_mfma_f32_16x16x32_bf16 v[128:131], v[166:169], v[202:205], v[128:131]
	v_mfma_f32_16x16x32_bf16 v[116:119], v[158:161], v[210:213], v[116:119]
	v_mfma_f32_16x16x32_bf16 v[112:115], v[166:169], v[210:213], v[112:115]
	v_mfma_f32_16x16x32_bf16 v[100:103], v[158:161], v[218:221], v[100:103]
	v_mfma_f32_16x16x32_bf16 v[96:99], v[166:169], v[218:221], v[96:99]
	v_mfma_f32_16x16x32_bf16 v[84:87], v[158:161], v[226:229], v[84:87]
	v_mfma_f32_16x16x32_bf16 v[80:83], v[166:169], v[226:229], v[80:83]
	s_setprio 0
	s_setprio 1
	v_mfma_f32_16x16x32_bf16 v[124:127], v[170:173], v[198:201], v[124:127]
	v_mfma_f32_16x16x32_bf16 v[120:123], v[178:181], v[198:201], v[120:123]
	v_mfma_f32_16x16x32_bf16 v[108:111], v[170:173], v[206:209], v[108:111]
	v_mfma_f32_16x16x32_bf16 v[104:107], v[178:181], v[206:209], v[104:107]
	v_mfma_f32_16x16x32_bf16 v[92:95], v[170:173], v[214:217], v[92:95]
	v_mfma_f32_16x16x32_bf16 v[88:91], v[178:181], v[214:217], v[88:91]
	v_mfma_f32_16x16x32_bf16 v[76:79], v[170:173], v[222:225], v[76:79]
	v_mfma_f32_16x16x32_bf16 v[72:75], v[178:181], v[222:225], v[72:75]
	v_mfma_f32_16x16x32_bf16 v[124:127], v[174:177], v[202:205], v[124:127]
	v_mfma_f32_16x16x32_bf16 v[120:123], v[194:197], v[202:205], v[120:123]
	v_mfma_f32_16x16x32_bf16 v[108:111], v[174:177], v[210:213], v[108:111]
	v_mfma_f32_16x16x32_bf16 v[104:107], v[194:197], v[210:213], v[104:107]
	v_mfma_f32_16x16x32_bf16 v[92:95], v[174:177], v[218:221], v[92:95]
	v_mfma_f32_16x16x32_bf16 v[88:91], v[194:197], v[218:221], v[88:91]
	v_mfma_f32_16x16x32_bf16 v[76:79], v[174:177], v[226:229], v[76:79]
	v_mfma_f32_16x16x32_bf16 v[72:75], v[194:197], v[226:229], v[72:75]
	s_setprio 0
	s_barrier
	s_add_i32 s0, s0, s19
	s_add_i32 m0, s0, 0xffffff80
	ds_read_b128 v[198:201], v193 offset:49152
	ds_read_b128 v[202:205], v193 offset:50176
	ds_read_b128 v[206:209], v193 offset:51200
	ds_read_b128 v[210:213], v193 offset:52224
	ds_read_b128 v[214:217], v193 offset:53248
	ds_read_b128 v[218:221], v193 offset:54272
	ds_read_b128 v[222:225], v193 offset:55296
	ds_read_b128 v[226:229], v193 offset:56320
	global_load_lds_dwordx4 v142, s[50:51] offset:128
	s_add_i32 m0, s0, 0x1f80
	s_add_i32 s0, s71, s19
	global_load_lds_dwordx4 v146, s[50:51] offset:128
	s_add_u32 s50, s50, 0x100080
	s_addc_u32 s51, s51, 0
	s_mov_b32 m0, s0
	s_nop 0
	global_load_lds_dwordx4 v142, s[50:51]
	s_add_i32 m0, s0, 0x2000
	s_nop 0
	global_load_lds_dwordx4 v146, s[50:51]
	s_add_i32 m0, s56, 0xffffff80
	s_nop 0
	global_load_lds_dwordx4 v140, s[52:53] offset:128
	s_add_i32 m0, s57, 0xffffff80
	s_nop 0
	global_load_lds_dwordx4 v144, s[52:53] offset:128
	s_waitcnt vmcnt(8)
	s_waitcnt lgkmcnt(0)
	s_setprio 1
	s_barrier
	v_mfma_f32_16x16x32_bf16 v[68:71], v[136:139], v[198:201], v[68:71]
	v_mfma_f32_16x16x32_bf16 v[64:67], v[162:165], v[198:201], v[64:67]
	s_add_i32 s70, s70, 2
	v_mfma_f32_16x16x32_bf16 v[52:55], v[136:139], v[206:209], v[52:55]
	s_add_u32 s42, s42, 0x100
	v_mfma_f32_16x16x32_bf16 v[48:51], v[162:165], v[206:209], v[48:51]
	s_addc_u32 s43, s43, 0
	v_mfma_f32_16x16x32_bf16 v[36:39], v[136:139], v[214:217], v[36:39]
	s_add_u32 s67, s67, 0x100
	v_mfma_f32_16x16x32_bf16 v[32:35], v[162:165], v[214:217], v[32:35]
	s_addc_u32 s68, s68, 0
	v_mfma_f32_16x16x32_bf16 v[20:23], v[136:139], v[222:225], v[20:23]
	s_add_u32 s0, s42, 0xfff00080
	v_mfma_f32_16x16x32_bf16 v[16:19], v[162:165], v[222:225], v[16:19]
	s_addc_u32 s50, s43, -1
	v_mfma_f32_16x16x32_bf16 v[68:71], v[158:161], v[202:205], v[68:71]
	s_cmp_eq_u32 s70, 60
	v_mfma_f32_16x16x32_bf16 v[64:67], v[166:169], v[202:205], v[64:67]
	s_cselect_b32 s53, s23, s50
	v_mfma_f32_16x16x32_bf16 v[52:55], v[158:161], v[210:213], v[52:55]
	s_cselect_b32 s52, s41, s0
	v_mfma_f32_16x16x32_bf16 v[48:51], v[166:169], v[210:213], v[48:51]
	s_cselect_b32 s51, s21, s68
	v_mfma_f32_16x16x32_bf16 v[36:39], v[158:161], v[218:221], v[36:39]
	s_cselect_b32 s50, s66, s67
	v_mfma_f32_16x16x32_bf16 v[32:35], v[166:169], v[218:221], v[32:35]
	s_add_i32 m0, s31, 0xc000
	v_mfma_f32_16x16x32_bf16 v[20:23], v[158:161], v[226:229], v[20:23]
	s_cmp_gt_u32 s70, 61
	v_mfma_f32_16x16x32_bf16 v[16:19], v[166:169], v[226:229], v[16:19]
	s_setprio 0
	s_setprio 1
	v_mfma_f32_16x16x32_bf16 v[60:63], v[170:173], v[198:201], v[60:63]
	v_mfma_f32_16x16x32_bf16 v[56:59], v[178:181], v[198:201], v[56:59]
	v_mfma_f32_16x16x32_bf16 v[44:47], v[170:173], v[206:209], v[44:47]
	v_mfma_f32_16x16x32_bf16 v[40:43], v[178:181], v[206:209], v[40:43]
	v_mfma_f32_16x16x32_bf16 v[28:31], v[170:173], v[214:217], v[28:31]
	v_mfma_f32_16x16x32_bf16 v[24:27], v[178:181], v[214:217], v[24:27]
	v_mfma_f32_16x16x32_bf16 v[10:13], v[170:173], v[222:225], v[12:15]
	v_mfma_f32_16x16x32_bf16 v[6:9], v[178:181], v[222:225], v[6:9]
	v_mfma_f32_16x16x32_bf16 v[60:63], v[174:177], v[202:205], v[60:63]
	v_mfma_f32_16x16x32_bf16 v[56:59], v[194:197], v[202:205], v[56:59]
	v_mfma_f32_16x16x32_bf16 v[44:47], v[174:177], v[210:213], v[44:47]
	v_mfma_f32_16x16x32_bf16 v[40:43], v[194:197], v[210:213], v[40:43]
	v_mfma_f32_16x16x32_bf16 v[28:31], v[174:177], v[218:221], v[28:31]
	v_mfma_f32_16x16x32_bf16 v[24:27], v[194:197], v[218:221], v[24:27]
	v_mfma_f32_16x16x32_bf16 v[12:15], v[174:177], v[226:229], v[10:13]
	v_mfma_f32_16x16x32_bf16 v[8:11], v[194:197], v[226:229], v[6:9]
	s_setprio 0
	s_barrier
	s_cbranch_scc0 .LBB0_170
	s_and_b64 vcc, exec, s[16:17]
	s_cbranch_vccz .LBB0_173
	s_barrier

.LBB0_341:
	s_add_u32 s26, s26, 0x2b0080
	s_addc_u32 s27, s27, 0
	s_add_u32 s60, s28, 0x100
	v_mov_b32_e32 v4, 0
	s_addc_u32 s61, s29, 0
	s_mov_b32 s62, -2
	s_waitcnt lgkmcnt(0)
	v_mov_b32_e32 v5, 0
	v_mov_b64_e32 v[6:7], 0
	v_mov_b64_e32 v[8:9], 0
	v_mov_b64_e32 v[10:11], 0
	v_mov_b64_e32 v[20:21], 0
	v_mov_b64_e32 v[22:23], 0
	v_mov_b64_e32 v[24:25], 0
	v_mov_b64_e32 v[26:27], 0
	v_mov_b64_e32 v[36:37], 0
	v_mov_b64_e32 v[38:39], 0
	v_mov_b64_e32 v[40:41], 0
	v_mov_b64_e32 v[42:43], 0
	v_mov_b64_e32 v[52:53], 0
	v_mov_b64_e32 v[54:55], 0
	v_mov_b64_e32 v[56:57], 0
	v_mov_b64_e32 v[58:59], 0
	v_mov_b64_e32 v[12:13], 0
	v_mov_b64_e32 v[14:15], 0
	v_mov_b64_e32 v[16:17], 0
	v_mov_b64_e32 v[18:19], 0
	v_mov_b64_e32 v[28:29], 0
	v_mov_b64_e32 v[30:31], 0
	v_mov_b64_e32 v[32:33], 0
	v_mov_b64_e32 v[34:35], 0
	v_mov_b64_e32 v[44:45], 0
	v_mov_b64_e32 v[46:47], 0
	v_mov_b64_e32 v[48:49], 0
	v_mov_b64_e32 v[50:51], 0
	v_mov_b64_e32 v[60:61], 0
	v_mov_b64_e32 v[62:63], 0
	v_mov_b64_e32 v[64:65], 0
	v_mov_b64_e32 v[66:67], 0
	v_mov_b64_e32 v[68:69], 0
	v_mov_b64_e32 v[70:71], 0
	v_mov_b64_e32 v[72:73], 0
	v_mov_b64_e32 v[74:75], 0
	v_mov_b64_e32 v[84:85], 0
	v_mov_b64_e32 v[86:87], 0
	v_mov_b64_e32 v[88:89], 0
	v_mov_b64_e32 v[90:91], 0
	v_mov_b64_e32 v[100:101], 0
	v_mov_b64_e32 v[102:103], 0
	v_mov_b64_e32 v[104:105], 0
	v_mov_b64_e32 v[106:107], 0
	v_mov_b64_e32 v[116:117], 0
	v_mov_b64_e32 v[118:119], 0
	v_mov_b64_e32 v[120:121], 0
	v_mov_b64_e32 v[122:123], 0
	v_mov_b64_e32 v[76:77], 0
	v_mov_b64_e32 v[78:79], 0
	v_mov_b64_e32 v[80:81], 0
	v_mov_b64_e32 v[82:83], 0
	v_mov_b64_e32 v[92:93], 0
	v_mov_b64_e32 v[94:95], 0
	v_mov_b64_e32 v[96:97], 0
	v_mov_b64_e32 v[98:99], 0
	v_mov_b64_e32 v[108:109], 0
	v_mov_b64_e32 v[110:111], 0
	v_mov_b64_e32 v[112:113], 0
	v_mov_b64_e32 v[114:115], 0
	v_mov_b64_e32 v[124:125], 0
	v_mov_b64_e32 v[126:127], 0
	v_mov_b64_e32 v[128:129], 0
	v_mov_b64_e32 v[130:131], 0
	s_add_u32 s0, s26, 0xffd50080
	s_addc_u32 s28, s27, -1
	s_cmpk_eq_i32 s62, 0xa8
	s_cselect_b32 s31, s7, s28
	s_cselect_b32 s30, s6, s0
	s_cselect_b32 s29, s25, s61
	s_cselect_b32 s28, s24, s60
	s_add_i32 m0, s43, 0xc000
.LBB0_342:
	ds_read_b128 v[132:135], v209
	ds_read_b128 v[136:139], v209 offset:1024
	ds_read_b128 v[140:143], v209 offset:2048
	ds_read_b128 v[144:147], v209 offset:3072
	ds_read_b128 v[148:151], v210
	ds_read_b128 v[152:155], v210 offset:1024
	ds_read_b128 v[156:159], v210 offset:2048
	ds_read_b128 v[160:163], v210 offset:3072
	ds_read_b128 v[164:167], v211
	ds_read_b128 v[168:171], v211 offset:1024
	ds_read_b128 v[172:175], v211 offset:2048
	ds_read_b128 v[176:179], v211 offset:3072
	ds_read_b128 v[196:199], v211 offset:4096
	ds_read_b128 v[200:203], v211 offset:5120
	ds_read_b128 v[204:207], v211 offset:6144
	ds_read_b128 v[214:217], v211 offset:7168
	global_load_lds_dwordx4 v188, s[26:27]
	s_add_i32 m0, s43, 0xe000
	s_nop 0
	global_load_lds_dwordx4 v190, s[26:27]
	s_waitcnt vmcnt(8)
	s_waitcnt lgkmcnt(0)
	s_setprio 1
	s_barrier
	v_mfma_f32_16x16x32_bf16 v[128:131], v[132:135], v[164:167], v[128:131]
	v_mfma_f32_16x16x32_bf16 v[124:127], v[140:143], v[164:167], v[124:127]
	v_mfma_f32_16x16x32_bf16 v[112:115], v[132:135], v[172:175], v[112:115]
	v_mfma_f32_16x16x32_bf16 v[108:111], v[140:143], v[172:175], v[108:111]
	v_mfma_f32_16x16x32_bf16 v[96:99], v[132:135], v[196:199], v[96:99]
	v_mfma_f32_16x16x32_bf16 v[92:95], v[140:143], v[196:199], v[92:95]
	v_mfma_f32_16x16x32_bf16 v[80:83], v[132:135], v[204:207], v[80:83]
	v_mfma_f32_16x16x32_bf16 v[76:79], v[140:143], v[204:207], v[76:79]
	v_mfma_f32_16x16x32_bf16 v[128:131], v[136:139], v[168:171], v[128:131]
	v_mfma_f32_16x16x32_bf16 v[124:127], v[144:147], v[168:171], v[124:127]
	v_mfma_f32_16x16x32_bf16 v[112:115], v[136:139], v[176:179], v[112:115]
	v_mfma_f32_16x16x32_bf16 v[108:111], v[144:147], v[176:179], v[108:111]
	v_mfma_f32_16x16x32_bf16 v[96:99], v[136:139], v[200:203], v[96:99]
	v_mfma_f32_16x16x32_bf16 v[92:95], v[144:147], v[200:203], v[92:95]
	v_mfma_f32_16x16x32_bf16 v[80:83], v[136:139], v[214:217], v[80:83]
	v_mfma_f32_16x16x32_bf16 v[76:79], v[144:147], v[214:217], v[76:79]
	s_setprio 0
	s_setprio 1
	v_mfma_f32_16x16x32_bf16 v[120:123], v[148:151], v[164:167], v[120:123]
	v_mfma_f32_16x16x32_bf16 v[116:119], v[156:159], v[164:167], v[116:119]
	v_mfma_f32_16x16x32_bf16 v[104:107], v[148:151], v[172:175], v[104:107]
	v_mfma_f32_16x16x32_bf16 v[100:103], v[156:159], v[172:175], v[100:103]
	v_mfma_f32_16x16x32_bf16 v[88:91], v[148:151], v[196:199], v[88:91]
	v_mfma_f32_16x16x32_bf16 v[84:87], v[156:159], v[196:199], v[84:87]
	v_mfma_f32_16x16x32_bf16 v[72:75], v[148:151], v[204:207], v[72:75]
	v_mfma_f32_16x16x32_bf16 v[68:71], v[156:159], v[204:207], v[68:71]
	v_mfma_f32_16x16x32_bf16 v[120:123], v[152:155], v[168:171], v[120:123]
	v_mfma_f32_16x16x32_bf16 v[116:119], v[160:163], v[168:171], v[116:119]
	v_mfma_f32_16x16x32_bf16 v[104:107], v[152:155], v[176:179], v[104:107]
	v_mfma_f32_16x16x32_bf16 v[100:103], v[160:163], v[176:179], v[100:103]
	v_mfma_f32_16x16x32_bf16 v[88:91], v[152:155], v[200:203], v[88:91]
	v_mfma_f32_16x16x32_bf16 v[84:87], v[160:163], v[200:203], v[84:87]
	v_mfma_f32_16x16x32_bf16 v[72:75], v[152:155], v[214:217], v[72:75]
	v_mfma_f32_16x16x32_bf16 v[68:71], v[160:163], v[214:217], v[68:71]
	s_setprio 0
	s_barrier
	s_add_i32 s0, s53, s42
	s_mov_b32 m0, s0
	ds_read_b128 v[164:167], v211 offset:16384
	ds_read_b128 v[168:171], v211 offset:17408
	ds_read_b128 v[172:175], v211 offset:18432
	ds_read_b128 v[176:179], v211 offset:19456
	ds_read_b128 v[196:199], v211 offset:20480
	ds_read_b128 v[200:203], v211 offset:21504
	ds_read_b128 v[204:207], v211 offset:22528
	ds_read_b128 v[214:217], v211 offset:23552
	global_load_lds_dwordx4 v182, s[28:29]
	s_add_i32 m0, s0, 0x2000
	s_add_u32 s64, s28, 0x2b0000
	s_addc_u32 s65, s29, 0
	s_add_i32 s0, s54, s42
	global_load_lds_dwordx4 v186, s[28:29]
	s_mov_b32 m0, s0
	s_nop 0
	global_load_lds_dwordx4 v182, s[64:65]
	s_add_i32 m0, s0, 0x2000
	s_nop 0
	global_load_lds_dwordx4 v186, s[64:65]
	s_mov_b32 m0, s43
	s_nop 0
	global_load_lds_dwordx4 v180, s[30:31]
	s_mov_b32 m0, s45
	s_nop 0
	global_load_lds_dwordx4 v184, s[30:31]
	s_waitcnt vmcnt(8)
	s_waitcnt lgkmcnt(0)
	s_setprio 1
	s_barrier
	v_mfma_f32_16x16x32_bf16 v[64:67], v[132:135], v[164:167], v[64:67]
	v_mfma_f32_16x16x32_bf16 v[60:63], v[140:143], v[164:167], v[60:63]
	v_mfma_f32_16x16x32_bf16 v[48:51], v[132:135], v[172:175], v[48:51]
	v_mfma_f32_16x16x32_bf16 v[44:47], v[140:143], v[172:175], v[44:47]
	v_mfma_f32_16x16x32_bf16 v[32:35], v[132:135], v[196:199], v[32:35]
	v_mfma_f32_16x16x32_bf16 v[28:31], v[140:143], v[196:199], v[28:31]
	v_mfma_f32_16x16x32_bf16 v[16:19], v[132:135], v[204:207], v[16:19]
	v_mfma_f32_16x16x32_bf16 v[12:15], v[140:143], v[204:207], v[12:15]
	v_mfma_f32_16x16x32_bf16 v[64:67], v[136:139], v[168:171], v[64:67]
	v_mfma_f32_16x16x32_bf16 v[60:63], v[144:147], v[168:171], v[60:63]
	v_mfma_f32_16x16x32_bf16 v[48:51], v[136:139], v[176:179], v[48:51]
	v_mfma_f32_16x16x32_bf16 v[44:47], v[144:147], v[176:179], v[44:47]
	v_mfma_f32_16x16x32_bf16 v[32:35], v[136:139], v[200:203], v[32:35]
	v_mfma_f32_16x16x32_bf16 v[28:31], v[144:147], v[200:203], v[28:31]
	v_mfma_f32_16x16x32_bf16 v[16:19], v[136:139], v[214:217], v[16:19]
	v_mfma_f32_16x16x32_bf16 v[12:15], v[144:147], v[214:217], v[12:15]
	s_setprio 0
	s_setprio 1
	v_mfma_f32_16x16x32_bf16 v[56:59], v[148:151], v[164:167], v[56:59]
	v_mfma_f32_16x16x32_bf16 v[52:55], v[156:159], v[164:167], v[52:55]
	v_mfma_f32_16x16x32_bf16 v[40:43], v[148:151], v[172:175], v[40:43]
	v_mfma_f32_16x16x32_bf16 v[36:39], v[156:159], v[172:175], v[36:39]
	v_mfma_f32_16x16x32_bf16 v[24:27], v[148:151], v[196:199], v[24:27]
	v_mfma_f32_16x16x32_bf16 v[20:23], v[156:159], v[196:199], v[20:23]
	v_mfma_f32_16x16x32_bf16 v[8:11], v[148:151], v[204:207], v[8:11]
	v_mfma_f32_16x16x32_bf16 v[4:7], v[156:159], v[204:207], v[4:7]
	v_mfma_f32_16x16x32_bf16 v[56:59], v[152:155], v[168:171], v[56:59]
	v_mfma_f32_16x16x32_bf16 v[52:55], v[160:163], v[168:171], v[52:55]
	v_mfma_f32_16x16x32_bf16 v[40:43], v[152:155], v[176:179], v[40:43]
	v_mfma_f32_16x16x32_bf16 v[36:39], v[160:163], v[176:179], v[36:39]
	v_mfma_f32_16x16x32_bf16 v[24:27], v[152:155], v[200:203], v[24:27]
	v_mfma_f32_16x16x32_bf16 v[20:23], v[160:163], v[200:203], v[20:23]
	v_mfma_f32_16x16x32_bf16 v[8:11], v[152:155], v[214:217], v[8:11]
	v_mfma_f32_16x16x32_bf16 v[4:7], v[160:163], v[214:217], v[4:7]
	s_setprio 0
	s_barrier
	s_add_i32 s0, 0, 0x18000
	s_add_i32 s63, 0, 0x1c000
	v_add_u32_e32 v144, s0, v3
	v_add_u32_e32 v160, s63, v3
	ds_read_b128 v[132:135], v144
	ds_read_b128 v[136:139], v144 offset:1024
	ds_read_b128 v[140:143], v144 offset:2048
	ds_read_b128 v[144:147], v144 offset:3072
	ds_read_b128 v[148:151], v160
	ds_read_b128 v[152:155], v160 offset:1024
	ds_read_b128 v[156:159], v160 offset:2048
	ds_read_b128 v[160:163], v160 offset:3072
	s_add_u32 s98, s30, 0x2b0000
	s_addc_u32 s99, s31, 0
	s_mov_b32 m0, s46
	ds_read_b128 v[164:167], v211 offset:32768
	ds_read_b128 v[168:171], v211 offset:33792
	ds_read_b128 v[172:175], v211 offset:34816
	ds_read_b128 v[176:179], v211 offset:35840
	ds_read_b128 v[196:199], v211 offset:36864
	ds_read_b128 v[200:203], v211 offset:37888
	ds_read_b128 v[204:207], v211 offset:38912
	ds_read_b128 v[214:217], v211 offset:39936
	global_load_lds_dwordx4 v180, s[98:99]
	s_mov_b32 m0, s47
	s_nop 0
	global_load_lds_dwordx4 v184, s[98:99]
	s_waitcnt vmcnt(8)
	s_waitcnt lgkmcnt(0)
	s_setprio 1
	s_barrier
	v_mfma_f32_16x16x32_bf16 v[128:131], v[132:135], v[164:167], v[128:131]
	v_mfma_f32_16x16x32_bf16 v[124:127], v[140:143], v[164:167], v[124:127]
	v_mfma_f32_16x16x32_bf16 v[112:115], v[132:135], v[172:175], v[112:115]
	v_mfma_f32_16x16x32_bf16 v[108:111], v[140:143], v[172:175], v[108:111]
	v_mfma_f32_16x16x32_bf16 v[96:99], v[132:135], v[196:199], v[96:99]
	v_mfma_f32_16x16x32_bf16 v[92:95], v[140:143], v[196:199], v[92:95]
	v_mfma_f32_16x16x32_bf16 v[80:83], v[132:135], v[204:207], v[80:83]
	v_mfma_f32_16x16x32_bf16 v[76:79], v[140:143], v[204:207], v[76:79]
	v_mfma_f32_16x16x32_bf16 v[128:131], v[136:139], v[168:171], v[128:131]
	v_mfma_f32_16x16x32_bf16 v[124:127], v[144:147], v[168:171], v[124:127]
	v_mfma_f32_16x16x32_bf16 v[112:115], v[136:139], v[176:179], v[112:115]
	v_mfma_f32_16x16x32_bf16 v[108:111], v[144:147], v[176:179], v[108:111]
	v_mfma_f32_16x16x32_bf16 v[96:99], v[136:139], v[200:203], v[96:99]
	v_mfma_f32_16x16x32_bf16 v[92:95], v[144:147], v[200:203], v[92:95]
	v_mfma_f32_16x16x32_bf16 v[80:83], v[136:139], v[214:217], v[80:83]
	v_mfma_f32_16x16x32_bf16 v[76:79], v[144:147], v[214:217], v[76:79]
	s_setprio 0
	s_setprio 1
	v_mfma_f32_16x16x32_bf16 v[120:123], v[148:151], v[164:167], v[120:123]
	v_mfma_f32_16x16x32_bf16 v[116:119], v[156:159], v[164:167], v[116:119]
	v_mfma_f32_16x16x32_bf16 v[104:107], v[148:151], v[172:175], v[104:107]
	v_mfma_f32_16x16x32_bf16 v[100:103], v[156:159], v[172:175], v[100:103]
	v_mfma_f32_16x16x32_bf16 v[88:91], v[148:151], v[196:199], v[88:91]
	v_mfma_f32_16x16x32_bf16 v[84:87], v[156:159], v[196:199], v[84:87]
	v_mfma_f32_16x16x32_bf16 v[72:75], v[148:151], v[204:207], v[72:75]
	v_mfma_f32_16x16x32_bf16 v[68:71], v[156:159], v[204:207], v[68:71]
	v_mfma_f32_16x16x32_bf16 v[120:123], v[152:155], v[168:171], v[120:123]
	v_mfma_f32_16x16x32_bf16 v[116:119], v[160:163], v[168:171], v[116:119]
	v_mfma_f32_16x16x32_bf16 v[104:107], v[152:155], v[176:179], v[104:107]
	v_mfma_f32_16x16x32_bf16 v[100:103], v[160:163], v[176:179], v[100:103]
	v_mfma_f32_16x16x32_bf16 v[88:91], v[152:155], v[200:203], v[88:91]
	v_mfma_f32_16x16x32_bf16 v[84:87], v[160:163], v[200:203], v[84:87]
	v_mfma_f32_16x16x32_bf16 v[72:75], v[152:155], v[214:217], v[72:75]
	v_mfma_f32_16x16x32_bf16 v[68:71], v[160:163], v[214:217], v[68:71]
	s_setprio 0
	s_barrier
	s_add_i32 s0, s0, s42
	s_add_i32 m0, s0, 0xffffff80
	ds_read_b128 v[164:167], v211 offset:49152
	ds_read_b128 v[168:171], v211 offset:50176
	ds_read_b128 v[172:175], v211 offset:51200
	ds_read_b128 v[176:179], v211 offset:52224
	ds_read_b128 v[196:199], v211 offset:53248
	ds_read_b128 v[200:203], v211 offset:54272
	ds_read_b128 v[204:207], v211 offset:55296
	ds_read_b128 v[214:217], v211 offset:56320
	global_load_lds_dwordx4 v182, s[28:29] offset:128
	s_add_i32 m0, s0, 0x1f80
	s_add_i32 s0, s63, s42
	global_load_lds_dwordx4 v186, s[28:29] offset:128
	s_add_u32 s28, s28, 0x2b0080
	s_addc_u32 s29, s29, 0
	s_mov_b32 m0, s0
	s_nop 0
	global_load_lds_dwordx4 v182, s[28:29]
	s_add_i32 m0, s0, 0x2000
	s_nop 0
	global_load_lds_dwordx4 v186, s[28:29]
	s_add_i32 m0, s51, 0xffffff80
	s_nop 0
	global_load_lds_dwordx4 v180, s[30:31] offset:128
	s_add_i32 m0, s52, 0xffffff80
	s_nop 0
	global_load_lds_dwordx4 v184, s[30:31] offset:128
	s_waitcnt vmcnt(8)
	s_waitcnt lgkmcnt(0)
	s_setprio 1
	s_barrier
	v_mfma_f32_16x16x32_bf16 v[64:67], v[132:135], v[164:167], v[64:67]
	v_mfma_f32_16x16x32_bf16 v[60:63], v[140:143], v[164:167], v[60:63]
	s_add_i32 s62, s62, 2
	v_mfma_f32_16x16x32_bf16 v[48:51], v[132:135], v[172:175], v[48:51]
	s_add_u32 s26, s26, 0x100
	v_mfma_f32_16x16x32_bf16 v[44:47], v[140:143], v[172:175], v[44:47]
	s_addc_u32 s27, s27, 0
	v_mfma_f32_16x16x32_bf16 v[32:35], v[132:135], v[196:199], v[32:35]
	s_add_u32 s60, s60, 0x100
	v_mfma_f32_16x16x32_bf16 v[28:31], v[140:143], v[196:199], v[28:31]
	s_addc_u32 s61, s61, 0
	v_mfma_f32_16x16x32_bf16 v[16:19], v[132:135], v[204:207], v[16:19]
	s_add_u32 s0, s26, 0xffd50080
	v_mfma_f32_16x16x32_bf16 v[12:15], v[140:143], v[204:207], v[12:15]
	s_addc_u32 s28, s27, -1
	v_mfma_f32_16x16x32_bf16 v[64:67], v[136:139], v[168:171], v[64:67]
	s_cmpk_eq_i32 s62, 0xa8
	v_mfma_f32_16x16x32_bf16 v[60:63], v[144:147], v[168:171], v[60:63]
	s_cselect_b32 s31, s7, s28
	v_mfma_f32_16x16x32_bf16 v[48:51], v[136:139], v[176:179], v[48:51]
	s_cselect_b32 s30, s6, s0
	v_mfma_f32_16x16x32_bf16 v[44:47], v[144:147], v[176:179], v[44:47]
	s_cselect_b32 s29, s25, s61
	v_mfma_f32_16x16x32_bf16 v[32:35], v[136:139], v[200:203], v[32:35]
	s_cselect_b32 s28, s24, s60
	v_mfma_f32_16x16x32_bf16 v[28:31], v[144:147], v[200:203], v[28:31]
	s_add_i32 m0, s43, 0xc000
	v_mfma_f32_16x16x32_bf16 v[16:19], v[136:139], v[214:217], v[16:19]
	s_cmpk_gt_u32 s62, 0xa9
	v_mfma_f32_16x16x32_bf16 v[12:15], v[144:147], v[214:217], v[12:15]
	s_setprio 0
	s_setprio 1
	v_mfma_f32_16x16x32_bf16 v[56:59], v[148:151], v[164:167], v[56:59]
	v_mfma_f32_16x16x32_bf16 v[52:55], v[156:159], v[164:167], v[52:55]
	v_mfma_f32_16x16x32_bf16 v[40:43], v[148:151], v[172:175], v[40:43]
	v_mfma_f32_16x16x32_bf16 v[36:39], v[156:159], v[172:175], v[36:39]
	v_mfma_f32_16x16x32_bf16 v[24:27], v[148:151], v[196:199], v[24:27]
	v_mfma_f32_16x16x32_bf16 v[20:23], v[156:159], v[196:199], v[20:23]
	v_mfma_f32_16x16x32_bf16 v[8:11], v[148:151], v[204:207], v[8:11]
	v_mfma_f32_16x16x32_bf16 v[4:7], v[156:159], v[204:207], v[4:7]
	v_mfma_f32_16x16x32_bf16 v[56:59], v[152:155], v[168:171], v[56:59]
	v_mfma_f32_16x16x32_bf16 v[52:55], v[160:163], v[168:171], v[52:55]
	v_mfma_f32_16x16x32_bf16 v[40:43], v[152:155], v[176:179], v[40:43]
	v_mfma_f32_16x16x32_bf16 v[36:39], v[160:163], v[176:179], v[36:39]
	v_mfma_f32_16x16x32_bf16 v[24:27], v[152:155], v[200:203], v[24:27]
	v_mfma_f32_16x16x32_bf16 v[20:23], v[160:163], v[200:203], v[20:23]
	v_mfma_f32_16x16x32_bf16 v[8:11], v[152:155], v[214:217], v[8:11]
	v_mfma_f32_16x16x32_bf16 v[4:7], v[160:163], v[214:217], v[4:7]
	s_setprio 0
	s_barrier
	s_cbranch_scc0 .LBB0_342
	s_and_b64 vcc, exec, s[22:23]
	s_cbranch_vccz .LBB0_345
	s_barrier

.LBB0_428:
	s_ashr_i32 s27, s26, 31
	s_lshl_b64 s[28:29], s[26:27], 21
	s_add_u32 s28, s35, s28
	s_addc_u32 s29, s45, s29
	s_and_b64 s[30:31], exec, s[6:7]
	s_cselect_b32 s27, s51, s29
	s_cselect_b32 s67, s50, s28
	s_ashr_i32 s25, s24, 31
	s_lshl_b64 s[30:31], s[24:25], 21
	s_add_u32 s30, s46, s30
	s_addc_u32 s31, s47, s31
	s_and_b64 s[54:55], exec, s[6:7]
	s_cselect_b32 s25, s53, s31
	s_cselect_b32 s68, s52, s30
	s_add_u32 s50, s50, 0x100080
	s_addc_u32 s51, s51, 0
	s_add_u32 s70, s52, 0x100
	v_mov_b32_e32 v4, 0
	s_addc_u32 s71, s53, 0
	s_mov_b32 s72, -2
	v_mov_b32_e32 v5, 0
	v_mov_b64_e32 v[6:7], 0
	v_mov_b64_e32 v[8:9], 0
	v_mov_b64_e32 v[10:11], 0
	v_mov_b64_e32 v[20:21], 0
	v_mov_b64_e32 v[22:23], 0
	v_mov_b64_e32 v[24:25], 0
	v_mov_b64_e32 v[26:27], 0
	v_mov_b64_e32 v[36:37], 0
	v_mov_b64_e32 v[38:39], 0
	v_mov_b64_e32 v[40:41], 0
	v_mov_b64_e32 v[42:43], 0
	v_mov_b64_e32 v[52:53], 0
	v_mov_b64_e32 v[54:55], 0
	v_mov_b64_e32 v[56:57], 0
	v_mov_b64_e32 v[58:59], 0
	v_mov_b64_e32 v[12:13], 0
	v_mov_b64_e32 v[14:15], 0
	v_mov_b64_e32 v[16:17], 0
	v_mov_b64_e32 v[18:19], 0
	v_mov_b64_e32 v[28:29], 0
	v_mov_b64_e32 v[30:31], 0
	v_mov_b64_e32 v[32:33], 0
	v_mov_b64_e32 v[34:35], 0
	v_mov_b64_e32 v[44:45], 0
	v_mov_b64_e32 v[46:47], 0
	v_mov_b64_e32 v[48:49], 0
	v_mov_b64_e32 v[50:51], 0
	v_mov_b64_e32 v[60:61], 0
	v_mov_b64_e32 v[62:63], 0
	v_mov_b64_e32 v[64:65], 0
	v_mov_b64_e32 v[66:67], 0
	v_mov_b64_e32 v[68:69], 0
	v_mov_b64_e32 v[70:71], 0
	v_mov_b64_e32 v[72:73], 0
	v_mov_b64_e32 v[74:75], 0
	v_mov_b64_e32 v[84:85], 0
	v_mov_b64_e32 v[86:87], 0
	v_mov_b64_e32 v[88:89], 0
	v_mov_b64_e32 v[90:91], 0
	v_mov_b64_e32 v[100:101], 0
	v_mov_b64_e32 v[102:103], 0
	v_mov_b64_e32 v[104:105], 0
	v_mov_b64_e32 v[106:107], 0
	v_mov_b64_e32 v[116:117], 0
	v_mov_b64_e32 v[118:119], 0
	v_mov_b64_e32 v[120:121], 0
	v_mov_b64_e32 v[122:123], 0
	v_mov_b64_e32 v[76:77], 0
	v_mov_b64_e32 v[78:79], 0
	v_mov_b64_e32 v[80:81], 0
	v_mov_b64_e32 v[82:83], 0
	v_mov_b64_e32 v[92:93], 0
	v_mov_b64_e32 v[94:95], 0
	v_mov_b64_e32 v[96:97], 0
	v_mov_b64_e32 v[98:99], 0
	v_mov_b64_e32 v[108:109], 0
	v_mov_b64_e32 v[110:111], 0
	v_mov_b64_e32 v[112:113], 0
	v_mov_b64_e32 v[114:115], 0
	v_mov_b64_e32 v[124:125], 0
	v_mov_b64_e32 v[126:127], 0
	v_mov_b64_e32 v[128:129], 0
	v_mov_b64_e32 v[130:131], 0
	s_add_u32 s0, s50, 0xfff00080
	s_addc_u32 s52, s51, -1
	s_cmp_eq_u32 s72, 60
	s_cselect_b32 s55, s27, s52
	s_cselect_b32 s54, s67, s0
	s_cselect_b32 s53, s25, s71
	s_cselect_b32 s52, s68, s70
	s_add_i32 m0, s43, 0xc000
.LBB0_429:
	ds_read_b128 v[150:153], v156
	ds_read_b128 v[162:165], v156 offset:1024
	ds_read_b128 v[166:169], v156 offset:2048
	ds_read_b128 v[170:173], v156 offset:3072
	ds_read_b128 v[174:177], v157
	ds_read_b128 v[178:181], v157 offset:1024
	ds_read_b128 v[182:185], v157 offset:2048
	ds_read_b128 v[186:189], v157 offset:3072
	ds_read_b128 v[190:193], v158
	ds_read_b128 v[194:197], v158 offset:1024
	ds_read_b128 v[198:201], v158 offset:2048
	ds_read_b128 v[202:205], v158 offset:3072
	ds_read_b128 v[206:209], v158 offset:4096
	ds_read_b128 v[210:213], v158 offset:5120
	ds_read_b128 v[214:217], v158 offset:6144
	ds_read_b128 v[218:221], v158 offset:7168
	global_load_lds_dwordx4 v142, s[50:51]
	s_add_i32 m0, s43, 0xe000
	s_nop 0
	global_load_lds_dwordx4 v144, s[50:51]
	s_waitcnt vmcnt(8)
	s_waitcnt lgkmcnt(0)
	s_setprio 1
	s_barrier
	v_mfma_f32_16x16x32_bf16 v[128:131], v[150:153], v[190:193], v[128:131]
	v_mfma_f32_16x16x32_bf16 v[124:127], v[166:169], v[190:193], v[124:127]
	v_mfma_f32_16x16x32_bf16 v[112:115], v[150:153], v[198:201], v[112:115]
	v_mfma_f32_16x16x32_bf16 v[108:111], v[166:169], v[198:201], v[108:111]
	v_mfma_f32_16x16x32_bf16 v[96:99], v[150:153], v[206:209], v[96:99]
	v_mfma_f32_16x16x32_bf16 v[92:95], v[166:169], v[206:209], v[92:95]
	v_mfma_f32_16x16x32_bf16 v[80:83], v[150:153], v[214:217], v[80:83]
	v_mfma_f32_16x16x32_bf16 v[76:79], v[166:169], v[214:217], v[76:79]
	v_mfma_f32_16x16x32_bf16 v[128:131], v[162:165], v[194:197], v[128:131]
	v_mfma_f32_16x16x32_bf16 v[124:127], v[170:173], v[194:197], v[124:127]
	v_mfma_f32_16x16x32_bf16 v[112:115], v[162:165], v[202:205], v[112:115]
	v_mfma_f32_16x16x32_bf16 v[108:111], v[170:173], v[202:205], v[108:111]
	v_mfma_f32_16x16x32_bf16 v[96:99], v[162:165], v[210:213], v[96:99]
	v_mfma_f32_16x16x32_bf16 v[92:95], v[170:173], v[210:213], v[92:95]
	v_mfma_f32_16x16x32_bf16 v[80:83], v[162:165], v[218:221], v[80:83]
	v_mfma_f32_16x16x32_bf16 v[76:79], v[170:173], v[218:221], v[76:79]
	s_setprio 0
	s_setprio 1
	v_mfma_f32_16x16x32_bf16 v[120:123], v[174:177], v[190:193], v[120:123]
	v_mfma_f32_16x16x32_bf16 v[116:119], v[182:185], v[190:193], v[116:119]
	v_mfma_f32_16x16x32_bf16 v[104:107], v[174:177], v[198:201], v[104:107]
	v_mfma_f32_16x16x32_bf16 v[100:103], v[182:185], v[198:201], v[100:103]
	v_mfma_f32_16x16x32_bf16 v[88:91], v[174:177], v[206:209], v[88:91]
	v_mfma_f32_16x16x32_bf16 v[84:87], v[182:185], v[206:209], v[84:87]
	v_mfma_f32_16x16x32_bf16 v[72:75], v[174:177], v[214:217], v[72:75]
	v_mfma_f32_16x16x32_bf16 v[68:71], v[182:185], v[214:217], v[68:71]
	v_mfma_f32_16x16x32_bf16 v[120:123], v[178:181], v[194:197], v[120:123]
	v_mfma_f32_16x16x32_bf16 v[116:119], v[186:189], v[194:197], v[116:119]
	v_mfma_f32_16x16x32_bf16 v[104:107], v[178:181], v[202:205], v[104:107]
	v_mfma_f32_16x16x32_bf16 v[100:103], v[186:189], v[202:205], v[100:103]
	v_mfma_f32_16x16x32_bf16 v[88:91], v[178:181], v[210:213], v[88:91]
	v_mfma_f32_16x16x32_bf16 v[84:87], v[186:189], v[210:213], v[84:87]
	v_mfma_f32_16x16x32_bf16 v[72:75], v[178:181], v[218:221], v[72:75]
	v_mfma_f32_16x16x32_bf16 v[68:71], v[186:189], v[218:221], v[68:71]
	s_setprio 0
	s_barrier
	s_add_i32 s0, s62, s41
	s_mov_b32 m0, s0
	ds_read_b128 v[190:193], v158 offset:16384
	ds_read_b128 v[194:197], v158 offset:17408
	ds_read_b128 v[198:201], v158 offset:18432
	ds_read_b128 v[202:205], v158 offset:19456
	ds_read_b128 v[206:209], v158 offset:20480
	ds_read_b128 v[210:213], v158 offset:21504
	ds_read_b128 v[214:217], v158 offset:22528
	ds_read_b128 v[218:221], v158 offset:23552
	global_load_lds_dwordx4 v136, s[52:53]
	s_add_i32 m0, s0, 0x2000
	s_add_u32 s74, s52, 0x100000
	s_addc_u32 s75, s53, 0
	s_add_i32 s0, s63, s41
	global_load_lds_dwordx4 v140, s[52:53]
	s_mov_b32 m0, s0
	s_nop 0
	global_load_lds_dwordx4 v136, s[74:75]
	s_add_i32 m0, s0, 0x2000
	s_nop 0
	global_load_lds_dwordx4 v140, s[74:75]
	s_mov_b32 m0, s43
	s_nop 0
	global_load_lds_dwordx4 v134, s[54:55]
	s_mov_b32 m0, s48
	s_nop 0
	global_load_lds_dwordx4 v138, s[54:55]
	s_waitcnt vmcnt(8)
	s_waitcnt lgkmcnt(0)
	s_setprio 1
	s_barrier
	v_mfma_f32_16x16x32_bf16 v[64:67], v[150:153], v[190:193], v[64:67]
	v_mfma_f32_16x16x32_bf16 v[60:63], v[166:169], v[190:193], v[60:63]
	v_mfma_f32_16x16x32_bf16 v[48:51], v[150:153], v[198:201], v[48:51]
	v_mfma_f32_16x16x32_bf16 v[44:47], v[166:169], v[198:201], v[44:47]
	v_mfma_f32_16x16x32_bf16 v[32:35], v[150:153], v[206:209], v[32:35]
	v_mfma_f32_16x16x32_bf16 v[28:31], v[166:169], v[206:209], v[28:31]
	v_mfma_f32_16x16x32_bf16 v[16:19], v[150:153], v[214:217], v[16:19]
	v_mfma_f32_16x16x32_bf16 v[12:15], v[166:169], v[214:217], v[12:15]
	v_mfma_f32_16x16x32_bf16 v[64:67], v[162:165], v[194:197], v[64:67]
	v_mfma_f32_16x16x32_bf16 v[60:63], v[170:173], v[194:197], v[60:63]
	v_mfma_f32_16x16x32_bf16 v[48:51], v[162:165], v[202:205], v[48:51]
	v_mfma_f32_16x16x32_bf16 v[44:47], v[170:173], v[202:205], v[44:47]
	v_mfma_f32_16x16x32_bf16 v[32:35], v[162:165], v[210:213], v[32:35]
	v_mfma_f32_16x16x32_bf16 v[28:31], v[170:173], v[210:213], v[28:31]
	v_mfma_f32_16x16x32_bf16 v[16:19], v[162:165], v[218:221], v[16:19]
	v_mfma_f32_16x16x32_bf16 v[12:15], v[170:173], v[218:221], v[12:15]
	s_setprio 0
	s_setprio 1
	v_mfma_f32_16x16x32_bf16 v[56:59], v[174:177], v[190:193], v[56:59]
	v_mfma_f32_16x16x32_bf16 v[52:55], v[182:185], v[190:193], v[52:55]
	v_mfma_f32_16x16x32_bf16 v[40:43], v[174:177], v[198:201], v[40:43]
	v_mfma_f32_16x16x32_bf16 v[36:39], v[182:185], v[198:201], v[36:39]
	v_mfma_f32_16x16x32_bf16 v[24:27], v[174:177], v[206:209], v[24:27]
	v_mfma_f32_16x16x32_bf16 v[20:23], v[182:185], v[206:209], v[20:23]
	v_mfma_f32_16x16x32_bf16 v[8:11], v[174:177], v[214:217], v[8:11]
	v_mfma_f32_16x16x32_bf16 v[4:7], v[182:185], v[214:217], v[4:7]
	v_mfma_f32_16x16x32_bf16 v[56:59], v[178:181], v[194:197], v[56:59]
	v_mfma_f32_16x16x32_bf16 v[52:55], v[186:189], v[194:197], v[52:55]
	v_mfma_f32_16x16x32_bf16 v[40:43], v[178:181], v[202:205], v[40:43]
	v_mfma_f32_16x16x32_bf16 v[36:39], v[186:189], v[202:205], v[36:39]
	v_mfma_f32_16x16x32_bf16 v[24:27], v[178:181], v[210:213], v[24:27]
	v_mfma_f32_16x16x32_bf16 v[20:23], v[186:189], v[210:213], v[20:23]
	v_mfma_f32_16x16x32_bf16 v[8:11], v[178:181], v[218:221], v[8:11]
	v_mfma_f32_16x16x32_bf16 v[4:7], v[186:189], v[218:221], v[4:7]
	s_setprio 0
	s_barrier
	s_add_i32 s0, 0, 0x18000
	v_add_u32_e32 v161, s0, v133
	s_add_i32 s73, 0, 0x1c000
	ds_read_b128 v[150:153], v161
	ds_read_b128 v[162:165], v161 offset:1024
	ds_read_b128 v[166:169], v161 offset:2048
	ds_read_b128 v[170:173], v161 offset:3072
	v_add_u32_e32 v161, s73, v133
	ds_read_b128 v[174:177], v161
	ds_read_b128 v[178:181], v161 offset:1024
	ds_read_b128 v[182:185], v161 offset:2048
	ds_read_b128 v[186:189], v161 offset:3072
	s_add_u32 s98, s54, 0x100000
	s_addc_u32 s99, s55, 0
	s_mov_b32 m0, s49
	ds_read_b128 v[190:193], v158 offset:32768
	ds_read_b128 v[194:197], v158 offset:33792
	ds_read_b128 v[198:201], v158 offset:34816
	ds_read_b128 v[202:205], v158 offset:35840
	ds_read_b128 v[206:209], v158 offset:36864
	ds_read_b128 v[210:213], v158 offset:37888
	ds_read_b128 v[214:217], v158 offset:38912
	ds_read_b128 v[218:221], v158 offset:39936
	global_load_lds_dwordx4 v134, s[98:99]
	s_mov_b32 m0, s56
	s_nop 0
	global_load_lds_dwordx4 v138, s[98:99]
	s_waitcnt vmcnt(8)
	s_waitcnt lgkmcnt(0)
	s_setprio 1
	s_barrier
	v_mfma_f32_16x16x32_bf16 v[128:131], v[150:153], v[190:193], v[128:131]
	v_mfma_f32_16x16x32_bf16 v[124:127], v[166:169], v[190:193], v[124:127]
	v_mfma_f32_16x16x32_bf16 v[112:115], v[150:153], v[198:201], v[112:115]
	v_mfma_f32_16x16x32_bf16 v[108:111], v[166:169], v[198:201], v[108:111]
	v_mfma_f32_16x16x32_bf16 v[96:99], v[150:153], v[206:209], v[96:99]
	v_mfma_f32_16x16x32_bf16 v[92:95], v[166:169], v[206:209], v[92:95]
	v_mfma_f32_16x16x32_bf16 v[80:83], v[150:153], v[214:217], v[80:83]
	v_mfma_f32_16x16x32_bf16 v[76:79], v[166:169], v[214:217], v[76:79]
	v_mfma_f32_16x16x32_bf16 v[128:131], v[162:165], v[194:197], v[128:131]
	v_mfma_f32_16x16x32_bf16 v[124:127], v[170:173], v[194:197], v[124:127]
	v_mfma_f32_16x16x32_bf16 v[112:115], v[162:165], v[202:205], v[112:115]
	v_mfma_f32_16x16x32_bf16 v[108:111], v[170:173], v[202:205], v[108:111]
	v_mfma_f32_16x16x32_bf16 v[96:99], v[162:165], v[210:213], v[96:99]
	v_mfma_f32_16x16x32_bf16 v[92:95], v[170:173], v[210:213], v[92:95]
	v_mfma_f32_16x16x32_bf16 v[80:83], v[162:165], v[218:221], v[80:83]
	v_mfma_f32_16x16x32_bf16 v[76:79], v[170:173], v[218:221], v[76:79]
	s_setprio 0
	s_setprio 1
	v_mfma_f32_16x16x32_bf16 v[120:123], v[174:177], v[190:193], v[120:123]
	v_mfma_f32_16x16x32_bf16 v[116:119], v[182:185], v[190:193], v[116:119]
	v_mfma_f32_16x16x32_bf16 v[104:107], v[174:177], v[198:201], v[104:107]
	v_mfma_f32_16x16x32_bf16 v[100:103], v[182:185], v[198:201], v[100:103]
	v_mfma_f32_16x16x32_bf16 v[88:91], v[174:177], v[206:209], v[88:91]
	v_mfma_f32_16x16x32_bf16 v[84:87], v[182:185], v[206:209], v[84:87]
	v_mfma_f32_16x16x32_bf16 v[72:75], v[174:177], v[214:217], v[72:75]
	v_mfma_f32_16x16x32_bf16 v[68:71], v[182:185], v[214:217], v[68:71]
	v_mfma_f32_16x16x32_bf16 v[120:123], v[178:181], v[194:197], v[120:123]
	v_mfma_f32_16x16x32_bf16 v[116:119], v[186:189], v[194:197], v[116:119]
	v_mfma_f32_16x16x32_bf16 v[104:107], v[178:181], v[202:205], v[104:107]
	v_mfma_f32_16x16x32_bf16 v[100:103], v[186:189], v[202:205], v[100:103]
	v_mfma_f32_16x16x32_bf16 v[88:91], v[178:181], v[210:213], v[88:91]
	v_mfma_f32_16x16x32_bf16 v[84:87], v[186:189], v[210:213], v[84:87]
	v_mfma_f32_16x16x32_bf16 v[72:75], v[178:181], v[218:221], v[72:75]
	v_mfma_f32_16x16x32_bf16 v[68:71], v[186:189], v[218:221], v[68:71]
	s_setprio 0
	s_barrier
	s_add_i32 s0, s0, s41
	s_add_i32 m0, s0, 0xffffff80
	ds_read_b128 v[190:193], v158 offset:49152
	ds_read_b128 v[194:197], v158 offset:50176
	ds_read_b128 v[198:201], v158 offset:51200
	ds_read_b128 v[202:205], v158 offset:52224
	ds_read_b128 v[206:209], v158 offset:53248
	ds_read_b128 v[210:213], v158 offset:54272
	ds_read_b128 v[214:217], v158 offset:55296
	ds_read_b128 v[218:221], v158 offset:56320
	global_load_lds_dwordx4 v136, s[52:53] offset:128
	s_add_i32 m0, s0, 0x1f80
	s_add_i32 s0, s73, s41
	global_load_lds_dwordx4 v140, s[52:53] offset:128
	s_add_u32 s52, s52, 0x100080
	s_addc_u32 s53, s53, 0
	s_mov_b32 m0, s0
	s_nop 0
	global_load_lds_dwordx4 v136, s[52:53]
	s_add_i32 m0, s0, 0x2000
	s_nop 0
	global_load_lds_dwordx4 v140, s[52:53]
	s_add_i32 m0, s59, 0xffffff80
	s_nop 0
	global_load_lds_dwordx4 v134, s[54:55] offset:128
	s_add_i32 m0, s60, 0xffffff80
	s_nop 0
	global_load_lds_dwordx4 v138, s[54:55] offset:128
	s_waitcnt vmcnt(8)
	s_waitcnt lgkmcnt(0)
	s_setprio 1
	s_barrier
	v_mfma_f32_16x16x32_bf16 v[64:67], v[150:153], v[190:193], v[64:67]
	v_mfma_f32_16x16x32_bf16 v[60:63], v[166:169], v[190:193], v[60:63]
	s_add_i32 s72, s72, 2
	v_mfma_f32_16x16x32_bf16 v[48:51], v[150:153], v[198:201], v[48:51]
	s_add_u32 s50, s50, 0x100
	v_mfma_f32_16x16x32_bf16 v[44:47], v[166:169], v[198:201], v[44:47]
	s_addc_u32 s51, s51, 0
	v_mfma_f32_16x16x32_bf16 v[32:35], v[150:153], v[206:209], v[32:35]
	s_add_u32 s70, s70, 0x100
	v_mfma_f32_16x16x32_bf16 v[28:31], v[166:169], v[206:209], v[28:31]
	s_addc_u32 s71, s71, 0
	v_mfma_f32_16x16x32_bf16 v[16:19], v[150:153], v[214:217], v[16:19]
	s_add_u32 s0, s50, 0xfff00080
	v_mfma_f32_16x16x32_bf16 v[12:15], v[166:169], v[214:217], v[12:15]
	s_addc_u32 s52, s51, -1
	v_mfma_f32_16x16x32_bf16 v[64:67], v[162:165], v[194:197], v[64:67]
	s_cmp_eq_u32 s72, 60
	v_mfma_f32_16x16x32_bf16 v[60:63], v[170:173], v[194:197], v[60:63]
	s_cselect_b32 s55, s27, s52
	v_mfma_f32_16x16x32_bf16 v[48:51], v[162:165], v[202:205], v[48:51]
	s_cselect_b32 s54, s67, s0
	v_mfma_f32_16x16x32_bf16 v[44:47], v[170:173], v[202:205], v[44:47]
	s_cselect_b32 s53, s25, s71
	v_mfma_f32_16x16x32_bf16 v[32:35], v[162:165], v[210:213], v[32:35]
	s_cselect_b32 s52, s68, s70
	v_mfma_f32_16x16x32_bf16 v[28:31], v[170:173], v[210:213], v[28:31]
	s_add_i32 m0, s43, 0xc000
	v_mfma_f32_16x16x32_bf16 v[16:19], v[162:165], v[218:221], v[16:19]
	s_cmp_gt_u32 s72, 61
	v_mfma_f32_16x16x32_bf16 v[12:15], v[170:173], v[218:221], v[12:15]
	s_setprio 0
	s_setprio 1
	v_mfma_f32_16x16x32_bf16 v[56:59], v[174:177], v[190:193], v[56:59]
	v_mfma_f32_16x16x32_bf16 v[52:55], v[182:185], v[190:193], v[52:55]
	v_mfma_f32_16x16x32_bf16 v[40:43], v[174:177], v[198:201], v[40:43]
	v_mfma_f32_16x16x32_bf16 v[36:39], v[182:185], v[198:201], v[36:39]
	v_mfma_f32_16x16x32_bf16 v[24:27], v[174:177], v[206:209], v[24:27]
	v_mfma_f32_16x16x32_bf16 v[20:23], v[182:185], v[206:209], v[20:23]
	v_mfma_f32_16x16x32_bf16 v[8:11], v[174:177], v[214:217], v[8:11]
	v_mfma_f32_16x16x32_bf16 v[4:7], v[182:185], v[214:217], v[4:7]
	v_mfma_f32_16x16x32_bf16 v[56:59], v[178:181], v[194:197], v[56:59]
	v_mfma_f32_16x16x32_bf16 v[52:55], v[186:189], v[194:197], v[52:55]
	v_mfma_f32_16x16x32_bf16 v[40:43], v[178:181], v[202:205], v[40:43]
	v_mfma_f32_16x16x32_bf16 v[36:39], v[186:189], v[202:205], v[36:39]
	v_mfma_f32_16x16x32_bf16 v[24:27], v[178:181], v[210:213], v[24:27]
	v_mfma_f32_16x16x32_bf16 v[20:23], v[186:189], v[210:213], v[20:23]
	v_mfma_f32_16x16x32_bf16 v[8:11], v[178:181], v[218:221], v[8:11]
	v_mfma_f32_16x16x32_bf16 v[4:7], v[186:189], v[218:221], v[4:7]
	s_setprio 0
	s_barrier
	s_cbranch_scc0 .LBB0_429
	s_and_b64 vcc, exec, s[22:23]
	s_cbranch_vccz .LBB0_432
	s_barrier

.LBB0_1031:
	s_ashr_i32 s27, s26, 31
	s_lshl_b64 s[28:29], s[26:27], 20
	s_cmp_eq_u32 s64, 0
	s_cselect_b32 s7, s1, s54
	s_cselect_b32 s5, s19, s55
	s_cselect_b32 s27, s35, s56
	s_cselect_b32 s50, s45, s57
	s_add_u32 s28, s7, s28
	s_addc_u32 s29, s5, s29
	s_and_b64 s[30:31], s[2:3], exec
	s_cselect_b32 s5, s29, s41
	s_cselect_b32 s7, s28, s40
	s_ashr_i32 s25, s24, 31
	s_lshl_b64 s[30:31], s[24:25], 20
	s_add_u32 s30, s27, s30
	s_addc_u32 s31, s50, s31
	s_and_b64 s[50:51], s[2:3], exec
	s_cselect_b32 s25, s31, s43
	s_cselect_b32 s27, s30, s42
	s_add_u32 s40, s40, 0x80080
	s_addc_u32 s41, s41, 0
	s_add_u32 s65, s42, 0x100
	s_addc_u32 s66, s43, 0
	s_mov_b32 s67, -2
	s_add_u32 s42, s40, 0xfff80080
	s_addc_u32 s43, s41, -1
	s_cmp_eq_u32 s67, 28
	s_cselect_b32 s51, s5, s43
	s_cselect_b32 s50, s7, s42
	s_cselect_b32 s43, s25, s66
	s_cselect_b32 s42, s27, s65
	s_add_i32 m0, s47, 0xc000
.LBB0_1032:
	v_add_u32_e32 v5, s60, v3
	ds_read_b128 v[140:143], v5
	ds_read_b128 v[144:147], v5 offset:1024
	ds_read_b128 v[148:151], v5 offset:2048
	ds_read_b128 v[152:155], v5 offset:3072
	v_add_u32_e32 v5, s61, v3
	ds_read_b128 v[156:159], v5
	ds_read_b128 v[160:163], v5 offset:1024
	ds_read_b128 v[164:167], v5 offset:2048
	ds_read_b128 v[168:171], v5 offset:3072
	ds_read_b128 v[172:175], v246
	ds_read_b128 v[176:179], v246 offset:1024
	ds_read_b128 v[180:183], v246 offset:2048
	ds_read_b128 v[184:187], v246 offset:3072
	ds_read_b128 v[188:191], v246 offset:4096
	ds_read_b128 v[192:195], v246 offset:5120
	ds_read_b128 v[196:199], v246 offset:6144
	ds_read_b128 v[200:203], v246 offset:7168
	global_load_lds_dwordx4 v216, s[40:41]
	s_add_i32 m0, s47, 0xe000
	s_nop 0
	global_load_lds_dwordx4 v218, s[40:41]
	s_waitcnt vmcnt(8)
	s_waitcnt lgkmcnt(0)
	s_setprio 1
	s_barrier
	v_mfma_f32_16x16x32_bf16 v[136:139], v[140:143], v[172:175], v[136:139]
	v_mfma_f32_16x16x32_bf16 v[132:135], v[148:151], v[172:175], v[132:135]
	v_mfma_f32_16x16x32_bf16 v[128:131], v[140:143], v[180:183], v[128:131]
	v_mfma_f32_16x16x32_bf16 v[124:127], v[148:151], v[180:183], v[124:127]
	v_mfma_f32_16x16x32_bf16 v[120:123], v[140:143], v[188:191], v[120:123]
	v_mfma_f32_16x16x32_bf16 v[116:119], v[148:151], v[188:191], v[116:119]
	v_mfma_f32_16x16x32_bf16 v[112:115], v[140:143], v[196:199], v[112:115]
	v_mfma_f32_16x16x32_bf16 v[108:111], v[148:151], v[196:199], v[108:111]
	v_mfma_f32_16x16x32_bf16 v[136:139], v[144:147], v[176:179], v[136:139]
	v_mfma_f32_16x16x32_bf16 v[132:135], v[152:155], v[176:179], v[132:135]
	v_mfma_f32_16x16x32_bf16 v[128:131], v[144:147], v[184:187], v[128:131]
	v_mfma_f32_16x16x32_bf16 v[124:127], v[152:155], v[184:187], v[124:127]
	v_mfma_f32_16x16x32_bf16 v[120:123], v[144:147], v[192:195], v[120:123]
	v_mfma_f32_16x16x32_bf16 v[116:119], v[152:155], v[192:195], v[116:119]
	v_mfma_f32_16x16x32_bf16 v[112:115], v[144:147], v[200:203], v[112:115]
	v_mfma_f32_16x16x32_bf16 v[108:111], v[152:155], v[200:203], v[108:111]
	s_setprio 0
	s_setprio 1
	v_mfma_f32_16x16x32_bf16 v[104:107], v[156:159], v[172:175], v[104:107]
	v_mfma_f32_16x16x32_bf16 v[100:103], v[164:167], v[172:175], v[100:103]
	v_mfma_f32_16x16x32_bf16 v[96:99], v[156:159], v[180:183], v[96:99]
	v_mfma_f32_16x16x32_bf16 v[92:95], v[164:167], v[180:183], v[92:95]
	v_mfma_f32_16x16x32_bf16 v[88:91], v[156:159], v[188:191], v[88:91]
	v_mfma_f32_16x16x32_bf16 v[84:87], v[164:167], v[188:191], v[84:87]
	v_mfma_f32_16x16x32_bf16 v[80:83], v[156:159], v[196:199], v[80:83]
	v_mfma_f32_16x16x32_bf16 v[76:79], v[164:167], v[196:199], v[76:79]
	v_mfma_f32_16x16x32_bf16 v[104:107], v[160:163], v[176:179], v[104:107]
	v_mfma_f32_16x16x32_bf16 v[100:103], v[168:171], v[176:179], v[100:103]
	v_mfma_f32_16x16x32_bf16 v[96:99], v[160:163], v[184:187], v[96:99]
	v_mfma_f32_16x16x32_bf16 v[92:95], v[168:171], v[184:187], v[92:95]
	v_mfma_f32_16x16x32_bf16 v[88:91], v[160:163], v[192:195], v[88:91]
	v_mfma_f32_16x16x32_bf16 v[84:87], v[168:171], v[192:195], v[84:87]
	v_mfma_f32_16x16x32_bf16 v[80:83], v[160:163], v[200:203], v[80:83]
	v_mfma_f32_16x16x32_bf16 v[76:79], v[168:171], v[200:203], v[76:79]
	s_setprio 0
	s_barrier
	s_add_i32 s68, s60, s46
	s_mov_b32 m0, s68
	ds_read_b128 v[172:175], v246 offset:16384
	ds_read_b128 v[176:179], v246 offset:17408
	ds_read_b128 v[180:183], v246 offset:18432
	ds_read_b128 v[184:187], v246 offset:19456
	ds_read_b128 v[188:191], v246 offset:20480
	ds_read_b128 v[192:195], v246 offset:21504
	ds_read_b128 v[196:199], v246 offset:22528
	ds_read_b128 v[200:203], v246 offset:23552
	global_load_lds_dwordx4 v210, s[42:43]
	s_add_i32 m0, s68, 0x2000
	s_add_u32 s70, s42, 0x80000
	s_addc_u32 s71, s43, 0
	s_add_i32 s68, s61, s46
	global_load_lds_dwordx4 v214, s[42:43]
	s_mov_b32 m0, s68
	s_nop 0
	global_load_lds_dwordx4 v210, s[70:71]
	s_add_i32 m0, s68, 0x2000
	s_nop 0
	global_load_lds_dwordx4 v214, s[70:71]
	s_mov_b32 m0, s47
	s_nop 0
	global_load_lds_dwordx4 v208, s[50:51]
	s_mov_b32 m0, s48
	s_nop 0
	global_load_lds_dwordx4 v212, s[50:51]
	s_waitcnt vmcnt(8)
	s_waitcnt lgkmcnt(0)
	s_setprio 1
	s_barrier
	v_mfma_f32_16x16x32_bf16 v[72:75], v[140:143], v[172:175], v[72:75]
	v_mfma_f32_16x16x32_bf16 v[68:71], v[148:151], v[172:175], v[68:71]
	v_mfma_f32_16x16x32_bf16 v[64:67], v[140:143], v[180:183], v[64:67]
	v_mfma_f32_16x16x32_bf16 v[60:63], v[148:151], v[180:183], v[60:63]
	v_mfma_f32_16x16x32_bf16 v[56:59], v[140:143], v[188:191], v[56:59]
	v_mfma_f32_16x16x32_bf16 v[52:55], v[148:151], v[188:191], v[52:55]
	v_mfma_f32_16x16x32_bf16 v[48:51], v[140:143], v[196:199], v[48:51]
	v_mfma_f32_16x16x32_bf16 v[44:47], v[148:151], v[196:199], v[44:47]
	v_mfma_f32_16x16x32_bf16 v[72:75], v[144:147], v[176:179], v[72:75]
	v_mfma_f32_16x16x32_bf16 v[68:71], v[152:155], v[176:179], v[68:71]
	v_mfma_f32_16x16x32_bf16 v[64:67], v[144:147], v[184:187], v[64:67]
	v_mfma_f32_16x16x32_bf16 v[60:63], v[152:155], v[184:187], v[60:63]
	v_mfma_f32_16x16x32_bf16 v[56:59], v[144:147], v[192:195], v[56:59]
	v_mfma_f32_16x16x32_bf16 v[52:55], v[152:155], v[192:195], v[52:55]
	v_mfma_f32_16x16x32_bf16 v[48:51], v[144:147], v[200:203], v[48:51]
	v_mfma_f32_16x16x32_bf16 v[44:47], v[152:155], v[200:203], v[44:47]
	s_setprio 0
	s_setprio 1
	v_mfma_f32_16x16x32_bf16 v[40:43], v[156:159], v[172:175], v[40:43]
	v_mfma_f32_16x16x32_bf16 v[36:39], v[164:167], v[172:175], v[36:39]
	v_mfma_f32_16x16x32_bf16 v[32:35], v[156:159], v[180:183], v[32:35]
	v_mfma_f32_16x16x32_bf16 v[28:31], v[164:167], v[180:183], v[28:31]
	v_mfma_f32_16x16x32_bf16 v[24:27], v[156:159], v[188:191], v[24:27]
	v_mfma_f32_16x16x32_bf16 v[20:23], v[164:167], v[188:191], v[20:23]
	v_mfma_f32_16x16x32_bf16 v[16:19], v[156:159], v[196:199], v[16:19]
	v_mfma_f32_16x16x32_bf16 v[12:15], v[164:167], v[196:199], v[12:15]
	v_mfma_f32_16x16x32_bf16 v[40:43], v[160:163], v[176:179], v[40:43]
	v_mfma_f32_16x16x32_bf16 v[36:39], v[168:171], v[176:179], v[36:39]
	v_mfma_f32_16x16x32_bf16 v[32:35], v[160:163], v[184:187], v[32:35]
	v_mfma_f32_16x16x32_bf16 v[28:31], v[168:171], v[184:187], v[28:31]
	v_mfma_f32_16x16x32_bf16 v[24:27], v[160:163], v[192:195], v[24:27]
	v_mfma_f32_16x16x32_bf16 v[20:23], v[168:171], v[192:195], v[20:23]
	v_mfma_f32_16x16x32_bf16 v[16:19], v[160:163], v[200:203], v[16:19]
	v_mfma_f32_16x16x32_bf16 v[12:15], v[168:171], v[200:203], v[12:15]
	s_setprio 0
	s_barrier
	s_add_i32 s68, 0, 0x18000
	v_add_u32_e32 v5, s68, v3
	s_add_i32 s70, 0, 0x1c000
	ds_read_b128 v[140:143], v5
	ds_read_b128 v[144:147], v5 offset:1024
	ds_read_b128 v[148:151], v5 offset:2048
	ds_read_b128 v[152:155], v5 offset:3072
	v_add_u32_e32 v5, s70, v3
	ds_read_b128 v[156:159], v5
	ds_read_b128 v[160:163], v5 offset:1024
	ds_read_b128 v[164:167], v5 offset:2048
	ds_read_b128 v[168:171], v5 offset:3072
	s_add_u32 s98, s50, 0x80000
	s_addc_u32 s99, s51, 0
	s_mov_b64 s[100:101], s[50:51]
	s_mov_b32 m0, s49
	ds_read_b128 v[172:175], v246 offset:32768
	ds_read_b128 v[176:179], v246 offset:33792
	ds_read_b128 v[180:183], v246 offset:34816
	ds_read_b128 v[184:187], v246 offset:35840
	ds_read_b128 v[188:191], v246 offset:36864
	ds_read_b128 v[192:195], v246 offset:37888
	ds_read_b128 v[196:199], v246 offset:38912
	ds_read_b128 v[200:203], v246 offset:39936
	global_load_lds_dwordx4 v208, s[98:99]
	s_mov_b32 m0, s52
	s_nop 0
	global_load_lds_dwordx4 v212, s[98:99]
	s_waitcnt vmcnt(8)
	s_waitcnt lgkmcnt(0)
	s_setprio 1
	s_barrier
	v_mfma_f32_16x16x32_bf16 v[136:139], v[140:143], v[172:175], v[136:139]
	v_mfma_f32_16x16x32_bf16 v[132:135], v[148:151], v[172:175], v[132:135]
	v_mfma_f32_16x16x32_bf16 v[128:131], v[140:143], v[180:183], v[128:131]
	v_mfma_f32_16x16x32_bf16 v[124:127], v[148:151], v[180:183], v[124:127]
	v_mfma_f32_16x16x32_bf16 v[120:123], v[140:143], v[188:191], v[120:123]
	v_mfma_f32_16x16x32_bf16 v[116:119], v[148:151], v[188:191], v[116:119]
	v_mfma_f32_16x16x32_bf16 v[112:115], v[140:143], v[196:199], v[112:115]
	v_mfma_f32_16x16x32_bf16 v[108:111], v[148:151], v[196:199], v[108:111]
	v_mfma_f32_16x16x32_bf16 v[136:139], v[144:147], v[176:179], v[136:139]
	v_mfma_f32_16x16x32_bf16 v[132:135], v[152:155], v[176:179], v[132:135]
	v_mfma_f32_16x16x32_bf16 v[128:131], v[144:147], v[184:187], v[128:131]
	v_mfma_f32_16x16x32_bf16 v[124:127], v[152:155], v[184:187], v[124:127]
	v_mfma_f32_16x16x32_bf16 v[120:123], v[144:147], v[192:195], v[120:123]
	v_mfma_f32_16x16x32_bf16 v[116:119], v[152:155], v[192:195], v[116:119]
	v_mfma_f32_16x16x32_bf16 v[112:115], v[144:147], v[200:203], v[112:115]
	v_mfma_f32_16x16x32_bf16 v[108:111], v[152:155], v[200:203], v[108:111]
	s_setprio 0
	s_setprio 1
	v_mfma_f32_16x16x32_bf16 v[104:107], v[156:159], v[172:175], v[104:107]
	v_mfma_f32_16x16x32_bf16 v[100:103], v[164:167], v[172:175], v[100:103]
	v_mfma_f32_16x16x32_bf16 v[96:99], v[156:159], v[180:183], v[96:99]
	v_mfma_f32_16x16x32_bf16 v[92:95], v[164:167], v[180:183], v[92:95]
	v_mfma_f32_16x16x32_bf16 v[88:91], v[156:159], v[188:191], v[88:91]
	v_mfma_f32_16x16x32_bf16 v[84:87], v[164:167], v[188:191], v[84:87]
	v_mfma_f32_16x16x32_bf16 v[80:83], v[156:159], v[196:199], v[80:83]
	v_mfma_f32_16x16x32_bf16 v[76:79], v[164:167], v[196:199], v[76:79]
	v_mfma_f32_16x16x32_bf16 v[104:107], v[160:163], v[176:179], v[104:107]
	v_mfma_f32_16x16x32_bf16 v[100:103], v[168:171], v[176:179], v[100:103]
	v_mfma_f32_16x16x32_bf16 v[96:99], v[160:163], v[184:187], v[96:99]
	v_mfma_f32_16x16x32_bf16 v[92:95], v[168:171], v[184:187], v[92:95]
	v_mfma_f32_16x16x32_bf16 v[88:91], v[160:163], v[192:195], v[88:91]
	v_mfma_f32_16x16x32_bf16 v[84:87], v[168:171], v[192:195], v[84:87]
	v_mfma_f32_16x16x32_bf16 v[80:83], v[160:163], v[200:203], v[80:83]
	v_mfma_f32_16x16x32_bf16 v[76:79], v[168:171], v[200:203], v[76:79]
	s_setprio 0
	s_barrier
	s_add_i32 s50, s68, s46
	s_add_i32 m0, s50, 0xffffff80
	ds_read_b128 v[172:175], v246 offset:49152
	ds_read_b128 v[176:179], v246 offset:50176
	ds_read_b128 v[180:183], v246 offset:51200
	ds_read_b128 v[184:187], v246 offset:52224
	ds_read_b128 v[188:191], v246 offset:53248
	ds_read_b128 v[192:195], v246 offset:54272
	ds_read_b128 v[196:199], v246 offset:55296
	ds_read_b128 v[200:203], v246 offset:56320
	global_load_lds_dwordx4 v210, s[42:43] offset:128
	s_add_i32 m0, s50, 0x1f80
	s_add_i32 s50, s70, s46
	global_load_lds_dwordx4 v214, s[42:43] offset:128
	s_add_u32 s42, s42, 0x80080
	s_addc_u32 s43, s43, 0
	s_mov_b32 m0, s50
	s_nop 0
	global_load_lds_dwordx4 v210, s[42:43]
	s_add_i32 m0, s50, 0x2000
	s_nop 0
	global_load_lds_dwordx4 v214, s[42:43]
	s_add_i32 m0, s58, 0xffffff80
	s_nop 0
	global_load_lds_dwordx4 v208, s[100:101] offset:128
	s_add_i32 m0, s59, 0xffffff80
	s_nop 0
	global_load_lds_dwordx4 v212, s[100:101] offset:128
	s_waitcnt vmcnt(8)
	s_waitcnt lgkmcnt(0)
	s_setprio 1
	s_barrier
	v_mfma_f32_16x16x32_bf16 v[72:75], v[140:143], v[172:175], v[72:75]
	v_mfma_f32_16x16x32_bf16 v[68:71], v[148:151], v[172:175], v[68:71]
	s_add_i32 s67, s67, 2
	v_mfma_f32_16x16x32_bf16 v[64:67], v[140:143], v[180:183], v[64:67]
	s_add_u32 s40, s40, 0x100
	v_mfma_f32_16x16x32_bf16 v[60:63], v[148:151], v[180:183], v[60:63]
	s_addc_u32 s41, s41, 0
	v_mfma_f32_16x16x32_bf16 v[56:59], v[140:143], v[188:191], v[56:59]
	s_add_u32 s65, s65, 0x100
	v_mfma_f32_16x16x32_bf16 v[52:55], v[148:151], v[188:191], v[52:55]
	s_addc_u32 s66, s66, 0
	v_mfma_f32_16x16x32_bf16 v[48:51], v[140:143], v[196:199], v[48:51]
	s_add_u32 s42, s40, 0xfff80080
	v_mfma_f32_16x16x32_bf16 v[44:47], v[148:151], v[196:199], v[44:47]
	s_addc_u32 s43, s41, -1
	v_mfma_f32_16x16x32_bf16 v[72:75], v[144:147], v[176:179], v[72:75]
	s_cmp_eq_u32 s67, 28
	v_mfma_f32_16x16x32_bf16 v[68:71], v[152:155], v[176:179], v[68:71]
	s_cselect_b32 s51, s5, s43
	v_mfma_f32_16x16x32_bf16 v[64:67], v[144:147], v[184:187], v[64:67]
	s_cselect_b32 s50, s7, s42
	v_mfma_f32_16x16x32_bf16 v[60:63], v[152:155], v[184:187], v[60:63]
	s_cselect_b32 s43, s25, s66
	v_mfma_f32_16x16x32_bf16 v[56:59], v[144:147], v[192:195], v[56:59]
	s_cselect_b32 s42, s27, s65
	v_mfma_f32_16x16x32_bf16 v[52:55], v[152:155], v[192:195], v[52:55]
	s_add_i32 m0, s47, 0xc000
	v_mfma_f32_16x16x32_bf16 v[48:51], v[144:147], v[200:203], v[48:51]
	s_cmp_gt_u32 s67, 29
	v_mfma_f32_16x16x32_bf16 v[44:47], v[152:155], v[200:203], v[44:47]
	s_setprio 0
	s_setprio 1
	v_mfma_f32_16x16x32_bf16 v[40:43], v[156:159], v[172:175], v[40:43]
	v_mfma_f32_16x16x32_bf16 v[36:39], v[164:167], v[172:175], v[36:39]
	v_mfma_f32_16x16x32_bf16 v[32:35], v[156:159], v[180:183], v[32:35]
	v_mfma_f32_16x16x32_bf16 v[28:31], v[164:167], v[180:183], v[28:31]
	v_mfma_f32_16x16x32_bf16 v[24:27], v[156:159], v[188:191], v[24:27]
	v_mfma_f32_16x16x32_bf16 v[20:23], v[164:167], v[188:191], v[20:23]
	v_mfma_f32_16x16x32_bf16 v[16:19], v[156:159], v[196:199], v[16:19]
	v_mfma_f32_16x16x32_bf16 v[12:15], v[164:167], v[196:199], v[12:15]
	v_mfma_f32_16x16x32_bf16 v[40:43], v[160:163], v[176:179], v[40:43]
	v_mfma_f32_16x16x32_bf16 v[36:39], v[168:171], v[176:179], v[36:39]
	v_mfma_f32_16x16x32_bf16 v[32:35], v[160:163], v[184:187], v[32:35]
	v_mfma_f32_16x16x32_bf16 v[28:31], v[168:171], v[184:187], v[28:31]
	v_mfma_f32_16x16x32_bf16 v[24:27], v[160:163], v[192:195], v[24:27]
	v_mfma_f32_16x16x32_bf16 v[20:23], v[168:171], v[192:195], v[20:23]
	v_mfma_f32_16x16x32_bf16 v[16:19], v[160:163], v[200:203], v[16:19]
	v_mfma_f32_16x16x32_bf16 v[12:15], v[168:171], v[200:203], v[12:15]
	s_setprio 0
	s_barrier
	s_cbranch_scc0 .LBB0_1032
	s_and_b64 vcc, exec, s[22:23]
	s_cbranch_vccz .LBB0_1035
	s_barrier

.LBB0_1202:
	s_ashr_i32 s25, s24, 31
	s_lshl_b64 s[26:27], s[24:25], 21
	s_add_u32 s26, s1, s26
	s_addc_u32 s27, s19, s27
	s_and_b64 s[28:29], s[4:5], exec
	s_cselect_b32 s25, s27, s43
	s_cselect_b32 s31, s26, s42
	s_ashr_i32 s23, s22, 31
	s_lshl_b64 s[28:29], s[22:23], 21
	s_add_u32 s28, s35, s28
	s_addc_u32 s29, s45, s29
	s_and_b64 s[52:53], s[4:5], exec
	s_cselect_b32 s23, s29, s51
	s_cselect_b32 s62, s28, s50
	s_add_u32 s42, s42, 0x100080
	s_addc_u32 s43, s43, 0
	s_add_u32 s63, s50, 0x100
	v_mov_b32_e32 v4, 0
	s_addc_u32 s64, s51, 0
	s_mov_b32 s65, -2
	s_waitcnt lgkmcnt(0)
	v_mov_b32_e32 v5, 0
	v_mov_b64_e32 v[6:7], 0
	v_mov_b64_e32 v[8:9], 0
	v_mov_b64_e32 v[10:11], 0
	v_mov_b64_e32 v[20:21], 0
	v_mov_b64_e32 v[22:23], 0
	v_mov_b64_e32 v[24:25], 0
	v_mov_b64_e32 v[26:27], 0
	v_mov_b64_e32 v[36:37], 0
	v_mov_b64_e32 v[38:39], 0
	v_mov_b64_e32 v[40:41], 0
	v_mov_b64_e32 v[42:43], 0
	v_mov_b64_e32 v[52:53], 0
	v_mov_b64_e32 v[54:55], 0
	v_mov_b64_e32 v[56:57], 0
	v_mov_b64_e32 v[58:59], 0
	v_mov_b64_e32 v[12:13], 0
	v_mov_b64_e32 v[14:15], 0
	v_mov_b64_e32 v[16:17], 0
	v_mov_b64_e32 v[18:19], 0
	v_mov_b64_e32 v[28:29], 0
	v_mov_b64_e32 v[30:31], 0
	v_mov_b64_e32 v[32:33], 0
	v_mov_b64_e32 v[34:35], 0
	v_mov_b64_e32 v[44:45], 0
	v_mov_b64_e32 v[46:47], 0
	v_mov_b64_e32 v[48:49], 0
	v_mov_b64_e32 v[50:51], 0
	v_mov_b64_e32 v[60:61], 0
	v_mov_b64_e32 v[62:63], 0
	v_mov_b64_e32 v[64:65], 0
	v_mov_b64_e32 v[66:67], 0
	v_mov_b64_e32 v[68:69], 0
	v_mov_b64_e32 v[70:71], 0
	v_mov_b64_e32 v[72:73], 0
	v_mov_b64_e32 v[74:75], 0
	v_mov_b64_e32 v[84:85], 0
	v_mov_b64_e32 v[86:87], 0
	v_mov_b64_e32 v[88:89], 0
	v_mov_b64_e32 v[90:91], 0
	v_mov_b64_e32 v[100:101], 0
	v_mov_b64_e32 v[102:103], 0
	v_mov_b64_e32 v[104:105], 0
	v_mov_b64_e32 v[106:107], 0
	v_mov_b64_e32 v[116:117], 0
	v_mov_b64_e32 v[118:119], 0
	v_mov_b64_e32 v[120:121], 0
	v_mov_b64_e32 v[122:123], 0
	v_mov_b64_e32 v[76:77], 0
	v_mov_b64_e32 v[78:79], 0
	v_mov_b64_e32 v[80:81], 0
	v_mov_b64_e32 v[82:83], 0
	v_mov_b64_e32 v[92:93], 0
	v_mov_b64_e32 v[94:95], 0
	v_mov_b64_e32 v[96:97], 0
	v_mov_b64_e32 v[98:99], 0
	v_mov_b64_e32 v[108:109], 0
	v_mov_b64_e32 v[110:111], 0
	v_mov_b64_e32 v[112:113], 0
	v_mov_b64_e32 v[114:115], 0
	v_mov_b64_e32 v[124:125], 0
	v_mov_b64_e32 v[126:127], 0
	v_mov_b64_e32 v[128:129], 0
	v_mov_b64_e32 v[130:131], 0
	s_add_u32 s0, s42, 0xfff00080
	s_addc_u32 s50, s43, -1
	s_cmp_eq_u32 s65, 60
	s_cselect_b32 s53, s25, s50
	s_cselect_b32 s52, s31, s0
	s_cselect_b32 s51, s23, s64
	s_cselect_b32 s50, s62, s63
	s_add_i32 m0, s41, 0xc000
.LBB0_1203:
	ds_read_b128 v[132:135], v187
	ds_read_b128 v[136:139], v187 offset:1024
	ds_read_b128 v[140:143], v187 offset:2048
	ds_read_b128 v[144:147], v187 offset:3072
	ds_read_b128 v[148:151], v188
	ds_read_b128 v[152:155], v188 offset:1024
	ds_read_b128 v[172:175], v188 offset:2048
	ds_read_b128 v[176:179], v188 offset:3072
	ds_read_b128 v[180:183], v189
	ds_read_b128 v[192:195], v189 offset:1024
	ds_read_b128 v[196:199], v189 offset:2048
	ds_read_b128 v[200:203], v189 offset:3072
	ds_read_b128 v[204:207], v189 offset:4096
	ds_read_b128 v[208:211], v189 offset:5120
	ds_read_b128 v[212:215], v189 offset:6144
	ds_read_b128 v[216:219], v189 offset:7168
	global_load_lds_dwordx4 v164, s[42:43]
	s_add_i32 m0, s41, 0xe000
	s_nop 0
	global_load_lds_dwordx4 v166, s[42:43]
	s_waitcnt vmcnt(8)
	s_waitcnt lgkmcnt(0)
	s_setprio 1
	s_barrier
	v_mfma_f32_16x16x32_bf16 v[128:131], v[132:135], v[180:183], v[128:131]
	v_mfma_f32_16x16x32_bf16 v[124:127], v[140:143], v[180:183], v[124:127]
	v_mfma_f32_16x16x32_bf16 v[112:115], v[132:135], v[196:199], v[112:115]
	v_mfma_f32_16x16x32_bf16 v[108:111], v[140:143], v[196:199], v[108:111]
	v_mfma_f32_16x16x32_bf16 v[96:99], v[132:135], v[204:207], v[96:99]
	v_mfma_f32_16x16x32_bf16 v[92:95], v[140:143], v[204:207], v[92:95]
	v_mfma_f32_16x16x32_bf16 v[80:83], v[132:135], v[212:215], v[80:83]
	v_mfma_f32_16x16x32_bf16 v[76:79], v[140:143], v[212:215], v[76:79]
	v_mfma_f32_16x16x32_bf16 v[128:131], v[136:139], v[192:195], v[128:131]
	v_mfma_f32_16x16x32_bf16 v[124:127], v[144:147], v[192:195], v[124:127]
	v_mfma_f32_16x16x32_bf16 v[112:115], v[136:139], v[200:203], v[112:115]
	v_mfma_f32_16x16x32_bf16 v[108:111], v[144:147], v[200:203], v[108:111]
	v_mfma_f32_16x16x32_bf16 v[96:99], v[136:139], v[208:211], v[96:99]
	v_mfma_f32_16x16x32_bf16 v[92:95], v[144:147], v[208:211], v[92:95]
	v_mfma_f32_16x16x32_bf16 v[80:83], v[136:139], v[216:219], v[80:83]
	v_mfma_f32_16x16x32_bf16 v[76:79], v[144:147], v[216:219], v[76:79]
	s_setprio 0
	s_setprio 1
	v_mfma_f32_16x16x32_bf16 v[120:123], v[148:151], v[180:183], v[120:123]
	v_mfma_f32_16x16x32_bf16 v[116:119], v[172:175], v[180:183], v[116:119]
	v_mfma_f32_16x16x32_bf16 v[104:107], v[148:151], v[196:199], v[104:107]
	v_mfma_f32_16x16x32_bf16 v[100:103], v[172:175], v[196:199], v[100:103]
	v_mfma_f32_16x16x32_bf16 v[88:91], v[148:151], v[204:207], v[88:91]
	v_mfma_f32_16x16x32_bf16 v[84:87], v[172:175], v[204:207], v[84:87]
	v_mfma_f32_16x16x32_bf16 v[72:75], v[148:151], v[212:215], v[72:75]
	v_mfma_f32_16x16x32_bf16 v[68:71], v[172:175], v[212:215], v[68:71]
	v_mfma_f32_16x16x32_bf16 v[120:123], v[152:155], v[192:195], v[120:123]
	v_mfma_f32_16x16x32_bf16 v[116:119], v[176:179], v[192:195], v[116:119]
	v_mfma_f32_16x16x32_bf16 v[104:107], v[152:155], v[200:203], v[104:107]
	v_mfma_f32_16x16x32_bf16 v[100:103], v[176:179], v[200:203], v[100:103]
	v_mfma_f32_16x16x32_bf16 v[88:91], v[152:155], v[208:211], v[88:91]
	v_mfma_f32_16x16x32_bf16 v[84:87], v[176:179], v[208:211], v[84:87]
	v_mfma_f32_16x16x32_bf16 v[72:75], v[152:155], v[216:219], v[72:75]
	v_mfma_f32_16x16x32_bf16 v[68:71], v[176:179], v[216:219], v[68:71]
	s_setprio 0
	s_barrier
	s_add_i32 s0, s59, s46
	s_mov_b32 m0, s0
	ds_read_b128 v[180:183], v189 offset:16384
	ds_read_b128 v[192:195], v189 offset:17408
	ds_read_b128 v[196:199], v189 offset:18432
	ds_read_b128 v[200:203], v189 offset:19456
	ds_read_b128 v[204:207], v189 offset:20480
	ds_read_b128 v[208:211], v189 offset:21504
	ds_read_b128 v[212:215], v189 offset:22528
	ds_read_b128 v[216:219], v189 offset:23552
	global_load_lds_dwordx4 v158, s[50:51]
	s_add_i32 m0, s0, 0x2000
	s_add_u32 s66, s50, 0x100000
	s_addc_u32 s67, s51, 0
	s_add_i32 s0, s60, s46
	global_load_lds_dwordx4 v162, s[50:51]
	s_mov_b32 m0, s0
	s_nop 0
	global_load_lds_dwordx4 v158, s[66:67]
	s_add_i32 m0, s0, 0x2000
	s_nop 0
	global_load_lds_dwordx4 v162, s[66:67]
	s_mov_b32 m0, s41
	s_nop 0
	global_load_lds_dwordx4 v156, s[52:53]
	s_mov_b32 m0, s47
	s_nop 0
	global_load_lds_dwordx4 v160, s[52:53]
	s_waitcnt vmcnt(8)
	s_waitcnt lgkmcnt(0)
	s_setprio 1
	s_barrier
	v_mfma_f32_16x16x32_bf16 v[64:67], v[132:135], v[180:183], v[64:67]
	v_mfma_f32_16x16x32_bf16 v[60:63], v[140:143], v[180:183], v[60:63]
	v_mfma_f32_16x16x32_bf16 v[48:51], v[132:135], v[196:199], v[48:51]
	v_mfma_f32_16x16x32_bf16 v[44:47], v[140:143], v[196:199], v[44:47]
	v_mfma_f32_16x16x32_bf16 v[32:35], v[132:135], v[204:207], v[32:35]
	v_mfma_f32_16x16x32_bf16 v[28:31], v[140:143], v[204:207], v[28:31]
	v_mfma_f32_16x16x32_bf16 v[16:19], v[132:135], v[212:215], v[16:19]
	v_mfma_f32_16x16x32_bf16 v[12:15], v[140:143], v[212:215], v[12:15]
	v_mfma_f32_16x16x32_bf16 v[64:67], v[136:139], v[192:195], v[64:67]
	v_mfma_f32_16x16x32_bf16 v[60:63], v[144:147], v[192:195], v[60:63]
	v_mfma_f32_16x16x32_bf16 v[48:51], v[136:139], v[200:203], v[48:51]
	v_mfma_f32_16x16x32_bf16 v[44:47], v[144:147], v[200:203], v[44:47]
	v_mfma_f32_16x16x32_bf16 v[32:35], v[136:139], v[208:211], v[32:35]
	v_mfma_f32_16x16x32_bf16 v[28:31], v[144:147], v[208:211], v[28:31]
	v_mfma_f32_16x16x32_bf16 v[16:19], v[136:139], v[216:219], v[16:19]
	v_mfma_f32_16x16x32_bf16 v[12:15], v[144:147], v[216:219], v[12:15]
	s_setprio 0
	s_setprio 1
	v_mfma_f32_16x16x32_bf16 v[56:59], v[148:151], v[180:183], v[56:59]
	v_mfma_f32_16x16x32_bf16 v[52:55], v[172:175], v[180:183], v[52:55]
	v_mfma_f32_16x16x32_bf16 v[40:43], v[148:151], v[196:199], v[40:43]
	v_mfma_f32_16x16x32_bf16 v[36:39], v[172:175], v[196:199], v[36:39]
	v_mfma_f32_16x16x32_bf16 v[24:27], v[148:151], v[204:207], v[24:27]
	v_mfma_f32_16x16x32_bf16 v[20:23], v[172:175], v[204:207], v[20:23]
	v_mfma_f32_16x16x32_bf16 v[8:11], v[148:151], v[212:215], v[8:11]
	v_mfma_f32_16x16x32_bf16 v[4:7], v[172:175], v[212:215], v[4:7]
	v_mfma_f32_16x16x32_bf16 v[56:59], v[152:155], v[192:195], v[56:59]
	v_mfma_f32_16x16x32_bf16 v[52:55], v[176:179], v[192:195], v[52:55]
	v_mfma_f32_16x16x32_bf16 v[40:43], v[152:155], v[200:203], v[40:43]
	v_mfma_f32_16x16x32_bf16 v[36:39], v[176:179], v[200:203], v[36:39]
	v_mfma_f32_16x16x32_bf16 v[24:27], v[152:155], v[208:211], v[24:27]
	v_mfma_f32_16x16x32_bf16 v[20:23], v[176:179], v[208:211], v[20:23]
	v_mfma_f32_16x16x32_bf16 v[8:11], v[152:155], v[216:219], v[8:11]
	v_mfma_f32_16x16x32_bf16 v[4:7], v[176:179], v[216:219], v[4:7]
	s_setprio 0
	s_barrier
	s_add_i32 s0, 0, 0x18000
	s_add_i32 s66, 0, 0x1c000
	v_add_u32_e32 v144, s0, v3
	v_add_u32_e32 v176, s66, v3
	ds_read_b128 v[132:135], v144
	ds_read_b128 v[136:139], v144 offset:1024
	ds_read_b128 v[140:143], v144 offset:2048
	ds_read_b128 v[144:147], v144 offset:3072
	ds_read_b128 v[148:151], v176
	ds_read_b128 v[152:155], v176 offset:1024
	ds_read_b128 v[172:175], v176 offset:2048
	ds_read_b128 v[176:179], v176 offset:3072
	s_add_u32 s98, s52, 0x100000
	s_addc_u32 s99, s53, 0
	s_mov_b32 m0, s48
	ds_read_b128 v[180:183], v189 offset:32768
	ds_read_b128 v[192:195], v189 offset:33792
	ds_read_b128 v[196:199], v189 offset:34816
	ds_read_b128 v[200:203], v189 offset:35840
	ds_read_b128 v[204:207], v189 offset:36864
	ds_read_b128 v[208:211], v189 offset:37888
	ds_read_b128 v[212:215], v189 offset:38912
	ds_read_b128 v[216:219], v189 offset:39936
	global_load_lds_dwordx4 v156, s[98:99]
	s_mov_b32 m0, s49
	s_nop 0
	global_load_lds_dwordx4 v160, s[98:99]
	s_waitcnt vmcnt(8)
	s_waitcnt lgkmcnt(0)
	s_setprio 1
	s_barrier
	v_mfma_f32_16x16x32_bf16 v[128:131], v[132:135], v[180:183], v[128:131]
	v_mfma_f32_16x16x32_bf16 v[124:127], v[140:143], v[180:183], v[124:127]
	v_mfma_f32_16x16x32_bf16 v[112:115], v[132:135], v[196:199], v[112:115]
	v_mfma_f32_16x16x32_bf16 v[108:111], v[140:143], v[196:199], v[108:111]
	v_mfma_f32_16x16x32_bf16 v[96:99], v[132:135], v[204:207], v[96:99]
	v_mfma_f32_16x16x32_bf16 v[92:95], v[140:143], v[204:207], v[92:95]
	v_mfma_f32_16x16x32_bf16 v[80:83], v[132:135], v[212:215], v[80:83]
	v_mfma_f32_16x16x32_bf16 v[76:79], v[140:143], v[212:215], v[76:79]
	v_mfma_f32_16x16x32_bf16 v[128:131], v[136:139], v[192:195], v[128:131]
	v_mfma_f32_16x16x32_bf16 v[124:127], v[144:147], v[192:195], v[124:127]
	v_mfma_f32_16x16x32_bf16 v[112:115], v[136:139], v[200:203], v[112:115]
	v_mfma_f32_16x16x32_bf16 v[108:111], v[144:147], v[200:203], v[108:111]
	v_mfma_f32_16x16x32_bf16 v[96:99], v[136:139], v[208:211], v[96:99]
	v_mfma_f32_16x16x32_bf16 v[92:95], v[144:147], v[208:211], v[92:95]
	v_mfma_f32_16x16x32_bf16 v[80:83], v[136:139], v[216:219], v[80:83]
	v_mfma_f32_16x16x32_bf16 v[76:79], v[144:147], v[216:219], v[76:79]
	s_setprio 0
	s_setprio 1
	v_mfma_f32_16x16x32_bf16 v[120:123], v[148:151], v[180:183], v[120:123]
	v_mfma_f32_16x16x32_bf16 v[116:119], v[172:175], v[180:183], v[116:119]
	v_mfma_f32_16x16x32_bf16 v[104:107], v[148:151], v[196:199], v[104:107]
	v_mfma_f32_16x16x32_bf16 v[100:103], v[172:175], v[196:199], v[100:103]
	v_mfma_f32_16x16x32_bf16 v[88:91], v[148:151], v[204:207], v[88:91]
	v_mfma_f32_16x16x32_bf16 v[84:87], v[172:175], v[204:207], v[84:87]
	v_mfma_f32_16x16x32_bf16 v[72:75], v[148:151], v[212:215], v[72:75]
	v_mfma_f32_16x16x32_bf16 v[68:71], v[172:175], v[212:215], v[68:71]
	v_mfma_f32_16x16x32_bf16 v[120:123], v[152:155], v[192:195], v[120:123]
	v_mfma_f32_16x16x32_bf16 v[116:119], v[176:179], v[192:195], v[116:119]
	v_mfma_f32_16x16x32_bf16 v[104:107], v[152:155], v[200:203], v[104:107]
	v_mfma_f32_16x16x32_bf16 v[100:103], v[176:179], v[200:203], v[100:103]
	v_mfma_f32_16x16x32_bf16 v[88:91], v[152:155], v[208:211], v[88:91]
	v_mfma_f32_16x16x32_bf16 v[84:87], v[176:179], v[208:211], v[84:87]
	v_mfma_f32_16x16x32_bf16 v[72:75], v[152:155], v[216:219], v[72:75]
	v_mfma_f32_16x16x32_bf16 v[68:71], v[176:179], v[216:219], v[68:71]
	s_setprio 0
	s_barrier
	s_add_i32 s0, s0, s46
	s_add_i32 m0, s0, 0xffffff80
	ds_read_b128 v[180:183], v189 offset:49152
	ds_read_b128 v[192:195], v189 offset:50176
	ds_read_b128 v[196:199], v189 offset:51200
	ds_read_b128 v[200:203], v189 offset:52224
	ds_read_b128 v[204:207], v189 offset:53248
	ds_read_b128 v[208:211], v189 offset:54272
	ds_read_b128 v[212:215], v189 offset:55296
	ds_read_b128 v[216:219], v189 offset:56320
	global_load_lds_dwordx4 v158, s[50:51] offset:128
	s_add_i32 m0, s0, 0x1f80
	s_add_i32 s0, s66, s46
	global_load_lds_dwordx4 v162, s[50:51] offset:128
	s_add_u32 s50, s50, 0x100080
	s_addc_u32 s51, s51, 0
	s_mov_b32 m0, s0
	s_nop 0
	global_load_lds_dwordx4 v158, s[50:51]
	s_add_i32 m0, s0, 0x2000
	s_nop 0
	global_load_lds_dwordx4 v162, s[50:51]
	s_add_i32 m0, s57, 0xffffff80
	s_nop 0
	global_load_lds_dwordx4 v156, s[52:53] offset:128
	s_add_i32 m0, s58, 0xffffff80
	s_nop 0
	global_load_lds_dwordx4 v160, s[52:53] offset:128
	s_waitcnt vmcnt(8)
	s_waitcnt lgkmcnt(0)
	s_setprio 1
	s_barrier
	v_mfma_f32_16x16x32_bf16 v[64:67], v[132:135], v[180:183], v[64:67]
	v_mfma_f32_16x16x32_bf16 v[60:63], v[140:143], v[180:183], v[60:63]
	s_add_i32 s65, s65, 2
	v_mfma_f32_16x16x32_bf16 v[48:51], v[132:135], v[196:199], v[48:51]
	s_add_u32 s42, s42, 0x100
	v_mfma_f32_16x16x32_bf16 v[44:47], v[140:143], v[196:199], v[44:47]
	s_addc_u32 s43, s43, 0
	v_mfma_f32_16x16x32_bf16 v[32:35], v[132:135], v[204:207], v[32:35]
	s_add_u32 s63, s63, 0x100
	v_mfma_f32_16x16x32_bf16 v[28:31], v[140:143], v[204:207], v[28:31]
	s_addc_u32 s64, s64, 0
	v_mfma_f32_16x16x32_bf16 v[16:19], v[132:135], v[212:215], v[16:19]
	s_add_u32 s0, s42, 0xfff00080
	v_mfma_f32_16x16x32_bf16 v[12:15], v[140:143], v[212:215], v[12:15]
	s_addc_u32 s50, s43, -1
	v_mfma_f32_16x16x32_bf16 v[64:67], v[136:139], v[192:195], v[64:67]
	s_cmp_eq_u32 s65, 60
	v_mfma_f32_16x16x32_bf16 v[60:63], v[144:147], v[192:195], v[60:63]
	s_cselect_b32 s53, s25, s50
	v_mfma_f32_16x16x32_bf16 v[48:51], v[136:139], v[200:203], v[48:51]
	s_cselect_b32 s52, s31, s0
	v_mfma_f32_16x16x32_bf16 v[44:47], v[144:147], v[200:203], v[44:47]
	s_cselect_b32 s51, s23, s64
	v_mfma_f32_16x16x32_bf16 v[32:35], v[136:139], v[208:211], v[32:35]
	s_cselect_b32 s50, s62, s63
	v_mfma_f32_16x16x32_bf16 v[28:31], v[144:147], v[208:211], v[28:31]
	s_add_i32 m0, s41, 0xc000
	v_mfma_f32_16x16x32_bf16 v[16:19], v[136:139], v[216:219], v[16:19]
	s_cmp_gt_u32 s65, 61
	v_mfma_f32_16x16x32_bf16 v[12:15], v[144:147], v[216:219], v[12:15]
	s_setprio 0
	s_setprio 1
	v_mfma_f32_16x16x32_bf16 v[56:59], v[148:151], v[180:183], v[56:59]
	v_mfma_f32_16x16x32_bf16 v[52:55], v[172:175], v[180:183], v[52:55]
	v_mfma_f32_16x16x32_bf16 v[40:43], v[148:151], v[196:199], v[40:43]
	v_mfma_f32_16x16x32_bf16 v[36:39], v[172:175], v[196:199], v[36:39]
	v_mfma_f32_16x16x32_bf16 v[24:27], v[148:151], v[204:207], v[24:27]
	v_mfma_f32_16x16x32_bf16 v[20:23], v[172:175], v[204:207], v[20:23]
	v_mfma_f32_16x16x32_bf16 v[8:11], v[148:151], v[212:215], v[8:11]
	v_mfma_f32_16x16x32_bf16 v[4:7], v[172:175], v[212:215], v[4:7]
	v_mfma_f32_16x16x32_bf16 v[56:59], v[152:155], v[192:195], v[56:59]
	v_mfma_f32_16x16x32_bf16 v[52:55], v[176:179], v[192:195], v[52:55]
	v_mfma_f32_16x16x32_bf16 v[40:43], v[152:155], v[200:203], v[40:43]
	v_mfma_f32_16x16x32_bf16 v[36:39], v[176:179], v[200:203], v[36:39]
	v_mfma_f32_16x16x32_bf16 v[24:27], v[152:155], v[208:211], v[24:27]
	v_mfma_f32_16x16x32_bf16 v[20:23], v[176:179], v[208:211], v[20:23]
	v_mfma_f32_16x16x32_bf16 v[8:11], v[152:155], v[216:219], v[8:11]
	v_mfma_f32_16x16x32_bf16 v[4:7], v[176:179], v[216:219], v[4:7]
	s_setprio 0
	s_barrier
	s_cbranch_scc0 .LBB0_1203
	s_and_b64 vcc, exec, s[20:21]
	s_cbranch_vccz .LBB0_1206
	s_barrier

.LBB0_1287:
	s_add_u32 s42, s42, 0x100080
	s_addc_u32 s43, s43, 0
	s_add_u32 s31, s50, 0x100
	v_mov_b32_e32 v4, 0
	s_addc_u32 s41, s51, 0
	s_mov_b32 s70, -2
	v_mov_b32_e32 v5, 0
	v_mov_b64_e32 v[6:7], 0
	v_mov_b64_e32 v[8:9], 0
	v_mov_b64_e32 v[10:11], 0
	v_mov_b64_e32 v[12:13], 0
	v_mov_b64_e32 v[14:15], 0
	v_mov_b64_e32 v[16:17], 0
	v_mov_b64_e32 v[18:19], 0
	v_mov_b64_e32 v[28:29], 0
	v_mov_b64_e32 v[30:31], 0
	v_mov_b64_e32 v[32:33], 0
	v_mov_b64_e32 v[34:35], 0
	v_mov_b64_e32 v[44:45], 0
	v_mov_b64_e32 v[46:47], 0
	v_mov_b64_e32 v[48:49], 0
	v_mov_b64_e32 v[50:51], 0
	v_mov_b64_e32 v[20:21], 0
	v_mov_b64_e32 v[22:23], 0
	v_mov_b64_e32 v[24:25], 0
	v_mov_b64_e32 v[26:27], 0
	v_mov_b64_e32 v[36:37], 0
	v_mov_b64_e32 v[38:39], 0
	v_mov_b64_e32 v[40:41], 0
	v_mov_b64_e32 v[42:43], 0
	v_mov_b64_e32 v[52:53], 0
	v_mov_b64_e32 v[54:55], 0
	v_mov_b64_e32 v[56:57], 0
	v_mov_b64_e32 v[58:59], 0
	v_mov_b64_e32 v[60:61], 0
	v_mov_b64_e32 v[62:63], 0
	v_mov_b64_e32 v[64:65], 0
	v_mov_b64_e32 v[66:67], 0
	v_mov_b64_e32 v[68:69], 0
	v_mov_b64_e32 v[70:71], 0
	v_mov_b64_e32 v[72:73], 0
	v_mov_b64_e32 v[74:75], 0
	v_mov_b64_e32 v[76:77], 0
	v_mov_b64_e32 v[78:79], 0
	v_mov_b64_e32 v[80:81], 0
	v_mov_b64_e32 v[82:83], 0
	v_mov_b64_e32 v[92:93], 0
	v_mov_b64_e32 v[94:95], 0
	v_mov_b64_e32 v[96:97], 0
	v_mov_b64_e32 v[98:99], 0
	v_mov_b64_e32 v[108:109], 0
	v_mov_b64_e32 v[110:111], 0
	v_mov_b64_e32 v[112:113], 0
	v_mov_b64_e32 v[114:115], 0
	v_mov_b64_e32 v[84:85], 0
	v_mov_b64_e32 v[86:87], 0
	v_mov_b64_e32 v[88:89], 0
	v_mov_b64_e32 v[90:91], 0
	v_mov_b64_e32 v[100:101], 0
	v_mov_b64_e32 v[102:103], 0
	v_mov_b64_e32 v[104:105], 0
	v_mov_b64_e32 v[106:107], 0
	v_mov_b64_e32 v[116:117], 0
	v_mov_b64_e32 v[118:119], 0
	v_mov_b64_e32 v[120:121], 0
	v_mov_b64_e32 v[122:123], 0
	v_mov_b64_e32 v[124:125], 0
	v_mov_b64_e32 v[126:127], 0
	v_mov_b64_e32 v[128:129], 0
	v_mov_b64_e32 v[130:131], 0
	s_add_u32 s0, s42, 0xfff00080
	s_addc_u32 s50, s43, -1
	s_cmp_eq_u32 s70, 12
	s_cselect_b32 s53, s29, s50
	s_cselect_b32 s52, s28, s0
	s_cselect_b32 s51, s5, s41
	s_cselect_b32 s50, s4, s31
	s_add_i32 m0, s17, 0xc000
.LBB0_1288:
	ds_read_b128 v[154:157], v150
	ds_read_b128 v[158:161], v150 offset:1024
	ds_read_b128 v[162:165], v150 offset:2048
	ds_read_b128 v[166:169], v150 offset:3072
	ds_read_b128 v[170:173], v151
	ds_read_b128 v[174:177], v151 offset:1024
	ds_read_b128 v[178:181], v151 offset:2048
	ds_read_b128 v[182:185], v151 offset:3072
	ds_read_b128 v[186:189], v152
	ds_read_b128 v[190:193], v152 offset:1024
	ds_read_b128 v[194:197], v152 offset:2048
	ds_read_b128 v[198:201], v152 offset:3072
	ds_read_b128 v[202:205], v152 offset:4096
	ds_read_b128 v[206:209], v152 offset:5120
	ds_read_b128 v[210:213], v152 offset:6144
	ds_read_b128 v[214:217], v152 offset:7168
	global_load_lds_dwordx4 v142, s[42:43]
	s_add_i32 m0, s17, 0xe000
	s_nop 0
	global_load_lds_dwordx4 v144, s[42:43]
	s_waitcnt vmcnt(8)
	s_waitcnt lgkmcnt(0)
	s_setprio 1
	s_barrier
	v_mfma_f32_16x16x32_bf16 v[128:131], v[154:157], v[186:189], v[128:131]
	v_mfma_f32_16x16x32_bf16 v[124:127], v[162:165], v[186:189], v[124:127]
	v_mfma_f32_16x16x32_bf16 v[120:123], v[154:157], v[194:197], v[120:123]
	v_mfma_f32_16x16x32_bf16 v[116:119], v[162:165], v[194:197], v[116:119]
	v_mfma_f32_16x16x32_bf16 v[104:107], v[154:157], v[202:205], v[104:107]
	v_mfma_f32_16x16x32_bf16 v[100:103], v[162:165], v[202:205], v[100:103]
	v_mfma_f32_16x16x32_bf16 v[88:91], v[154:157], v[210:213], v[88:91]
	v_mfma_f32_16x16x32_bf16 v[84:87], v[162:165], v[210:213], v[84:87]
	v_mfma_f32_16x16x32_bf16 v[128:131], v[158:161], v[190:193], v[128:131]
	v_mfma_f32_16x16x32_bf16 v[124:127], v[166:169], v[190:193], v[124:127]
	v_mfma_f32_16x16x32_bf16 v[120:123], v[158:161], v[198:201], v[120:123]
	v_mfma_f32_16x16x32_bf16 v[116:119], v[166:169], v[198:201], v[116:119]
	v_mfma_f32_16x16x32_bf16 v[104:107], v[158:161], v[206:209], v[104:107]
	v_mfma_f32_16x16x32_bf16 v[100:103], v[166:169], v[206:209], v[100:103]
	v_mfma_f32_16x16x32_bf16 v[88:91], v[158:161], v[214:217], v[88:91]
	v_mfma_f32_16x16x32_bf16 v[84:87], v[166:169], v[214:217], v[84:87]
	s_setprio 0
	s_setprio 1
	v_mfma_f32_16x16x32_bf16 v[112:115], v[170:173], v[186:189], v[112:115]
	v_mfma_f32_16x16x32_bf16 v[108:111], v[178:181], v[186:189], v[108:111]
	v_mfma_f32_16x16x32_bf16 v[96:99], v[170:173], v[194:197], v[96:99]
	v_mfma_f32_16x16x32_bf16 v[92:95], v[178:181], v[194:197], v[92:95]
	v_mfma_f32_16x16x32_bf16 v[80:83], v[170:173], v[202:205], v[80:83]
	v_mfma_f32_16x16x32_bf16 v[76:79], v[178:181], v[202:205], v[76:79]
	v_mfma_f32_16x16x32_bf16 v[72:75], v[170:173], v[210:213], v[72:75]
	v_mfma_f32_16x16x32_bf16 v[68:71], v[178:181], v[210:213], v[68:71]
	v_mfma_f32_16x16x32_bf16 v[112:115], v[174:177], v[190:193], v[112:115]
	v_mfma_f32_16x16x32_bf16 v[108:111], v[182:185], v[190:193], v[108:111]
	v_mfma_f32_16x16x32_bf16 v[96:99], v[174:177], v[198:201], v[96:99]
	v_mfma_f32_16x16x32_bf16 v[92:95], v[182:185], v[198:201], v[92:95]
	v_mfma_f32_16x16x32_bf16 v[80:83], v[174:177], v[206:209], v[80:83]
	v_mfma_f32_16x16x32_bf16 v[76:79], v[182:185], v[206:209], v[76:79]
	v_mfma_f32_16x16x32_bf16 v[72:75], v[174:177], v[214:217], v[72:75]
	v_mfma_f32_16x16x32_bf16 v[68:71], v[182:185], v[214:217], v[68:71]
	s_setprio 0
	s_barrier
	s_add_i32 s0, s60, s46
	s_mov_b32 m0, s0
	ds_read_b128 v[186:189], v152 offset:16384
	ds_read_b128 v[190:193], v152 offset:17408
	ds_read_b128 v[194:197], v152 offset:18432
	ds_read_b128 v[198:201], v152 offset:19456
	ds_read_b128 v[202:205], v152 offset:20480
	ds_read_b128 v[206:209], v152 offset:21504
	ds_read_b128 v[210:213], v152 offset:22528
	ds_read_b128 v[214:217], v152 offset:23552
	global_load_lds_dwordx4 v136, s[50:51]
	s_add_i32 m0, s0, 0x2000
	s_add_u32 s72, s50, 0x100000
	s_addc_u32 s73, s51, 0
	s_add_i32 s0, s61, s46
	global_load_lds_dwordx4 v132, s[50:51]
	s_mov_b32 m0, s0
	s_nop 0
	global_load_lds_dwordx4 v136, s[72:73]
	s_add_i32 m0, s0, 0x2000
	s_nop 0
	global_load_lds_dwordx4 v132, s[72:73]
	s_mov_b32 m0, s17
	s_nop 0
	global_load_lds_dwordx4 v138, s[52:53]
	s_mov_b32 m0, s47
	s_nop 0
	global_load_lds_dwordx4 v134, s[52:53]
	s_waitcnt vmcnt(8)
	s_waitcnt lgkmcnt(0)
	s_setprio 1
	s_barrier
	v_mfma_f32_16x16x32_bf16 v[64:67], v[154:157], v[186:189], v[64:67]
	v_mfma_f32_16x16x32_bf16 v[60:63], v[162:165], v[186:189], v[60:63]
	v_mfma_f32_16x16x32_bf16 v[56:59], v[154:157], v[194:197], v[56:59]
	v_mfma_f32_16x16x32_bf16 v[52:55], v[162:165], v[194:197], v[52:55]
	v_mfma_f32_16x16x32_bf16 v[40:43], v[154:157], v[202:205], v[40:43]
	v_mfma_f32_16x16x32_bf16 v[36:39], v[162:165], v[202:205], v[36:39]
	v_mfma_f32_16x16x32_bf16 v[24:27], v[154:157], v[210:213], v[24:27]
	v_mfma_f32_16x16x32_bf16 v[20:23], v[162:165], v[210:213], v[20:23]
	v_mfma_f32_16x16x32_bf16 v[64:67], v[158:161], v[190:193], v[64:67]
	v_mfma_f32_16x16x32_bf16 v[60:63], v[166:169], v[190:193], v[60:63]
	v_mfma_f32_16x16x32_bf16 v[56:59], v[158:161], v[198:201], v[56:59]
	v_mfma_f32_16x16x32_bf16 v[52:55], v[166:169], v[198:201], v[52:55]
	v_mfma_f32_16x16x32_bf16 v[40:43], v[158:161], v[206:209], v[40:43]
	v_mfma_f32_16x16x32_bf16 v[36:39], v[166:169], v[206:209], v[36:39]
	v_mfma_f32_16x16x32_bf16 v[24:27], v[158:161], v[214:217], v[24:27]
	v_mfma_f32_16x16x32_bf16 v[20:23], v[166:169], v[214:217], v[20:23]
	s_setprio 0
	s_setprio 1
	v_mfma_f32_16x16x32_bf16 v[48:51], v[170:173], v[186:189], v[48:51]
	v_mfma_f32_16x16x32_bf16 v[44:47], v[178:181], v[186:189], v[44:47]
	v_mfma_f32_16x16x32_bf16 v[32:35], v[170:173], v[194:197], v[32:35]
	v_mfma_f32_16x16x32_bf16 v[28:31], v[178:181], v[194:197], v[28:31]
	v_mfma_f32_16x16x32_bf16 v[16:19], v[170:173], v[202:205], v[16:19]
	v_mfma_f32_16x16x32_bf16 v[12:15], v[178:181], v[202:205], v[12:15]
	v_mfma_f32_16x16x32_bf16 v[8:11], v[170:173], v[210:213], v[8:11]
	v_mfma_f32_16x16x32_bf16 v[4:7], v[178:181], v[210:213], v[4:7]
	v_mfma_f32_16x16x32_bf16 v[48:51], v[174:177], v[190:193], v[48:51]
	v_mfma_f32_16x16x32_bf16 v[44:47], v[182:185], v[190:193], v[44:47]
	v_mfma_f32_16x16x32_bf16 v[32:35], v[174:177], v[198:201], v[32:35]
	v_mfma_f32_16x16x32_bf16 v[28:31], v[182:185], v[198:201], v[28:31]
	v_mfma_f32_16x16x32_bf16 v[16:19], v[174:177], v[206:209], v[16:19]
	v_mfma_f32_16x16x32_bf16 v[12:15], v[182:185], v[206:209], v[12:15]
	v_mfma_f32_16x16x32_bf16 v[8:11], v[174:177], v[214:217], v[8:11]
	v_mfma_f32_16x16x32_bf16 v[4:7], v[182:185], v[214:217], v[4:7]
	s_setprio 0
	s_barrier
	s_add_i32 s0, 0, 0x18000
	v_add_u32_e32 v140, s0, v3
	s_add_i32 s71, 0, 0x1c000
	ds_read_b128 v[154:157], v140
	ds_read_b128 v[158:161], v140 offset:1024
	ds_read_b128 v[162:165], v140 offset:2048
	ds_read_b128 v[166:169], v140 offset:3072
	v_add_u32_e32 v140, s71, v3
	ds_read_b128 v[170:173], v140
	ds_read_b128 v[174:177], v140 offset:1024
	ds_read_b128 v[178:181], v140 offset:2048
	ds_read_b128 v[182:185], v140 offset:3072
	s_add_u32 s98, s52, 0x100000
	s_addc_u32 s99, s53, 0
	s_mov_b32 m0, s48
	ds_read_b128 v[186:189], v152 offset:32768
	ds_read_b128 v[190:193], v152 offset:33792
	ds_read_b128 v[194:197], v152 offset:34816
	ds_read_b128 v[198:201], v152 offset:35840
	ds_read_b128 v[202:205], v152 offset:36864
	ds_read_b128 v[206:209], v152 offset:37888
	ds_read_b128 v[210:213], v152 offset:38912
	ds_read_b128 v[214:217], v152 offset:39936
	global_load_lds_dwordx4 v138, s[98:99]
	s_mov_b32 m0, s49
	s_nop 0
	global_load_lds_dwordx4 v134, s[98:99]
	s_waitcnt vmcnt(8)
	s_waitcnt lgkmcnt(0)
	s_setprio 1
	s_barrier
	v_mfma_f32_16x16x32_bf16 v[128:131], v[154:157], v[186:189], v[128:131]
	v_mfma_f32_16x16x32_bf16 v[124:127], v[162:165], v[186:189], v[124:127]
	v_mfma_f32_16x16x32_bf16 v[120:123], v[154:157], v[194:197], v[120:123]
	v_mfma_f32_16x16x32_bf16 v[116:119], v[162:165], v[194:197], v[116:119]
	v_mfma_f32_16x16x32_bf16 v[104:107], v[154:157], v[202:205], v[104:107]
	v_mfma_f32_16x16x32_bf16 v[100:103], v[162:165], v[202:205], v[100:103]
	v_mfma_f32_16x16x32_bf16 v[88:91], v[154:157], v[210:213], v[88:91]
	v_mfma_f32_16x16x32_bf16 v[84:87], v[162:165], v[210:213], v[84:87]
	v_mfma_f32_16x16x32_bf16 v[128:131], v[158:161], v[190:193], v[128:131]
	v_mfma_f32_16x16x32_bf16 v[124:127], v[166:169], v[190:193], v[124:127]
	v_mfma_f32_16x16x32_bf16 v[120:123], v[158:161], v[198:201], v[120:123]
	v_mfma_f32_16x16x32_bf16 v[116:119], v[166:169], v[198:201], v[116:119]
	v_mfma_f32_16x16x32_bf16 v[104:107], v[158:161], v[206:209], v[104:107]
	v_mfma_f32_16x16x32_bf16 v[100:103], v[166:169], v[206:209], v[100:103]
	v_mfma_f32_16x16x32_bf16 v[88:91], v[158:161], v[214:217], v[88:91]
	v_mfma_f32_16x16x32_bf16 v[84:87], v[166:169], v[214:217], v[84:87]
	s_setprio 0
	s_setprio 1
	v_mfma_f32_16x16x32_bf16 v[112:115], v[170:173], v[186:189], v[112:115]
	v_mfma_f32_16x16x32_bf16 v[108:111], v[178:181], v[186:189], v[108:111]
	v_mfma_f32_16x16x32_bf16 v[96:99], v[170:173], v[194:197], v[96:99]
	v_mfma_f32_16x16x32_bf16 v[92:95], v[178:181], v[194:197], v[92:95]
	v_mfma_f32_16x16x32_bf16 v[80:83], v[170:173], v[202:205], v[80:83]
	v_mfma_f32_16x16x32_bf16 v[76:79], v[178:181], v[202:205], v[76:79]
	v_mfma_f32_16x16x32_bf16 v[72:75], v[170:173], v[210:213], v[72:75]
	v_mfma_f32_16x16x32_bf16 v[68:71], v[178:181], v[210:213], v[68:71]
	v_mfma_f32_16x16x32_bf16 v[112:115], v[174:177], v[190:193], v[112:115]
	v_mfma_f32_16x16x32_bf16 v[108:111], v[182:185], v[190:193], v[108:111]
	v_mfma_f32_16x16x32_bf16 v[96:99], v[174:177], v[198:201], v[96:99]
	v_mfma_f32_16x16x32_bf16 v[92:95], v[182:185], v[198:201], v[92:95]
	v_mfma_f32_16x16x32_bf16 v[80:83], v[174:177], v[206:209], v[80:83]
	v_mfma_f32_16x16x32_bf16 v[76:79], v[182:185], v[206:209], v[76:79]
	v_mfma_f32_16x16x32_bf16 v[72:75], v[174:177], v[214:217], v[72:75]
	v_mfma_f32_16x16x32_bf16 v[68:71], v[182:185], v[214:217], v[68:71]
	s_setprio 0
	s_barrier
	s_add_i32 s0, s0, s46
	s_add_i32 m0, s0, 0xffffff80
	ds_read_b128 v[186:189], v152 offset:49152
	ds_read_b128 v[190:193], v152 offset:50176
	ds_read_b128 v[194:197], v152 offset:51200
	ds_read_b128 v[198:201], v152 offset:52224
	ds_read_b128 v[202:205], v152 offset:53248
	ds_read_b128 v[206:209], v152 offset:54272
	ds_read_b128 v[210:213], v152 offset:55296
	ds_read_b128 v[214:217], v152 offset:56320
	global_load_lds_dwordx4 v136, s[50:51] offset:128
	s_add_i32 m0, s0, 0x1f80
	s_add_i32 s0, s71, s46
	global_load_lds_dwordx4 v132, s[50:51] offset:128
	s_add_u32 s50, s50, 0x100080
	s_addc_u32 s51, s51, 0
	s_mov_b32 m0, s0
	s_nop 0
	global_load_lds_dwordx4 v136, s[50:51]
	s_add_i32 m0, s0, 0x2000
	s_nop 0
	global_load_lds_dwordx4 v132, s[50:51]
	s_add_i32 m0, s58, 0xffffff80
	s_nop 0
	global_load_lds_dwordx4 v138, s[52:53] offset:128
	s_add_i32 m0, s59, 0xffffff80
	s_nop 0
	global_load_lds_dwordx4 v134, s[52:53] offset:128
	s_waitcnt vmcnt(8)
	s_waitcnt lgkmcnt(0)
	s_setprio 1
	s_barrier
	v_mfma_f32_16x16x32_bf16 v[64:67], v[154:157], v[186:189], v[64:67]
	v_mfma_f32_16x16x32_bf16 v[60:63], v[162:165], v[186:189], v[60:63]
	s_add_i32 s70, s70, 2
	v_mfma_f32_16x16x32_bf16 v[56:59], v[154:157], v[194:197], v[56:59]
	s_add_u32 s42, s42, 0x100
	v_mfma_f32_16x16x32_bf16 v[52:55], v[162:165], v[194:197], v[52:55]
	s_addc_u32 s43, s43, 0
	v_mfma_f32_16x16x32_bf16 v[40:43], v[154:157], v[202:205], v[40:43]
	s_add_u32 s31, s31, 0x100
	v_mfma_f32_16x16x32_bf16 v[36:39], v[162:165], v[202:205], v[36:39]
	s_addc_u32 s41, s41, 0
	v_mfma_f32_16x16x32_bf16 v[24:27], v[154:157], v[210:213], v[24:27]
	s_add_u32 s0, s42, 0xfff00080
	v_mfma_f32_16x16x32_bf16 v[20:23], v[162:165], v[210:213], v[20:23]
	s_addc_u32 s50, s43, -1
	v_mfma_f32_16x16x32_bf16 v[64:67], v[158:161], v[190:193], v[64:67]
	s_cmp_eq_u32 s70, 12
	v_mfma_f32_16x16x32_bf16 v[60:63], v[166:169], v[190:193], v[60:63]
	s_cselect_b32 s53, s29, s50
	v_mfma_f32_16x16x32_bf16 v[56:59], v[158:161], v[198:201], v[56:59]
	s_cselect_b32 s52, s28, s0
	v_mfma_f32_16x16x32_bf16 v[52:55], v[166:169], v[198:201], v[52:55]
	s_cselect_b32 s51, s5, s41
	v_mfma_f32_16x16x32_bf16 v[40:43], v[158:161], v[206:209], v[40:43]
	s_cselect_b32 s50, s4, s31
	v_mfma_f32_16x16x32_bf16 v[36:39], v[166:169], v[206:209], v[36:39]
	s_add_i32 m0, s17, 0xc000
	v_mfma_f32_16x16x32_bf16 v[24:27], v[158:161], v[214:217], v[24:27]
	s_cmp_gt_u32 s70, 13
	v_mfma_f32_16x16x32_bf16 v[20:23], v[166:169], v[214:217], v[20:23]
	s_setprio 0
	s_setprio 1
	v_mfma_f32_16x16x32_bf16 v[48:51], v[170:173], v[186:189], v[48:51]
	v_mfma_f32_16x16x32_bf16 v[44:47], v[178:181], v[186:189], v[44:47]
	v_mfma_f32_16x16x32_bf16 v[32:35], v[170:173], v[194:197], v[32:35]
	v_mfma_f32_16x16x32_bf16 v[28:31], v[178:181], v[194:197], v[28:31]
	v_mfma_f32_16x16x32_bf16 v[16:19], v[170:173], v[202:205], v[16:19]
	v_mfma_f32_16x16x32_bf16 v[12:15], v[178:181], v[202:205], v[12:15]
	v_mfma_f32_16x16x32_bf16 v[8:11], v[170:173], v[210:213], v[8:11]
	v_mfma_f32_16x16x32_bf16 v[4:7], v[178:181], v[210:213], v[4:7]
	v_mfma_f32_16x16x32_bf16 v[48:51], v[174:177], v[190:193], v[48:51]
	v_mfma_f32_16x16x32_bf16 v[44:47], v[182:185], v[190:193], v[44:47]
	v_mfma_f32_16x16x32_bf16 v[32:35], v[174:177], v[198:201], v[32:35]
	v_mfma_f32_16x16x32_bf16 v[28:31], v[182:185], v[198:201], v[28:31]
	v_mfma_f32_16x16x32_bf16 v[16:19], v[174:177], v[206:209], v[16:19]
	v_mfma_f32_16x16x32_bf16 v[12:15], v[182:185], v[206:209], v[12:15]
	v_mfma_f32_16x16x32_bf16 v[8:11], v[174:177], v[214:217], v[8:11]
	v_mfma_f32_16x16x32_bf16 v[4:7], v[182:185], v[214:217], v[4:7]
	s_setprio 0
	s_barrier
	s_cbranch_scc0 .LBB0_1288
	s_and_b64 vcc, exec, s[14:15]
	s_cbranch_vccz .LBB0_1291
	s_barrier

.LBB0_1414:
	s_ashr_i32 s25, s24, 31
	s_lshl_b64 s[26:27], s[24:25], 18
	s_add_u32 s26, s1, s26
	s_addc_u32 s27, s18, s27
	s_and_b64 s[28:29], s[4:5], exec
	s_cselect_b32 s25, s27, s43
	s_cselect_b32 s31, s26, s42
	s_ashr_i32 s23, s22, 31
	s_lshl_b64 s[28:29], s[22:23], 18
	s_add_u32 s28, s19, s28
	s_addc_u32 s29, s35, s29
	s_and_b64 s[52:53], s[4:5], exec
	s_cselect_b32 s23, s29, s51
	s_cselect_b32 s61, s28, s50
	s_add_u32 s42, s42, 0x20080
	s_addc_u32 s43, s43, 0
	s_add_u32 s62, s50, 0x100
	v_mov_b32_e32 v4, 0
	s_addc_u32 s63, s51, 0
	s_mov_b32 s64, -2
	s_waitcnt lgkmcnt(0)
	v_mov_b32_e32 v5, 0
	v_mov_b64_e32 v[6:7], 0
	v_mov_b64_e32 v[8:9], 0
	v_mov_b64_e32 v[10:11], 0
	v_mov_b64_e32 v[20:21], 0
	v_mov_b64_e32 v[22:23], 0
	v_mov_b64_e32 v[24:25], 0
	v_mov_b64_e32 v[26:27], 0
	v_mov_b64_e32 v[36:37], 0
	v_mov_b64_e32 v[38:39], 0
	v_mov_b64_e32 v[40:41], 0
	v_mov_b64_e32 v[42:43], 0
	v_mov_b64_e32 v[52:53], 0
	v_mov_b64_e32 v[54:55], 0
	v_mov_b64_e32 v[56:57], 0
	v_mov_b64_e32 v[58:59], 0
	v_mov_b64_e32 v[12:13], 0
	v_mov_b64_e32 v[14:15], 0
	v_mov_b64_e32 v[16:17], 0
	v_mov_b64_e32 v[18:19], 0
	v_mov_b64_e32 v[28:29], 0
	v_mov_b64_e32 v[30:31], 0
	v_mov_b64_e32 v[32:33], 0
	v_mov_b64_e32 v[34:35], 0
	v_mov_b64_e32 v[44:45], 0
	v_mov_b64_e32 v[46:47], 0
	v_mov_b64_e32 v[48:49], 0
	v_mov_b64_e32 v[50:51], 0
	v_mov_b64_e32 v[60:61], 0
	v_mov_b64_e32 v[62:63], 0
	v_mov_b64_e32 v[64:65], 0
	v_mov_b64_e32 v[66:67], 0
	v_mov_b64_e32 v[68:69], 0
	v_mov_b64_e32 v[70:71], 0
	v_mov_b64_e32 v[72:73], 0
	v_mov_b64_e32 v[74:75], 0
	v_mov_b64_e32 v[84:85], 0
	v_mov_b64_e32 v[86:87], 0
	v_mov_b64_e32 v[88:89], 0
	v_mov_b64_e32 v[90:91], 0
	v_mov_b64_e32 v[100:101], 0
	v_mov_b64_e32 v[102:103], 0
	v_mov_b64_e32 v[104:105], 0
	v_mov_b64_e32 v[106:107], 0
	v_mov_b64_e32 v[116:117], 0
	v_mov_b64_e32 v[118:119], 0
	v_mov_b64_e32 v[120:121], 0
	v_mov_b64_e32 v[122:123], 0
	v_mov_b64_e32 v[76:77], 0
	v_mov_b64_e32 v[78:79], 0
	v_mov_b64_e32 v[80:81], 0
	v_mov_b64_e32 v[82:83], 0
	v_mov_b64_e32 v[92:93], 0
	v_mov_b64_e32 v[94:95], 0
	v_mov_b64_e32 v[96:97], 0
	v_mov_b64_e32 v[98:99], 0
	v_mov_b64_e32 v[108:109], 0
	v_mov_b64_e32 v[110:111], 0
	v_mov_b64_e32 v[112:113], 0
	v_mov_b64_e32 v[114:115], 0
	v_mov_b64_e32 v[124:125], 0
	v_mov_b64_e32 v[126:127], 0
	v_mov_b64_e32 v[128:129], 0
	v_mov_b64_e32 v[130:131], 0
	s_add_u32 s0, s42, 0xfffe0080
	s_addc_u32 s50, s43, -1
	s_cmp_eq_u32 s64, 4
	s_cselect_b32 s53, s25, s50
	s_cselect_b32 s52, s31, s0
	s_cselect_b32 s51, s23, s63
	s_cselect_b32 s50, s61, s62
	s_add_i32 m0, s41, 0xc000
.LBB0_1415:
	ds_read_b128 v[132:135], v187
	ds_read_b128 v[136:139], v187 offset:1024
	ds_read_b128 v[140:143], v187 offset:2048
	ds_read_b128 v[144:147], v187 offset:3072
	ds_read_b128 v[148:151], v188
	ds_read_b128 v[152:155], v188 offset:1024
	ds_read_b128 v[172:175], v188 offset:2048
	ds_read_b128 v[176:179], v188 offset:3072
	ds_read_b128 v[180:183], v189
	ds_read_b128 v[192:195], v189 offset:1024
	ds_read_b128 v[196:199], v189 offset:2048
	ds_read_b128 v[200:203], v189 offset:3072
	ds_read_b128 v[204:207], v189 offset:4096
	ds_read_b128 v[208:211], v189 offset:5120
	ds_read_b128 v[212:215], v189 offset:6144
	ds_read_b128 v[216:219], v189 offset:7168
	global_load_lds_dwordx4 v164, s[42:43]
	s_add_i32 m0, s41, 0xe000
	s_nop 0
	global_load_lds_dwordx4 v166, s[42:43]
	s_waitcnt vmcnt(8)
	s_waitcnt lgkmcnt(0)
	s_setprio 1
	s_barrier
	v_mfma_f32_16x16x32_bf16 v[128:131], v[132:135], v[180:183], v[128:131]
	v_mfma_f32_16x16x32_bf16 v[124:127], v[140:143], v[180:183], v[124:127]
	v_mfma_f32_16x16x32_bf16 v[112:115], v[132:135], v[196:199], v[112:115]
	v_mfma_f32_16x16x32_bf16 v[108:111], v[140:143], v[196:199], v[108:111]
	v_mfma_f32_16x16x32_bf16 v[96:99], v[132:135], v[204:207], v[96:99]
	v_mfma_f32_16x16x32_bf16 v[92:95], v[140:143], v[204:207], v[92:95]
	v_mfma_f32_16x16x32_bf16 v[80:83], v[132:135], v[212:215], v[80:83]
	v_mfma_f32_16x16x32_bf16 v[76:79], v[140:143], v[212:215], v[76:79]
	v_mfma_f32_16x16x32_bf16 v[128:131], v[136:139], v[192:195], v[128:131]
	v_mfma_f32_16x16x32_bf16 v[124:127], v[144:147], v[192:195], v[124:127]
	v_mfma_f32_16x16x32_bf16 v[112:115], v[136:139], v[200:203], v[112:115]
	v_mfma_f32_16x16x32_bf16 v[108:111], v[144:147], v[200:203], v[108:111]
	v_mfma_f32_16x16x32_bf16 v[96:99], v[136:139], v[208:211], v[96:99]
	v_mfma_f32_16x16x32_bf16 v[92:95], v[144:147], v[208:211], v[92:95]
	v_mfma_f32_16x16x32_bf16 v[80:83], v[136:139], v[216:219], v[80:83]
	v_mfma_f32_16x16x32_bf16 v[76:79], v[144:147], v[216:219], v[76:79]
	s_setprio 0
	s_setprio 1
	v_mfma_f32_16x16x32_bf16 v[120:123], v[148:151], v[180:183], v[120:123]
	v_mfma_f32_16x16x32_bf16 v[116:119], v[172:175], v[180:183], v[116:119]
	v_mfma_f32_16x16x32_bf16 v[104:107], v[148:151], v[196:199], v[104:107]
	v_mfma_f32_16x16x32_bf16 v[100:103], v[172:175], v[196:199], v[100:103]
	v_mfma_f32_16x16x32_bf16 v[88:91], v[148:151], v[204:207], v[88:91]
	v_mfma_f32_16x16x32_bf16 v[84:87], v[172:175], v[204:207], v[84:87]
	v_mfma_f32_16x16x32_bf16 v[72:75], v[148:151], v[212:215], v[72:75]
	v_mfma_f32_16x16x32_bf16 v[68:71], v[172:175], v[212:215], v[68:71]
	v_mfma_f32_16x16x32_bf16 v[120:123], v[152:155], v[192:195], v[120:123]
	v_mfma_f32_16x16x32_bf16 v[116:119], v[176:179], v[192:195], v[116:119]
	v_mfma_f32_16x16x32_bf16 v[104:107], v[152:155], v[200:203], v[104:107]
	v_mfma_f32_16x16x32_bf16 v[100:103], v[176:179], v[200:203], v[100:103]
	v_mfma_f32_16x16x32_bf16 v[88:91], v[152:155], v[208:211], v[88:91]
	v_mfma_f32_16x16x32_bf16 v[84:87], v[176:179], v[208:211], v[84:87]
	v_mfma_f32_16x16x32_bf16 v[72:75], v[152:155], v[216:219], v[72:75]
	v_mfma_f32_16x16x32_bf16 v[68:71], v[176:179], v[216:219], v[68:71]
	s_setprio 0
	s_barrier
	s_add_i32 s0, s58, s45
	s_mov_b32 m0, s0
	ds_read_b128 v[180:183], v189 offset:16384
	ds_read_b128 v[192:195], v189 offset:17408
	ds_read_b128 v[196:199], v189 offset:18432
	ds_read_b128 v[200:203], v189 offset:19456
	ds_read_b128 v[204:207], v189 offset:20480
	ds_read_b128 v[208:211], v189 offset:21504
	ds_read_b128 v[212:215], v189 offset:22528
	ds_read_b128 v[216:219], v189 offset:23552
	global_load_lds_dwordx4 v158, s[50:51]
	s_add_i32 m0, s0, 0x2000
	s_add_u32 s66, s50, 0x20000
	s_addc_u32 s67, s51, 0
	s_add_i32 s0, s59, s45
	global_load_lds_dwordx4 v162, s[50:51]
	s_mov_b32 m0, s0
	s_nop 0
	global_load_lds_dwordx4 v158, s[66:67]
	s_add_i32 m0, s0, 0x2000
	s_nop 0
	global_load_lds_dwordx4 v162, s[66:67]
	s_mov_b32 m0, s41
	s_nop 0
	global_load_lds_dwordx4 v156, s[52:53]
	s_mov_b32 m0, s46
	s_nop 0
	global_load_lds_dwordx4 v160, s[52:53]
	s_waitcnt vmcnt(8)
	s_waitcnt lgkmcnt(0)
	s_setprio 1
	s_barrier
	v_mfma_f32_16x16x32_bf16 v[64:67], v[132:135], v[180:183], v[64:67]
	v_mfma_f32_16x16x32_bf16 v[60:63], v[140:143], v[180:183], v[60:63]
	v_mfma_f32_16x16x32_bf16 v[48:51], v[132:135], v[196:199], v[48:51]
	v_mfma_f32_16x16x32_bf16 v[44:47], v[140:143], v[196:199], v[44:47]
	v_mfma_f32_16x16x32_bf16 v[32:35], v[132:135], v[204:207], v[32:35]
	v_mfma_f32_16x16x32_bf16 v[28:31], v[140:143], v[204:207], v[28:31]
	v_mfma_f32_16x16x32_bf16 v[16:19], v[132:135], v[212:215], v[16:19]
	v_mfma_f32_16x16x32_bf16 v[12:15], v[140:143], v[212:215], v[12:15]
	v_mfma_f32_16x16x32_bf16 v[64:67], v[136:139], v[192:195], v[64:67]
	v_mfma_f32_16x16x32_bf16 v[60:63], v[144:147], v[192:195], v[60:63]
	v_mfma_f32_16x16x32_bf16 v[48:51], v[136:139], v[200:203], v[48:51]
	v_mfma_f32_16x16x32_bf16 v[44:47], v[144:147], v[200:203], v[44:47]
	v_mfma_f32_16x16x32_bf16 v[32:35], v[136:139], v[208:211], v[32:35]
	v_mfma_f32_16x16x32_bf16 v[28:31], v[144:147], v[208:211], v[28:31]
	v_mfma_f32_16x16x32_bf16 v[16:19], v[136:139], v[216:219], v[16:19]
	v_mfma_f32_16x16x32_bf16 v[12:15], v[144:147], v[216:219], v[12:15]
	s_setprio 0
	s_setprio 1
	v_mfma_f32_16x16x32_bf16 v[56:59], v[148:151], v[180:183], v[56:59]
	v_mfma_f32_16x16x32_bf16 v[52:55], v[172:175], v[180:183], v[52:55]
	v_mfma_f32_16x16x32_bf16 v[40:43], v[148:151], v[196:199], v[40:43]
	v_mfma_f32_16x16x32_bf16 v[36:39], v[172:175], v[196:199], v[36:39]
	v_mfma_f32_16x16x32_bf16 v[24:27], v[148:151], v[204:207], v[24:27]
	v_mfma_f32_16x16x32_bf16 v[20:23], v[172:175], v[204:207], v[20:23]
	v_mfma_f32_16x16x32_bf16 v[8:11], v[148:151], v[212:215], v[8:11]
	v_mfma_f32_16x16x32_bf16 v[4:7], v[172:175], v[212:215], v[4:7]
	v_mfma_f32_16x16x32_bf16 v[56:59], v[152:155], v[192:195], v[56:59]
	v_mfma_f32_16x16x32_bf16 v[52:55], v[176:179], v[192:195], v[52:55]
	v_mfma_f32_16x16x32_bf16 v[40:43], v[152:155], v[200:203], v[40:43]
	v_mfma_f32_16x16x32_bf16 v[36:39], v[176:179], v[200:203], v[36:39]
	v_mfma_f32_16x16x32_bf16 v[24:27], v[152:155], v[208:211], v[24:27]
	v_mfma_f32_16x16x32_bf16 v[20:23], v[176:179], v[208:211], v[20:23]
	v_mfma_f32_16x16x32_bf16 v[8:11], v[152:155], v[216:219], v[8:11]
	v_mfma_f32_16x16x32_bf16 v[4:7], v[176:179], v[216:219], v[4:7]
	s_setprio 0
	s_barrier
	s_add_i32 s0, 0, 0x18000
	s_add_i32 s65, 0, 0x1c000
	v_add_u32_e32 v144, s0, v3
	v_add_u32_e32 v176, s65, v3
	ds_read_b128 v[132:135], v144
	ds_read_b128 v[136:139], v144 offset:1024
	ds_read_b128 v[140:143], v144 offset:2048
	ds_read_b128 v[144:147], v144 offset:3072
	ds_read_b128 v[148:151], v176
	ds_read_b128 v[152:155], v176 offset:1024
	ds_read_b128 v[172:175], v176 offset:2048
	ds_read_b128 v[176:179], v176 offset:3072
	s_add_u32 s98, s52, 0x20000
	s_addc_u32 s99, s53, 0
	s_mov_b32 m0, s47
	ds_read_b128 v[180:183], v189 offset:32768
	ds_read_b128 v[192:195], v189 offset:33792
	ds_read_b128 v[196:199], v189 offset:34816
	ds_read_b128 v[200:203], v189 offset:35840
	ds_read_b128 v[204:207], v189 offset:36864
	ds_read_b128 v[208:211], v189 offset:37888
	ds_read_b128 v[212:215], v189 offset:38912
	ds_read_b128 v[216:219], v189 offset:39936
	global_load_lds_dwordx4 v156, s[98:99]
	s_mov_b32 m0, s48
	s_nop 0
	global_load_lds_dwordx4 v160, s[98:99]
	s_waitcnt vmcnt(8)
	s_waitcnt lgkmcnt(0)
	s_setprio 1
	s_barrier
	v_mfma_f32_16x16x32_bf16 v[128:131], v[132:135], v[180:183], v[128:131]
	v_mfma_f32_16x16x32_bf16 v[124:127], v[140:143], v[180:183], v[124:127]
	v_mfma_f32_16x16x32_bf16 v[112:115], v[132:135], v[196:199], v[112:115]
	v_mfma_f32_16x16x32_bf16 v[108:111], v[140:143], v[196:199], v[108:111]
	v_mfma_f32_16x16x32_bf16 v[96:99], v[132:135], v[204:207], v[96:99]
	v_mfma_f32_16x16x32_bf16 v[92:95], v[140:143], v[204:207], v[92:95]
	v_mfma_f32_16x16x32_bf16 v[80:83], v[132:135], v[212:215], v[80:83]
	v_mfma_f32_16x16x32_bf16 v[76:79], v[140:143], v[212:215], v[76:79]
	v_mfma_f32_16x16x32_bf16 v[128:131], v[136:139], v[192:195], v[128:131]
	v_mfma_f32_16x16x32_bf16 v[124:127], v[144:147], v[192:195], v[124:127]
	v_mfma_f32_16x16x32_bf16 v[112:115], v[136:139], v[200:203], v[112:115]
	v_mfma_f32_16x16x32_bf16 v[108:111], v[144:147], v[200:203], v[108:111]
	v_mfma_f32_16x16x32_bf16 v[96:99], v[136:139], v[208:211], v[96:99]
	v_mfma_f32_16x16x32_bf16 v[92:95], v[144:147], v[208:211], v[92:95]
	v_mfma_f32_16x16x32_bf16 v[80:83], v[136:139], v[216:219], v[80:83]
	v_mfma_f32_16x16x32_bf16 v[76:79], v[144:147], v[216:219], v[76:79]
	s_setprio 0
	s_setprio 1
	v_mfma_f32_16x16x32_bf16 v[120:123], v[148:151], v[180:183], v[120:123]
	v_mfma_f32_16x16x32_bf16 v[116:119], v[172:175], v[180:183], v[116:119]
	v_mfma_f32_16x16x32_bf16 v[104:107], v[148:151], v[196:199], v[104:107]
	v_mfma_f32_16x16x32_bf16 v[100:103], v[172:175], v[196:199], v[100:103]
	v_mfma_f32_16x16x32_bf16 v[88:91], v[148:151], v[204:207], v[88:91]
	v_mfma_f32_16x16x32_bf16 v[84:87], v[172:175], v[204:207], v[84:87]
	v_mfma_f32_16x16x32_bf16 v[72:75], v[148:151], v[212:215], v[72:75]
	v_mfma_f32_16x16x32_bf16 v[68:71], v[172:175], v[212:215], v[68:71]
	v_mfma_f32_16x16x32_bf16 v[120:123], v[152:155], v[192:195], v[120:123]
	v_mfma_f32_16x16x32_bf16 v[116:119], v[176:179], v[192:195], v[116:119]
	v_mfma_f32_16x16x32_bf16 v[104:107], v[152:155], v[200:203], v[104:107]
	v_mfma_f32_16x16x32_bf16 v[100:103], v[176:179], v[200:203], v[100:103]
	v_mfma_f32_16x16x32_bf16 v[88:91], v[152:155], v[208:211], v[88:91]
	v_mfma_f32_16x16x32_bf16 v[84:87], v[176:179], v[208:211], v[84:87]
	v_mfma_f32_16x16x32_bf16 v[72:75], v[152:155], v[216:219], v[72:75]
	v_mfma_f32_16x16x32_bf16 v[68:71], v[176:179], v[216:219], v[68:71]
	s_setprio 0
	s_barrier
	s_add_i32 s0, s0, s45
	s_add_i32 m0, s0, 0xffffff80
	ds_read_b128 v[180:183], v189 offset:49152
	ds_read_b128 v[192:195], v189 offset:50176
	ds_read_b128 v[196:199], v189 offset:51200
	ds_read_b128 v[200:203], v189 offset:52224
	ds_read_b128 v[204:207], v189 offset:53248
	ds_read_b128 v[208:211], v189 offset:54272
	ds_read_b128 v[212:215], v189 offset:55296
	ds_read_b128 v[216:219], v189 offset:56320
	global_load_lds_dwordx4 v158, s[50:51] offset:128
	s_add_i32 m0, s0, 0x1f80
	s_add_i32 s0, s65, s45
	global_load_lds_dwordx4 v162, s[50:51] offset:128
	s_add_u32 s50, s50, 0x20080
	s_addc_u32 s51, s51, 0
	s_mov_b32 m0, s0
	s_nop 0
	global_load_lds_dwordx4 v158, s[50:51]
	s_add_i32 m0, s0, 0x2000
	s_nop 0
	global_load_lds_dwordx4 v162, s[50:51]
	s_add_i32 m0, s56, 0xffffff80
	s_nop 0
	global_load_lds_dwordx4 v156, s[52:53] offset:128
	s_add_i32 m0, s57, 0xffffff80
	s_nop 0
	global_load_lds_dwordx4 v160, s[52:53] offset:128
	s_waitcnt vmcnt(8)
	s_waitcnt lgkmcnt(0)
	s_setprio 1
	s_barrier
	v_mfma_f32_16x16x32_bf16 v[64:67], v[132:135], v[180:183], v[64:67]
	v_mfma_f32_16x16x32_bf16 v[60:63], v[140:143], v[180:183], v[60:63]
	s_add_i32 s64, s64, 2
	v_mfma_f32_16x16x32_bf16 v[48:51], v[132:135], v[196:199], v[48:51]
	s_add_u32 s42, s42, 0x100
	v_mfma_f32_16x16x32_bf16 v[44:47], v[140:143], v[196:199], v[44:47]
	s_addc_u32 s43, s43, 0
	v_mfma_f32_16x16x32_bf16 v[32:35], v[132:135], v[204:207], v[32:35]
	s_add_u32 s62, s62, 0x100
	v_mfma_f32_16x16x32_bf16 v[28:31], v[140:143], v[204:207], v[28:31]
	s_addc_u32 s63, s63, 0
	v_mfma_f32_16x16x32_bf16 v[16:19], v[132:135], v[212:215], v[16:19]
	s_add_u32 s0, s42, 0xfffe0080
	v_mfma_f32_16x16x32_bf16 v[12:15], v[140:143], v[212:215], v[12:15]
	s_addc_u32 s50, s43, -1
	v_mfma_f32_16x16x32_bf16 v[64:67], v[136:139], v[192:195], v[64:67]
	s_cmp_eq_u32 s64, 4
	v_mfma_f32_16x16x32_bf16 v[60:63], v[144:147], v[192:195], v[60:63]
	s_cselect_b32 s53, s25, s50
	v_mfma_f32_16x16x32_bf16 v[48:51], v[136:139], v[200:203], v[48:51]
	s_cselect_b32 s52, s31, s0
	v_mfma_f32_16x16x32_bf16 v[44:47], v[144:147], v[200:203], v[44:47]
	s_cselect_b32 s51, s23, s63
	v_mfma_f32_16x16x32_bf16 v[32:35], v[136:139], v[208:211], v[32:35]
	s_cselect_b32 s50, s61, s62
	v_mfma_f32_16x16x32_bf16 v[28:31], v[144:147], v[208:211], v[28:31]
	s_add_i32 m0, s41, 0xc000
	v_mfma_f32_16x16x32_bf16 v[16:19], v[136:139], v[216:219], v[16:19]
	s_cmp_gt_u32 s64, 5
	v_mfma_f32_16x16x32_bf16 v[12:15], v[144:147], v[216:219], v[12:15]
	s_setprio 0
	s_setprio 1
	v_mfma_f32_16x16x32_bf16 v[56:59], v[148:151], v[180:183], v[56:59]
	v_mfma_f32_16x16x32_bf16 v[52:55], v[172:175], v[180:183], v[52:55]
	v_mfma_f32_16x16x32_bf16 v[40:43], v[148:151], v[196:199], v[40:43]
	v_mfma_f32_16x16x32_bf16 v[36:39], v[172:175], v[196:199], v[36:39]
	v_mfma_f32_16x16x32_bf16 v[24:27], v[148:151], v[204:207], v[24:27]
	v_mfma_f32_16x16x32_bf16 v[20:23], v[172:175], v[204:207], v[20:23]
	v_mfma_f32_16x16x32_bf16 v[8:11], v[148:151], v[212:215], v[8:11]
	v_mfma_f32_16x16x32_bf16 v[4:7], v[172:175], v[212:215], v[4:7]
	v_mfma_f32_16x16x32_bf16 v[56:59], v[152:155], v[192:195], v[56:59]
	v_mfma_f32_16x16x32_bf16 v[52:55], v[176:179], v[192:195], v[52:55]
	v_mfma_f32_16x16x32_bf16 v[40:43], v[152:155], v[200:203], v[40:43]
	v_mfma_f32_16x16x32_bf16 v[36:39], v[176:179], v[200:203], v[36:39]
	v_mfma_f32_16x16x32_bf16 v[24:27], v[152:155], v[208:211], v[24:27]
	v_mfma_f32_16x16x32_bf16 v[20:23], v[176:179], v[208:211], v[20:23]
	v_mfma_f32_16x16x32_bf16 v[8:11], v[152:155], v[216:219], v[8:11]
	v_mfma_f32_16x16x32_bf16 v[4:7], v[176:179], v[216:219], v[4:7]
	s_setprio 0
	s_barrier
	s_cbranch_scc0 .LBB0_1415
	s_and_b64 vcc, exec, s[16:17]
	s_cbranch_vccz .LBB0_1418
	s_barrier

.LBB0_1502:
	s_ashr_i32 s31, s30, 31
	s_lshl_b64 s[40:41], s[30:31], 21
	s_add_u32 s40, s19, s40
	s_addc_u32 s41, s35, s41
	s_and_b64 s[42:43], exec, s[6:7]
	s_cselect_b32 s31, s55, s41
	s_cselect_b32 s71, s54, s40
	s_ashr_i32 s29, s28, 31
	s_lshl_b64 s[42:43], s[28:29], 21
	s_add_u32 s42, s45, s42
	s_addc_u32 s43, s46, s43
	s_and_b64 s[58:59], exec, s[6:7]
	s_cselect_b32 s29, s57, s43
	s_cselect_b32 s72, s56, s42
	s_add_u32 s54, s54, 0x100080
	s_addc_u32 s55, s55, 0
	s_add_u32 s73, s56, 0x100
	v_mov_b32_e32 v8, 0
	s_addc_u32 s74, s57, 0
	s_mov_b32 s75, -2
	v_mov_b32_e32 v9, 0
	v_mov_b64_e32 v[10:11], 0
	v_mov_b64_e32 v[12:13], 0
	v_mov_b64_e32 v[14:15], 0
	v_mov_b64_e32 v[24:25], 0
	v_mov_b64_e32 v[26:27], 0
	v_mov_b64_e32 v[28:29], 0
	v_mov_b64_e32 v[30:31], 0
	v_mov_b64_e32 v[40:41], 0
	v_mov_b64_e32 v[42:43], 0
	v_mov_b64_e32 v[44:45], 0
	v_mov_b64_e32 v[46:47], 0
	v_mov_b64_e32 v[56:57], 0
	v_mov_b64_e32 v[58:59], 0
	v_mov_b64_e32 v[60:61], 0
	v_mov_b64_e32 v[62:63], 0
	v_mov_b64_e32 v[16:17], 0
	v_mov_b64_e32 v[18:19], 0
	v_mov_b64_e32 v[20:21], 0
	v_mov_b64_e32 v[22:23], 0
	v_mov_b64_e32 v[32:33], 0
	v_mov_b64_e32 v[34:35], 0
	v_mov_b64_e32 v[36:37], 0
	v_mov_b64_e32 v[38:39], 0
	v_mov_b64_e32 v[48:49], 0
	v_mov_b64_e32 v[50:51], 0
	v_mov_b64_e32 v[52:53], 0
	v_mov_b64_e32 v[54:55], 0
	v_mov_b64_e32 v[64:65], 0
	v_mov_b64_e32 v[66:67], 0
	v_mov_b64_e32 v[68:69], 0
	v_mov_b64_e32 v[70:71], 0
	v_mov_b64_e32 v[72:73], 0
	v_mov_b64_e32 v[74:75], 0
	v_mov_b64_e32 v[76:77], 0
	v_mov_b64_e32 v[78:79], 0
	v_mov_b64_e32 v[88:89], 0
	v_mov_b64_e32 v[90:91], 0
	v_mov_b64_e32 v[92:93], 0
	v_mov_b64_e32 v[94:95], 0
	v_mov_b64_e32 v[104:105], 0
	v_mov_b64_e32 v[106:107], 0
	v_mov_b64_e32 v[108:109], 0
	v_mov_b64_e32 v[110:111], 0
	v_mov_b64_e32 v[120:121], 0
	v_mov_b64_e32 v[122:123], 0
	v_mov_b64_e32 v[124:125], 0
	v_mov_b64_e32 v[126:127], 0
	v_mov_b64_e32 v[80:81], 0
	v_mov_b64_e32 v[82:83], 0
	v_mov_b64_e32 v[84:85], 0
	v_mov_b64_e32 v[86:87], 0
	v_mov_b64_e32 v[96:97], 0
	v_mov_b64_e32 v[98:99], 0
	v_mov_b64_e32 v[100:101], 0
	v_mov_b64_e32 v[102:103], 0
	v_mov_b64_e32 v[112:113], 0
	v_mov_b64_e32 v[114:115], 0
	v_mov_b64_e32 v[116:117], 0
	v_mov_b64_e32 v[118:119], 0
	v_mov_b64_e32 v[128:129], 0
	v_mov_b64_e32 v[130:131], 0
	v_mov_b64_e32 v[136:137], 0
	v_mov_b64_e32 v[138:139], 0
	s_add_u32 s0, s54, 0xfff00080
	s_addc_u32 s56, s55, -1
	s_cmp_eq_u32 s75, 60
	s_cselect_b32 s59, s31, s56
	s_cselect_b32 s58, s71, s0
	s_cselect_b32 s57, s29, s74
	s_cselect_b32 s56, s72, s73
	s_add_i32 m0, s48, 0xc000
.LBB0_1503:
	ds_read_b128 v[132:135], v159
	ds_read_b128 v[164:167], v159 offset:1024
	ds_read_b128 v[168:171], v159 offset:2048
	ds_read_b128 v[172:175], v159 offset:3072
	ds_read_b128 v[176:179], v160
	ds_read_b128 v[180:183], v160 offset:1024
	ds_read_b128 v[184:187], v160 offset:2048
	ds_read_b128 v[188:191], v160 offset:3072
	ds_read_b128 v[192:195], v161
	ds_read_b128 v[196:199], v161 offset:1024
	ds_read_b128 v[200:203], v161 offset:2048
	ds_read_b128 v[204:207], v161 offset:3072
	ds_read_b128 v[208:211], v161 offset:4096
	ds_read_b128 v[212:215], v161 offset:5120
	ds_read_b128 v[216:219], v161 offset:6144
	ds_read_b128 v[220:223], v161 offset:7168
	global_load_lds_dwordx4 v148, s[54:55]
	s_add_i32 m0, s48, 0xe000
	s_nop 0
	global_load_lds_dwordx4 v150, s[54:55]
	s_waitcnt vmcnt(8)
	s_waitcnt lgkmcnt(0)
	s_setprio 1
	s_barrier
	v_mfma_f32_16x16x32_bf16 v[136:139], v[132:135], v[192:195], v[136:139]
	v_mfma_f32_16x16x32_bf16 v[128:131], v[168:171], v[192:195], v[128:131]
	v_mfma_f32_16x16x32_bf16 v[116:119], v[132:135], v[200:203], v[116:119]
	v_mfma_f32_16x16x32_bf16 v[112:115], v[168:171], v[200:203], v[112:115]
	v_mfma_f32_16x16x32_bf16 v[100:103], v[132:135], v[208:211], v[100:103]
	v_mfma_f32_16x16x32_bf16 v[96:99], v[168:171], v[208:211], v[96:99]
	v_mfma_f32_16x16x32_bf16 v[84:87], v[132:135], v[216:219], v[84:87]
	v_mfma_f32_16x16x32_bf16 v[80:83], v[168:171], v[216:219], v[80:83]
	v_mfma_f32_16x16x32_bf16 v[136:139], v[164:167], v[196:199], v[136:139]
	v_mfma_f32_16x16x32_bf16 v[128:131], v[172:175], v[196:199], v[128:131]
	v_mfma_f32_16x16x32_bf16 v[116:119], v[164:167], v[204:207], v[116:119]
	v_mfma_f32_16x16x32_bf16 v[112:115], v[172:175], v[204:207], v[112:115]
	v_mfma_f32_16x16x32_bf16 v[100:103], v[164:167], v[212:215], v[100:103]
	v_mfma_f32_16x16x32_bf16 v[96:99], v[172:175], v[212:215], v[96:99]
	v_mfma_f32_16x16x32_bf16 v[84:87], v[164:167], v[220:223], v[84:87]
	v_mfma_f32_16x16x32_bf16 v[80:83], v[172:175], v[220:223], v[80:83]
	s_setprio 0
	s_setprio 1
	v_mfma_f32_16x16x32_bf16 v[124:127], v[176:179], v[192:195], v[124:127]
	v_mfma_f32_16x16x32_bf16 v[120:123], v[184:187], v[192:195], v[120:123]
	v_mfma_f32_16x16x32_bf16 v[108:111], v[176:179], v[200:203], v[108:111]
	v_mfma_f32_16x16x32_bf16 v[104:107], v[184:187], v[200:203], v[104:107]
	v_mfma_f32_16x16x32_bf16 v[92:95], v[176:179], v[208:211], v[92:95]
	v_mfma_f32_16x16x32_bf16 v[88:91], v[184:187], v[208:211], v[88:91]
	v_mfma_f32_16x16x32_bf16 v[76:79], v[176:179], v[216:219], v[76:79]
	v_mfma_f32_16x16x32_bf16 v[72:75], v[184:187], v[216:219], v[72:75]
	v_mfma_f32_16x16x32_bf16 v[124:127], v[180:183], v[196:199], v[124:127]
	v_mfma_f32_16x16x32_bf16 v[120:123], v[188:191], v[196:199], v[120:123]
	v_mfma_f32_16x16x32_bf16 v[108:111], v[180:183], v[204:207], v[108:111]
	v_mfma_f32_16x16x32_bf16 v[104:107], v[188:191], v[204:207], v[104:107]
	v_mfma_f32_16x16x32_bf16 v[92:95], v[180:183], v[212:215], v[92:95]
	v_mfma_f32_16x16x32_bf16 v[88:91], v[188:191], v[212:215], v[88:91]
	v_mfma_f32_16x16x32_bf16 v[76:79], v[180:183], v[220:223], v[76:79]
	v_mfma_f32_16x16x32_bf16 v[72:75], v[188:191], v[220:223], v[72:75]
	s_setprio 0
	s_barrier
	s_add_i32 s0, s65, s47
	s_mov_b32 m0, s0
	ds_read_b128 v[192:195], v161 offset:16384
	ds_read_b128 v[196:199], v161 offset:17408
	ds_read_b128 v[200:203], v161 offset:18432
	ds_read_b128 v[204:207], v161 offset:19456
	ds_read_b128 v[208:211], v161 offset:20480
	ds_read_b128 v[212:215], v161 offset:21504
	ds_read_b128 v[216:219], v161 offset:22528
	ds_read_b128 v[220:223], v161 offset:23552
	global_load_lds_dwordx4 v142, s[56:57]
	s_add_i32 m0, s0, 0x2000
	s_add_u32 s76, s56, 0x100000
	s_addc_u32 s77, s57, 0
	s_add_i32 s0, s66, s47
	global_load_lds_dwordx4 v146, s[56:57]
	s_mov_b32 m0, s0
	s_nop 0
	global_load_lds_dwordx4 v142, s[76:77]
	s_add_i32 m0, s0, 0x2000
	s_nop 0
	global_load_lds_dwordx4 v146, s[76:77]
	s_mov_b32 m0, s48
	s_nop 0
	global_load_lds_dwordx4 v140, s[58:59]
	s_mov_b32 m0, s49
	s_nop 0
	global_load_lds_dwordx4 v144, s[58:59]
	s_waitcnt vmcnt(8)
	s_waitcnt lgkmcnt(0)
	s_setprio 1
	s_barrier
	v_mfma_f32_16x16x32_bf16 v[68:71], v[132:135], v[192:195], v[68:71]
	v_mfma_f32_16x16x32_bf16 v[64:67], v[168:171], v[192:195], v[64:67]
	v_mfma_f32_16x16x32_bf16 v[52:55], v[132:135], v[200:203], v[52:55]
	v_mfma_f32_16x16x32_bf16 v[48:51], v[168:171], v[200:203], v[48:51]
	v_mfma_f32_16x16x32_bf16 v[36:39], v[132:135], v[208:211], v[36:39]
	v_mfma_f32_16x16x32_bf16 v[32:35], v[168:171], v[208:211], v[32:35]
	v_mfma_f32_16x16x32_bf16 v[20:23], v[132:135], v[216:219], v[20:23]
	v_mfma_f32_16x16x32_bf16 v[16:19], v[168:171], v[216:219], v[16:19]
	v_mfma_f32_16x16x32_bf16 v[68:71], v[164:167], v[196:199], v[68:71]
	v_mfma_f32_16x16x32_bf16 v[64:67], v[172:175], v[196:199], v[64:67]
	v_mfma_f32_16x16x32_bf16 v[52:55], v[164:167], v[204:207], v[52:55]
	v_mfma_f32_16x16x32_bf16 v[48:51], v[172:175], v[204:207], v[48:51]
	v_mfma_f32_16x16x32_bf16 v[36:39], v[164:167], v[212:215], v[36:39]
	v_mfma_f32_16x16x32_bf16 v[32:35], v[172:175], v[212:215], v[32:35]
	v_mfma_f32_16x16x32_bf16 v[20:23], v[164:167], v[220:223], v[20:23]
	v_mfma_f32_16x16x32_bf16 v[16:19], v[172:175], v[220:223], v[16:19]
	s_setprio 0
	s_setprio 1
	v_mfma_f32_16x16x32_bf16 v[60:63], v[176:179], v[192:195], v[60:63]
	v_mfma_f32_16x16x32_bf16 v[56:59], v[184:187], v[192:195], v[56:59]
	v_mfma_f32_16x16x32_bf16 v[44:47], v[176:179], v[200:203], v[44:47]
	v_mfma_f32_16x16x32_bf16 v[40:43], v[184:187], v[200:203], v[40:43]
	v_mfma_f32_16x16x32_bf16 v[28:31], v[176:179], v[208:211], v[28:31]
	v_mfma_f32_16x16x32_bf16 v[24:27], v[184:187], v[208:211], v[24:27]
	v_mfma_f32_16x16x32_bf16 v[12:15], v[176:179], v[216:219], v[12:15]
	v_mfma_f32_16x16x32_bf16 v[8:11], v[184:187], v[216:219], v[8:11]
	v_mfma_f32_16x16x32_bf16 v[60:63], v[180:183], v[196:199], v[60:63]
	v_mfma_f32_16x16x32_bf16 v[56:59], v[188:191], v[196:199], v[56:59]
	v_mfma_f32_16x16x32_bf16 v[44:47], v[180:183], v[204:207], v[44:47]
	v_mfma_f32_16x16x32_bf16 v[40:43], v[188:191], v[204:207], v[40:43]
	v_mfma_f32_16x16x32_bf16 v[28:31], v[180:183], v[212:215], v[28:31]
	v_mfma_f32_16x16x32_bf16 v[24:27], v[188:191], v[212:215], v[24:27]
	v_mfma_f32_16x16x32_bf16 v[12:15], v[180:183], v[220:223], v[12:15]
	v_mfma_f32_16x16x32_bf16 v[8:11], v[188:191], v[220:223], v[8:11]
	s_setprio 0
	s_barrier
	s_add_i32 s0, 0, 0x18000
	s_add_i32 s76, 0, 0x1c000
	v_add_u32_e32 v172, s0, v156
	v_add_u32_e32 v188, s76, v156
	ds_read_b128 v[132:135], v172
	ds_read_b128 v[164:167], v172 offset:1024
	ds_read_b128 v[168:171], v172 offset:2048
	ds_read_b128 v[172:175], v172 offset:3072
	ds_read_b128 v[176:179], v188
	ds_read_b128 v[180:183], v188 offset:1024
	ds_read_b128 v[184:187], v188 offset:2048
	ds_read_b128 v[188:191], v188 offset:3072
	s_add_u32 s98, s58, 0x100000
	s_addc_u32 s99, s59, 0
	s_mov_b32 m0, s51
	ds_read_b128 v[192:195], v161 offset:32768
	ds_read_b128 v[196:199], v161 offset:33792
	ds_read_b128 v[200:203], v161 offset:34816
	ds_read_b128 v[204:207], v161 offset:35840
	ds_read_b128 v[208:211], v161 offset:36864
	ds_read_b128 v[212:215], v161 offset:37888
	ds_read_b128 v[216:219], v161 offset:38912
	ds_read_b128 v[220:223], v161 offset:39936
	global_load_lds_dwordx4 v140, s[98:99]
	s_mov_b32 m0, s53
	s_nop 0
	global_load_lds_dwordx4 v144, s[98:99]
	s_waitcnt vmcnt(8)
	s_waitcnt lgkmcnt(0)
	s_setprio 1
	s_barrier
	v_mfma_f32_16x16x32_bf16 v[136:139], v[132:135], v[192:195], v[136:139]
	v_mfma_f32_16x16x32_bf16 v[128:131], v[168:171], v[192:195], v[128:131]
	v_mfma_f32_16x16x32_bf16 v[116:119], v[132:135], v[200:203], v[116:119]
	v_mfma_f32_16x16x32_bf16 v[112:115], v[168:171], v[200:203], v[112:115]
	v_mfma_f32_16x16x32_bf16 v[100:103], v[132:135], v[208:211], v[100:103]
	v_mfma_f32_16x16x32_bf16 v[96:99], v[168:171], v[208:211], v[96:99]
	v_mfma_f32_16x16x32_bf16 v[84:87], v[132:135], v[216:219], v[84:87]
	v_mfma_f32_16x16x32_bf16 v[80:83], v[168:171], v[216:219], v[80:83]
	v_mfma_f32_16x16x32_bf16 v[136:139], v[164:167], v[196:199], v[136:139]
	v_mfma_f32_16x16x32_bf16 v[128:131], v[172:175], v[196:199], v[128:131]
	v_mfma_f32_16x16x32_bf16 v[116:119], v[164:167], v[204:207], v[116:119]
	v_mfma_f32_16x16x32_bf16 v[112:115], v[172:175], v[204:207], v[112:115]
	v_mfma_f32_16x16x32_bf16 v[100:103], v[164:167], v[212:215], v[100:103]
	v_mfma_f32_16x16x32_bf16 v[96:99], v[172:175], v[212:215], v[96:99]
	v_mfma_f32_16x16x32_bf16 v[84:87], v[164:167], v[220:223], v[84:87]
	v_mfma_f32_16x16x32_bf16 v[80:83], v[172:175], v[220:223], v[80:83]
	s_setprio 0
	s_setprio 1
	v_mfma_f32_16x16x32_bf16 v[124:127], v[176:179], v[192:195], v[124:127]
	v_mfma_f32_16x16x32_bf16 v[120:123], v[184:187], v[192:195], v[120:123]
	v_mfma_f32_16x16x32_bf16 v[108:111], v[176:179], v[200:203], v[108:111]
	v_mfma_f32_16x16x32_bf16 v[104:107], v[184:187], v[200:203], v[104:107]
	v_mfma_f32_16x16x32_bf16 v[92:95], v[176:179], v[208:211], v[92:95]
	v_mfma_f32_16x16x32_bf16 v[88:91], v[184:187], v[208:211], v[88:91]
	v_mfma_f32_16x16x32_bf16 v[76:79], v[176:179], v[216:219], v[76:79]
	v_mfma_f32_16x16x32_bf16 v[72:75], v[184:187], v[216:219], v[72:75]
	v_mfma_f32_16x16x32_bf16 v[124:127], v[180:183], v[196:199], v[124:127]
	v_mfma_f32_16x16x32_bf16 v[120:123], v[188:191], v[196:199], v[120:123]
	v_mfma_f32_16x16x32_bf16 v[108:111], v[180:183], v[204:207], v[108:111]
	v_mfma_f32_16x16x32_bf16 v[104:107], v[188:191], v[204:207], v[104:107]
	v_mfma_f32_16x16x32_bf16 v[92:95], v[180:183], v[212:215], v[92:95]
	v_mfma_f32_16x16x32_bf16 v[88:91], v[188:191], v[212:215], v[88:91]
	v_mfma_f32_16x16x32_bf16 v[76:79], v[180:183], v[220:223], v[76:79]
	v_mfma_f32_16x16x32_bf16 v[72:75], v[188:191], v[220:223], v[72:75]
	s_setprio 0
	s_barrier
	s_add_i32 s0, s0, s47
	s_add_i32 m0, s0, 0xffffff80
	ds_read_b128 v[192:195], v161 offset:49152
	ds_read_b128 v[196:199], v161 offset:50176
	ds_read_b128 v[200:203], v161 offset:51200
	ds_read_b128 v[204:207], v161 offset:52224
	ds_read_b128 v[208:211], v161 offset:53248
	ds_read_b128 v[212:215], v161 offset:54272
	ds_read_b128 v[216:219], v161 offset:55296
	ds_read_b128 v[220:223], v161 offset:56320
	global_load_lds_dwordx4 v142, s[56:57] offset:128
	s_add_i32 m0, s0, 0x1f80
	s_add_i32 s0, s76, s47
	global_load_lds_dwordx4 v146, s[56:57] offset:128
	s_add_u32 s56, s56, 0x100080
	s_addc_u32 s57, s57, 0
	s_mov_b32 m0, s0
	s_nop 0
	global_load_lds_dwordx4 v142, s[56:57]
	s_add_i32 m0, s0, 0x2000
	s_nop 0
	global_load_lds_dwordx4 v146, s[56:57]
	s_add_i32 m0, s62, 0xffffff80
	s_nop 0
	global_load_lds_dwordx4 v140, s[58:59] offset:128
	s_add_i32 m0, s63, 0xffffff80
	s_nop 0
	global_load_lds_dwordx4 v144, s[58:59] offset:128
	s_waitcnt vmcnt(8)
	s_waitcnt lgkmcnt(0)
	s_setprio 1
	s_barrier
	v_mfma_f32_16x16x32_bf16 v[68:71], v[132:135], v[192:195], v[68:71]
	v_mfma_f32_16x16x32_bf16 v[64:67], v[168:171], v[192:195], v[64:67]
	s_add_i32 s75, s75, 2
	v_mfma_f32_16x16x32_bf16 v[52:55], v[132:135], v[200:203], v[52:55]
	s_add_u32 s54, s54, 0x100
	v_mfma_f32_16x16x32_bf16 v[48:51], v[168:171], v[200:203], v[48:51]
	s_addc_u32 s55, s55, 0
	v_mfma_f32_16x16x32_bf16 v[36:39], v[132:135], v[208:211], v[36:39]
	s_add_u32 s73, s73, 0x100
	v_mfma_f32_16x16x32_bf16 v[32:35], v[168:171], v[208:211], v[32:35]
	s_addc_u32 s74, s74, 0
	v_mfma_f32_16x16x32_bf16 v[20:23], v[132:135], v[216:219], v[20:23]
	s_add_u32 s0, s54, 0xfff00080
	v_mfma_f32_16x16x32_bf16 v[16:19], v[168:171], v[216:219], v[16:19]
	s_addc_u32 s56, s55, -1
	v_mfma_f32_16x16x32_bf16 v[68:71], v[164:167], v[196:199], v[68:71]
	s_cmp_eq_u32 s75, 60
	v_mfma_f32_16x16x32_bf16 v[64:67], v[172:175], v[196:199], v[64:67]
	s_cselect_b32 s59, s31, s56
	v_mfma_f32_16x16x32_bf16 v[52:55], v[164:167], v[204:207], v[52:55]
	s_cselect_b32 s58, s71, s0
	v_mfma_f32_16x16x32_bf16 v[48:51], v[172:175], v[204:207], v[48:51]
	s_cselect_b32 s57, s29, s74
	v_mfma_f32_16x16x32_bf16 v[36:39], v[164:167], v[212:215], v[36:39]
	s_cselect_b32 s56, s72, s73
	v_mfma_f32_16x16x32_bf16 v[32:35], v[172:175], v[212:215], v[32:35]
	s_add_i32 m0, s48, 0xc000
	v_mfma_f32_16x16x32_bf16 v[20:23], v[164:167], v[220:223], v[20:23]
	s_cmp_gt_u32 s75, 61
	v_mfma_f32_16x16x32_bf16 v[16:19], v[172:175], v[220:223], v[16:19]
	s_setprio 0
	s_setprio 1
	v_mfma_f32_16x16x32_bf16 v[60:63], v[176:179], v[192:195], v[60:63]
	v_mfma_f32_16x16x32_bf16 v[56:59], v[184:187], v[192:195], v[56:59]
	v_mfma_f32_16x16x32_bf16 v[44:47], v[176:179], v[200:203], v[44:47]
	v_mfma_f32_16x16x32_bf16 v[40:43], v[184:187], v[200:203], v[40:43]
	v_mfma_f32_16x16x32_bf16 v[28:31], v[176:179], v[208:211], v[28:31]
	v_mfma_f32_16x16x32_bf16 v[24:27], v[184:187], v[208:211], v[24:27]
	v_mfma_f32_16x16x32_bf16 v[12:15], v[176:179], v[216:219], v[12:15]
	v_mfma_f32_16x16x32_bf16 v[8:11], v[184:187], v[216:219], v[8:11]
	v_mfma_f32_16x16x32_bf16 v[60:63], v[180:183], v[196:199], v[60:63]
	v_mfma_f32_16x16x32_bf16 v[56:59], v[188:191], v[196:199], v[56:59]
	v_mfma_f32_16x16x32_bf16 v[44:47], v[180:183], v[204:207], v[44:47]
	v_mfma_f32_16x16x32_bf16 v[40:43], v[188:191], v[204:207], v[40:43]
	v_mfma_f32_16x16x32_bf16 v[28:31], v[180:183], v[212:215], v[28:31]
	v_mfma_f32_16x16x32_bf16 v[24:27], v[188:191], v[212:215], v[24:27]
	v_mfma_f32_16x16x32_bf16 v[12:15], v[180:183], v[220:223], v[12:15]
	v_mfma_f32_16x16x32_bf16 v[8:11], v[188:191], v[220:223], v[8:11]
	s_setprio 0
	s_barrier
	s_cbranch_scc0 .LBB0_1503
	s_and_b64 vcc, exec, s[26:27]
	s_cbranch_vccz .LBB0_1506
	s_barrier

.LBB0_1671:
	s_add_u32 s30, s30, 0x2b0080
	s_addc_u32 s31, s31, 0
	s_add_u32 s64, s42, 0x100
	v_mov_b32_e32 v4, 0
	s_addc_u32 s65, s43, 0
	s_mov_b32 s66, -2
	s_waitcnt lgkmcnt(0)
	v_mov_b32_e32 v5, 0
	v_mov_b64_e32 v[6:7], 0
	v_mov_b64_e32 v[8:9], 0
	v_mov_b64_e32 v[10:11], 0
	v_mov_b64_e32 v[20:21], 0
	v_mov_b64_e32 v[22:23], 0
	v_mov_b64_e32 v[24:25], 0
	v_mov_b64_e32 v[26:27], 0
	v_mov_b64_e32 v[36:37], 0
	v_mov_b64_e32 v[38:39], 0
	v_mov_b64_e32 v[40:41], 0
	v_mov_b64_e32 v[42:43], 0
	v_mov_b64_e32 v[52:53], 0
	v_mov_b64_e32 v[54:55], 0
	v_mov_b64_e32 v[56:57], 0
	v_mov_b64_e32 v[58:59], 0
	v_mov_b64_e32 v[12:13], 0
	v_mov_b64_e32 v[14:15], 0
	v_mov_b64_e32 v[16:17], 0
	v_mov_b64_e32 v[18:19], 0
	v_mov_b64_e32 v[28:29], 0
	v_mov_b64_e32 v[30:31], 0
	v_mov_b64_e32 v[32:33], 0
	v_mov_b64_e32 v[34:35], 0
	v_mov_b64_e32 v[44:45], 0
	v_mov_b64_e32 v[46:47], 0
	v_mov_b64_e32 v[48:49], 0
	v_mov_b64_e32 v[50:51], 0
	v_mov_b64_e32 v[60:61], 0
	v_mov_b64_e32 v[62:63], 0
	v_mov_b64_e32 v[64:65], 0
	v_mov_b64_e32 v[66:67], 0
	v_mov_b64_e32 v[68:69], 0
	v_mov_b64_e32 v[70:71], 0
	v_mov_b64_e32 v[72:73], 0
	v_mov_b64_e32 v[74:75], 0
	v_mov_b64_e32 v[84:85], 0
	v_mov_b64_e32 v[86:87], 0
	v_mov_b64_e32 v[88:89], 0
	v_mov_b64_e32 v[90:91], 0
	v_mov_b64_e32 v[100:101], 0
	v_mov_b64_e32 v[102:103], 0
	v_mov_b64_e32 v[104:105], 0
	v_mov_b64_e32 v[106:107], 0
	v_mov_b64_e32 v[116:117], 0
	v_mov_b64_e32 v[118:119], 0
	v_mov_b64_e32 v[120:121], 0
	v_mov_b64_e32 v[122:123], 0
	v_mov_b64_e32 v[76:77], 0
	v_mov_b64_e32 v[78:79], 0
	v_mov_b64_e32 v[80:81], 0
	v_mov_b64_e32 v[82:83], 0
	v_mov_b64_e32 v[92:93], 0
	v_mov_b64_e32 v[94:95], 0
	v_mov_b64_e32 v[96:97], 0
	v_mov_b64_e32 v[98:99], 0
	v_mov_b64_e32 v[108:109], 0
	v_mov_b64_e32 v[110:111], 0
	v_mov_b64_e32 v[112:113], 0
	v_mov_b64_e32 v[114:115], 0
	v_mov_b64_e32 v[124:125], 0
	v_mov_b64_e32 v[126:127], 0
	v_mov_b64_e32 v[128:129], 0
	v_mov_b64_e32 v[130:131], 0
	s_add_u32 s0, s30, 0xffd50080
	s_addc_u32 s42, s31, -1
	s_cmpk_eq_i32 s66, 0xa8
	s_cselect_b32 s51, s7, s42
	s_cselect_b32 s50, s6, s0
	s_cselect_b32 s43, s29, s65
	s_cselect_b32 s42, s28, s64
	s_add_i32 m0, s46, 0xc000
.LBB0_1672:
	ds_read_b128 v[132:135], v193
	ds_read_b128 v[136:139], v193 offset:1024
	ds_read_b128 v[140:143], v193 offset:2048
	ds_read_b128 v[144:147], v193 offset:3072
	ds_read_b128 v[148:151], v194
	ds_read_b128 v[152:155], v194 offset:1024
	ds_read_b128 v[172:175], v194 offset:2048
	ds_read_b128 v[176:179], v194 offset:3072
	ds_read_b128 v[180:183], v195
	ds_read_b128 v[198:201], v195 offset:1024
	ds_read_b128 v[202:205], v195 offset:2048
	ds_read_b128 v[206:209], v195 offset:3072
	ds_read_b128 v[210:213], v195 offset:4096
	ds_read_b128 v[214:217], v195 offset:5120
	ds_read_b128 v[218:221], v195 offset:6144
	ds_read_b128 v[222:225], v195 offset:7168
	global_load_lds_dwordx4 v164, s[30:31]
	s_add_i32 m0, s46, 0xe000
	s_nop 0
	global_load_lds_dwordx4 v166, s[30:31]
	s_waitcnt vmcnt(8)
	s_waitcnt lgkmcnt(0)
	s_setprio 1
	s_barrier
	v_mfma_f32_16x16x32_bf16 v[128:131], v[132:135], v[180:183], v[128:131]
	v_mfma_f32_16x16x32_bf16 v[124:127], v[140:143], v[180:183], v[124:127]
	v_mfma_f32_16x16x32_bf16 v[112:115], v[132:135], v[202:205], v[112:115]
	v_mfma_f32_16x16x32_bf16 v[108:111], v[140:143], v[202:205], v[108:111]
	v_mfma_f32_16x16x32_bf16 v[96:99], v[132:135], v[210:213], v[96:99]
	v_mfma_f32_16x16x32_bf16 v[92:95], v[140:143], v[210:213], v[92:95]
	v_mfma_f32_16x16x32_bf16 v[80:83], v[132:135], v[218:221], v[80:83]
	v_mfma_f32_16x16x32_bf16 v[76:79], v[140:143], v[218:221], v[76:79]
	v_mfma_f32_16x16x32_bf16 v[128:131], v[136:139], v[198:201], v[128:131]
	v_mfma_f32_16x16x32_bf16 v[124:127], v[144:147], v[198:201], v[124:127]
	v_mfma_f32_16x16x32_bf16 v[112:115], v[136:139], v[206:209], v[112:115]
	v_mfma_f32_16x16x32_bf16 v[108:111], v[144:147], v[206:209], v[108:111]
	v_mfma_f32_16x16x32_bf16 v[96:99], v[136:139], v[214:217], v[96:99]
	v_mfma_f32_16x16x32_bf16 v[92:95], v[144:147], v[214:217], v[92:95]
	v_mfma_f32_16x16x32_bf16 v[80:83], v[136:139], v[222:225], v[80:83]
	v_mfma_f32_16x16x32_bf16 v[76:79], v[144:147], v[222:225], v[76:79]
	s_setprio 0
	s_setprio 1
	v_mfma_f32_16x16x32_bf16 v[120:123], v[148:151], v[180:183], v[120:123]
	v_mfma_f32_16x16x32_bf16 v[116:119], v[172:175], v[180:183], v[116:119]
	v_mfma_f32_16x16x32_bf16 v[104:107], v[148:151], v[202:205], v[104:107]
	v_mfma_f32_16x16x32_bf16 v[100:103], v[172:175], v[202:205], v[100:103]
	v_mfma_f32_16x16x32_bf16 v[88:91], v[148:151], v[210:213], v[88:91]
	v_mfma_f32_16x16x32_bf16 v[84:87], v[172:175], v[210:213], v[84:87]
	v_mfma_f32_16x16x32_bf16 v[72:75], v[148:151], v[218:221], v[72:75]
	v_mfma_f32_16x16x32_bf16 v[68:71], v[172:175], v[218:221], v[68:71]
	v_mfma_f32_16x16x32_bf16 v[120:123], v[152:155], v[198:201], v[120:123]
	v_mfma_f32_16x16x32_bf16 v[116:119], v[176:179], v[198:201], v[116:119]
	v_mfma_f32_16x16x32_bf16 v[104:107], v[152:155], v[206:209], v[104:107]
	v_mfma_f32_16x16x32_bf16 v[100:103], v[176:179], v[206:209], v[100:103]
	v_mfma_f32_16x16x32_bf16 v[88:91], v[152:155], v[214:217], v[88:91]
	v_mfma_f32_16x16x32_bf16 v[84:87], v[176:179], v[214:217], v[84:87]
	v_mfma_f32_16x16x32_bf16 v[72:75], v[152:155], v[222:225], v[72:75]
	v_mfma_f32_16x16x32_bf16 v[68:71], v[176:179], v[222:225], v[68:71]
	s_setprio 0
	s_barrier
	s_add_i32 s0, s57, s45
	s_mov_b32 m0, s0
	ds_read_b128 v[180:183], v195 offset:16384
	ds_read_b128 v[198:201], v195 offset:17408
	ds_read_b128 v[202:205], v195 offset:18432
	ds_read_b128 v[206:209], v195 offset:19456
	ds_read_b128 v[210:213], v195 offset:20480
	ds_read_b128 v[214:217], v195 offset:21504
	ds_read_b128 v[218:221], v195 offset:22528
	ds_read_b128 v[222:225], v195 offset:23552
	global_load_lds_dwordx4 v158, s[42:43]
	s_add_i32 m0, s0, 0x2000
	s_add_u32 s70, s42, 0x2b0000
	s_addc_u32 s71, s43, 0
	s_add_i32 s0, s58, s45
	global_load_lds_dwordx4 v162, s[42:43]
	s_mov_b32 m0, s0
	s_nop 0
	global_load_lds_dwordx4 v158, s[70:71]
	s_add_i32 m0, s0, 0x2000
	s_nop 0
	global_load_lds_dwordx4 v162, s[70:71]
	s_mov_b32 m0, s46
	s_nop 0
	global_load_lds_dwordx4 v156, s[50:51]
	s_mov_b32 m0, s47
	s_nop 0
	global_load_lds_dwordx4 v160, s[50:51]
	s_waitcnt vmcnt(8)
	s_waitcnt lgkmcnt(0)
	s_setprio 1
	s_barrier
	v_mfma_f32_16x16x32_bf16 v[64:67], v[132:135], v[180:183], v[64:67]
	v_mfma_f32_16x16x32_bf16 v[60:63], v[140:143], v[180:183], v[60:63]
	v_mfma_f32_16x16x32_bf16 v[48:51], v[132:135], v[202:205], v[48:51]
	v_mfma_f32_16x16x32_bf16 v[44:47], v[140:143], v[202:205], v[44:47]
	v_mfma_f32_16x16x32_bf16 v[32:35], v[132:135], v[210:213], v[32:35]
	v_mfma_f32_16x16x32_bf16 v[28:31], v[140:143], v[210:213], v[28:31]
	v_mfma_f32_16x16x32_bf16 v[16:19], v[132:135], v[218:221], v[16:19]
	v_mfma_f32_16x16x32_bf16 v[12:15], v[140:143], v[218:221], v[12:15]
	v_mfma_f32_16x16x32_bf16 v[64:67], v[136:139], v[198:201], v[64:67]
	v_mfma_f32_16x16x32_bf16 v[60:63], v[144:147], v[198:201], v[60:63]
	v_mfma_f32_16x16x32_bf16 v[48:51], v[136:139], v[206:209], v[48:51]
	v_mfma_f32_16x16x32_bf16 v[44:47], v[144:147], v[206:209], v[44:47]
	v_mfma_f32_16x16x32_bf16 v[32:35], v[136:139], v[214:217], v[32:35]
	v_mfma_f32_16x16x32_bf16 v[28:31], v[144:147], v[214:217], v[28:31]
	v_mfma_f32_16x16x32_bf16 v[16:19], v[136:139], v[222:225], v[16:19]
	v_mfma_f32_16x16x32_bf16 v[12:15], v[144:147], v[222:225], v[12:15]
	s_setprio 0
	s_setprio 1
	v_mfma_f32_16x16x32_bf16 v[56:59], v[148:151], v[180:183], v[56:59]
	v_mfma_f32_16x16x32_bf16 v[52:55], v[172:175], v[180:183], v[52:55]
	v_mfma_f32_16x16x32_bf16 v[40:43], v[148:151], v[202:205], v[40:43]
	v_mfma_f32_16x16x32_bf16 v[36:39], v[172:175], v[202:205], v[36:39]
	v_mfma_f32_16x16x32_bf16 v[24:27], v[148:151], v[210:213], v[24:27]
	v_mfma_f32_16x16x32_bf16 v[20:23], v[172:175], v[210:213], v[20:23]
	v_mfma_f32_16x16x32_bf16 v[8:11], v[148:151], v[218:221], v[8:11]
	v_mfma_f32_16x16x32_bf16 v[4:7], v[172:175], v[218:221], v[4:7]
	v_mfma_f32_16x16x32_bf16 v[56:59], v[152:155], v[198:201], v[56:59]
	v_mfma_f32_16x16x32_bf16 v[52:55], v[176:179], v[198:201], v[52:55]
	v_mfma_f32_16x16x32_bf16 v[40:43], v[152:155], v[206:209], v[40:43]
	v_mfma_f32_16x16x32_bf16 v[36:39], v[176:179], v[206:209], v[36:39]
	v_mfma_f32_16x16x32_bf16 v[24:27], v[152:155], v[214:217], v[24:27]
	v_mfma_f32_16x16x32_bf16 v[20:23], v[176:179], v[214:217], v[20:23]
	v_mfma_f32_16x16x32_bf16 v[8:11], v[152:155], v[222:225], v[8:11]
	v_mfma_f32_16x16x32_bf16 v[4:7], v[176:179], v[222:225], v[4:7]
	s_setprio 0
	s_barrier
	s_add_i32 s0, 0, 0x18000
	s_add_i32 s67, 0, 0x1c000
	v_add_u32_e32 v144, s0, v191
	v_add_u32_e32 v176, s67, v191
	ds_read_b128 v[132:135], v144
	ds_read_b128 v[136:139], v144 offset:1024
	ds_read_b128 v[140:143], v144 offset:2048
	ds_read_b128 v[144:147], v144 offset:3072
	ds_read_b128 v[148:151], v176
	ds_read_b128 v[152:155], v176 offset:1024
	ds_read_b128 v[172:175], v176 offset:2048
	ds_read_b128 v[176:179], v176 offset:3072
	s_add_u32 s98, s50, 0x2b0000
	s_addc_u32 s99, s51, 0
	s_mov_b32 m0, s48
	ds_read_b128 v[180:183], v195 offset:32768
	ds_read_b128 v[198:201], v195 offset:33792
	ds_read_b128 v[202:205], v195 offset:34816
	ds_read_b128 v[206:209], v195 offset:35840
	ds_read_b128 v[210:213], v195 offset:36864
	ds_read_b128 v[214:217], v195 offset:37888
	ds_read_b128 v[218:221], v195 offset:38912
	ds_read_b128 v[222:225], v195 offset:39936
	global_load_lds_dwordx4 v156, s[98:99]
	s_mov_b32 m0, s49
	s_nop 0
	global_load_lds_dwordx4 v160, s[98:99]
	s_waitcnt vmcnt(8)
	s_waitcnt lgkmcnt(0)
	s_setprio 1
	s_barrier
	v_mfma_f32_16x16x32_bf16 v[128:131], v[132:135], v[180:183], v[128:131]
	v_mfma_f32_16x16x32_bf16 v[124:127], v[140:143], v[180:183], v[124:127]
	v_mfma_f32_16x16x32_bf16 v[112:115], v[132:135], v[202:205], v[112:115]
	v_mfma_f32_16x16x32_bf16 v[108:111], v[140:143], v[202:205], v[108:111]
	v_mfma_f32_16x16x32_bf16 v[96:99], v[132:135], v[210:213], v[96:99]
	v_mfma_f32_16x16x32_bf16 v[92:95], v[140:143], v[210:213], v[92:95]
	v_mfma_f32_16x16x32_bf16 v[80:83], v[132:135], v[218:221], v[80:83]
	v_mfma_f32_16x16x32_bf16 v[76:79], v[140:143], v[218:221], v[76:79]
	v_mfma_f32_16x16x32_bf16 v[128:131], v[136:139], v[198:201], v[128:131]
	v_mfma_f32_16x16x32_bf16 v[124:127], v[144:147], v[198:201], v[124:127]
	v_mfma_f32_16x16x32_bf16 v[112:115], v[136:139], v[206:209], v[112:115]
	v_mfma_f32_16x16x32_bf16 v[108:111], v[144:147], v[206:209], v[108:111]
	v_mfma_f32_16x16x32_bf16 v[96:99], v[136:139], v[214:217], v[96:99]
	v_mfma_f32_16x16x32_bf16 v[92:95], v[144:147], v[214:217], v[92:95]
	v_mfma_f32_16x16x32_bf16 v[80:83], v[136:139], v[222:225], v[80:83]
	v_mfma_f32_16x16x32_bf16 v[76:79], v[144:147], v[222:225], v[76:79]
	s_setprio 0
	s_setprio 1
	v_mfma_f32_16x16x32_bf16 v[120:123], v[148:151], v[180:183], v[120:123]
	v_mfma_f32_16x16x32_bf16 v[116:119], v[172:175], v[180:183], v[116:119]
	v_mfma_f32_16x16x32_bf16 v[104:107], v[148:151], v[202:205], v[104:107]
	v_mfma_f32_16x16x32_bf16 v[100:103], v[172:175], v[202:205], v[100:103]
	v_mfma_f32_16x16x32_bf16 v[88:91], v[148:151], v[210:213], v[88:91]
	v_mfma_f32_16x16x32_bf16 v[84:87], v[172:175], v[210:213], v[84:87]
	v_mfma_f32_16x16x32_bf16 v[72:75], v[148:151], v[218:221], v[72:75]
	v_mfma_f32_16x16x32_bf16 v[68:71], v[172:175], v[218:221], v[68:71]
	v_mfma_f32_16x16x32_bf16 v[120:123], v[152:155], v[198:201], v[120:123]
	v_mfma_f32_16x16x32_bf16 v[116:119], v[176:179], v[198:201], v[116:119]
	v_mfma_f32_16x16x32_bf16 v[104:107], v[152:155], v[206:209], v[104:107]
	v_mfma_f32_16x16x32_bf16 v[100:103], v[176:179], v[206:209], v[100:103]
	v_mfma_f32_16x16x32_bf16 v[88:91], v[152:155], v[214:217], v[88:91]
	v_mfma_f32_16x16x32_bf16 v[84:87], v[176:179], v[214:217], v[84:87]
	v_mfma_f32_16x16x32_bf16 v[72:75], v[152:155], v[222:225], v[72:75]
	v_mfma_f32_16x16x32_bf16 v[68:71], v[176:179], v[222:225], v[68:71]
	s_setprio 0
	s_barrier
	s_add_i32 s0, s0, s45
	s_add_i32 m0, s0, 0xffffff80
	ds_read_b128 v[180:183], v195 offset:49152
	ds_read_b128 v[198:201], v195 offset:50176
	ds_read_b128 v[202:205], v195 offset:51200
	ds_read_b128 v[206:209], v195 offset:52224
	ds_read_b128 v[210:213], v195 offset:53248
	ds_read_b128 v[214:217], v195 offset:54272
	ds_read_b128 v[218:221], v195 offset:55296
	ds_read_b128 v[222:225], v195 offset:56320
	global_load_lds_dwordx4 v158, s[42:43] offset:128
	s_add_i32 m0, s0, 0x1f80
	s_add_i32 s0, s67, s45
	global_load_lds_dwordx4 v162, s[42:43] offset:128
	s_add_u32 s42, s42, 0x2b0080
	s_addc_u32 s43, s43, 0
	s_mov_b32 m0, s0
	s_nop 0
	global_load_lds_dwordx4 v158, s[42:43]
	s_add_i32 m0, s0, 0x2000
	s_nop 0
	global_load_lds_dwordx4 v162, s[42:43]
	s_add_i32 m0, s55, 0xffffff80
	s_nop 0
	global_load_lds_dwordx4 v156, s[50:51] offset:128
	s_add_i32 m0, s56, 0xffffff80
	s_nop 0
	global_load_lds_dwordx4 v160, s[50:51] offset:128
	s_waitcnt vmcnt(8)
	s_waitcnt lgkmcnt(0)
	s_setprio 1
	s_barrier
	v_mfma_f32_16x16x32_bf16 v[64:67], v[132:135], v[180:183], v[64:67]
	v_mfma_f32_16x16x32_bf16 v[60:63], v[140:143], v[180:183], v[60:63]
	s_add_i32 s66, s66, 2
	v_mfma_f32_16x16x32_bf16 v[48:51], v[132:135], v[202:205], v[48:51]
	s_add_u32 s30, s30, 0x100
	v_mfma_f32_16x16x32_bf16 v[44:47], v[140:143], v[202:205], v[44:47]
	s_addc_u32 s31, s31, 0
	v_mfma_f32_16x16x32_bf16 v[32:35], v[132:135], v[210:213], v[32:35]
	s_add_u32 s64, s64, 0x100
	v_mfma_f32_16x16x32_bf16 v[28:31], v[140:143], v[210:213], v[28:31]
	s_addc_u32 s65, s65, 0
	v_mfma_f32_16x16x32_bf16 v[16:19], v[132:135], v[218:221], v[16:19]
	s_add_u32 s0, s30, 0xffd50080
	v_mfma_f32_16x16x32_bf16 v[12:15], v[140:143], v[218:221], v[12:15]
	s_addc_u32 s42, s31, -1
	v_mfma_f32_16x16x32_bf16 v[64:67], v[136:139], v[198:201], v[64:67]
	s_cmpk_eq_i32 s66, 0xa8
	v_mfma_f32_16x16x32_bf16 v[60:63], v[144:147], v[198:201], v[60:63]
	s_cselect_b32 s51, s7, s42
	v_mfma_f32_16x16x32_bf16 v[48:51], v[136:139], v[206:209], v[48:51]
	s_cselect_b32 s50, s6, s0
	v_mfma_f32_16x16x32_bf16 v[44:47], v[144:147], v[206:209], v[44:47]
	s_cselect_b32 s43, s29, s65
	v_mfma_f32_16x16x32_bf16 v[32:35], v[136:139], v[214:217], v[32:35]
	s_cselect_b32 s42, s28, s64
	v_mfma_f32_16x16x32_bf16 v[28:31], v[144:147], v[214:217], v[28:31]
	s_add_i32 m0, s46, 0xc000
	v_mfma_f32_16x16x32_bf16 v[16:19], v[136:139], v[222:225], v[16:19]
	s_cmpk_gt_u32 s66, 0xa9
	v_mfma_f32_16x16x32_bf16 v[12:15], v[144:147], v[222:225], v[12:15]
	s_setprio 0
	s_setprio 1
	v_mfma_f32_16x16x32_bf16 v[56:59], v[148:151], v[180:183], v[56:59]
	v_mfma_f32_16x16x32_bf16 v[52:55], v[172:175], v[180:183], v[52:55]
	v_mfma_f32_16x16x32_bf16 v[40:43], v[148:151], v[202:205], v[40:43]
	v_mfma_f32_16x16x32_bf16 v[36:39], v[172:175], v[202:205], v[36:39]
	v_mfma_f32_16x16x32_bf16 v[24:27], v[148:151], v[210:213], v[24:27]
	v_mfma_f32_16x16x32_bf16 v[20:23], v[172:175], v[210:213], v[20:23]
	v_mfma_f32_16x16x32_bf16 v[8:11], v[148:151], v[218:221], v[8:11]
	v_mfma_f32_16x16x32_bf16 v[4:7], v[172:175], v[218:221], v[4:7]
	v_mfma_f32_16x16x32_bf16 v[56:59], v[152:155], v[198:201], v[56:59]
	v_mfma_f32_16x16x32_bf16 v[52:55], v[176:179], v[198:201], v[52:55]
	v_mfma_f32_16x16x32_bf16 v[40:43], v[152:155], v[206:209], v[40:43]
	v_mfma_f32_16x16x32_bf16 v[36:39], v[176:179], v[206:209], v[36:39]
	v_mfma_f32_16x16x32_bf16 v[24:27], v[152:155], v[214:217], v[24:27]
	v_mfma_f32_16x16x32_bf16 v[20:23], v[176:179], v[214:217], v[20:23]
	v_mfma_f32_16x16x32_bf16 v[8:11], v[152:155], v[222:225], v[8:11]
	v_mfma_f32_16x16x32_bf16 v[4:7], v[176:179], v[222:225], v[4:7]
	s_setprio 0
	s_barrier
	s_cbranch_scc0 .LBB0_1672
	s_and_b64 vcc, exec, s[24:25]
	s_cbranch_vccz .LBB0_1675
	s_barrier

.LBB0_1702:
	s_mov_b32 s22, s64
	s_or_b32 s64, s0, s33
	s_mul_i32 s0, s64, 0x560000
	s_mov_b64 s[6:7], s[18:19]
	s_add_u32 s18, s1, s0
	s_addc_u32 s19, s35, 0
	s_and_b64 s[8:9], s[10:11], exec
	s_cselect_b32 s50, s19, s7
	s_cselect_b32 s51, s18, s6
	s_add_u32 s65, s6, 0x100
	s_addc_u32 s66, s7, 0
	v_lshl_add_u64 v[132:133], s[6:7], 0, v[172:173]
	v_lshl_add_u64 v[134:135], s[6:7], 0, v[174:175]
	s_mov_b32 s67, -2
	s_mov_b64 s[6:7], 0
	v_mov_b32_e32 v4, v171
	v_mov_b32_e32 v5, v171
	v_mov_b32_e32 v6, v171
	v_mov_b32_e32 v7, v171
	v_mov_b32_e32 v8, v171
	v_mov_b32_e32 v9, v171
	v_mov_b32_e32 v10, v171
	v_mov_b32_e32 v11, v171
	v_mov_b32_e32 v20, v171
	v_mov_b32_e32 v21, v171
	v_mov_b32_e32 v22, v171
	v_mov_b32_e32 v23, v171
	v_mov_b32_e32 v24, v171
	v_mov_b32_e32 v25, v171
	v_mov_b32_e32 v26, v171
	v_mov_b32_e32 v27, v171
	v_mov_b32_e32 v36, v171
	v_mov_b32_e32 v37, v171
	v_mov_b32_e32 v38, v171
	v_mov_b32_e32 v39, v171
	v_mov_b32_e32 v40, v171
	v_mov_b32_e32 v41, v171
	v_mov_b32_e32 v42, v171
	v_mov_b32_e32 v43, v171
	v_mov_b32_e32 v52, v171
	v_mov_b32_e32 v53, v171
	v_mov_b32_e32 v54, v171
	v_mov_b32_e32 v55, v171
	v_mov_b32_e32 v56, v171
	v_mov_b32_e32 v57, v171
	v_mov_b32_e32 v58, v171
	v_mov_b32_e32 v59, v171
	v_mov_b32_e32 v12, v171
	v_mov_b32_e32 v13, v171
	v_mov_b32_e32 v14, v171
	v_mov_b32_e32 v15, v171
	v_mov_b32_e32 v16, v171
	v_mov_b32_e32 v17, v171
	v_mov_b32_e32 v18, v171
	v_mov_b32_e32 v19, v171
	v_mov_b32_e32 v28, v171
	v_mov_b32_e32 v29, v171
	v_mov_b32_e32 v30, v171
	v_mov_b32_e32 v31, v171
	v_mov_b32_e32 v32, v171
	v_mov_b32_e32 v33, v171
	v_mov_b32_e32 v34, v171
	v_mov_b32_e32 v35, v171
	v_mov_b32_e32 v44, v171
	v_mov_b32_e32 v45, v171
	v_mov_b32_e32 v46, v171
	v_mov_b32_e32 v47, v171
	v_mov_b32_e32 v48, v171
	v_mov_b32_e32 v49, v171
	v_mov_b32_e32 v50, v171
	v_mov_b32_e32 v51, v171
	v_mov_b32_e32 v60, v171
	v_mov_b32_e32 v61, v171
	v_mov_b32_e32 v62, v171
	v_mov_b32_e32 v63, v171
	v_mov_b32_e32 v64, v171
	v_mov_b32_e32 v65, v171
	v_mov_b32_e32 v66, v171
	v_mov_b32_e32 v67, v171
	v_mov_b32_e32 v68, v171
	v_mov_b32_e32 v69, v171
	v_mov_b32_e32 v70, v171
	v_mov_b32_e32 v71, v171
	v_mov_b32_e32 v72, v171
	v_mov_b32_e32 v73, v171
	v_mov_b32_e32 v74, v171
	v_mov_b32_e32 v75, v171
	v_mov_b32_e32 v84, v171
	v_mov_b32_e32 v85, v171
	v_mov_b32_e32 v86, v171
	v_mov_b32_e32 v87, v171
	v_mov_b32_e32 v88, v171
	v_mov_b32_e32 v89, v171
	v_mov_b32_e32 v90, v171
	v_mov_b32_e32 v91, v171
	v_mov_b32_e32 v100, v171
	v_mov_b32_e32 v101, v171
	v_mov_b32_e32 v102, v171
	v_mov_b32_e32 v103, v171
	v_mov_b32_e32 v104, v171
	v_mov_b32_e32 v105, v171
	v_mov_b32_e32 v106, v171
	v_mov_b32_e32 v107, v171
	v_mov_b32_e32 v116, v171
	v_mov_b32_e32 v117, v171
	v_mov_b32_e32 v118, v171
	v_mov_b32_e32 v119, v171
	v_mov_b32_e32 v120, v171
	v_mov_b32_e32 v121, v171
	v_mov_b32_e32 v122, v171
	v_mov_b32_e32 v123, v171
	v_mov_b32_e32 v76, v171
	v_mov_b32_e32 v77, v171
	v_mov_b32_e32 v78, v171
	v_mov_b32_e32 v79, v171
	v_mov_b32_e32 v80, v171
	v_mov_b32_e32 v81, v171
	v_mov_b32_e32 v82, v171
	v_mov_b32_e32 v83, v171
	v_mov_b32_e32 v92, v171
	v_mov_b32_e32 v93, v171
	v_mov_b32_e32 v94, v171
	v_mov_b32_e32 v95, v171
	v_mov_b32_e32 v96, v171
	v_mov_b32_e32 v97, v171
	v_mov_b32_e32 v98, v171
	v_mov_b32_e32 v99, v171
	v_mov_b32_e32 v108, v171
	v_mov_b32_e32 v109, v171
	v_mov_b32_e32 v110, v171
	v_mov_b32_e32 v111, v171
	v_mov_b32_e32 v112, v171
	v_mov_b32_e32 v113, v171
	v_mov_b32_e32 v114, v171
	v_mov_b32_e32 v115, v171
	v_mov_b32_e32 v124, v171
	v_mov_b32_e32 v125, v171
	v_mov_b32_e32 v126, v171
	v_mov_b32_e32 v127, v171
	v_mov_b32_e32 v128, v171
	v_mov_b32_e32 v129, v171
	v_mov_b32_e32 v130, v171
	v_mov_b32_e32 v131, v171
	s_add_u32 s8, s6, 0x100
	s_addc_u32 s9, s7, 0
	s_add_u32 s0, s65, s6
	s_addc_u32 s40, s66, s7
	s_cmpk_eq_i32 s67, 0xa8
	s_cselect_b32 s43, s50, s40
	s_cselect_b32 s40, 0, s8
	s_cselect_b32 s42, s51, s0
	s_cselect_b32 s0, 0, s9
	s_add_u32 s40, s16, s40
	s_addc_u32 s41, s17, s0
	s_mov_b32 m0, s58
.LBB0_1703:
	ds_read_b128 v[136:139], v196
	ds_read_b128 v[140:143], v196 offset:1024
	ds_read_b128 v[144:147], v196 offset:2048
	ds_read_b128 v[148:151], v196 offset:3072
	ds_read_b128 v[152:155], v197
	ds_read_b128 v[176:179], v197 offset:1024
	ds_read_b128 v[180:183], v197 offset:2048
	ds_read_b128 v[184:187], v197 offset:3072
	v_lshl_add_u64 v[226:227], v[132:133], 0, s[6:7]
	ds_read_b128 v[188:191], v198
	ds_read_b128 v[192:195], v198 offset:1024
	ds_read_b128 v[202:205], v198 offset:2048
	ds_read_b128 v[206:209], v198 offset:3072
	ds_read_b128 v[210:213], v198 offset:4096
	ds_read_b128 v[214:217], v198 offset:5120
	ds_read_b128 v[218:221], v198 offset:6144
	ds_read_b128 v[222:225], v198 offset:7168
	global_load_lds_dwordx4 v[226:227], off
	v_lshl_add_u64 v[226:227], v[134:135], 0, s[6:7]
	s_mov_b32 m0, s59
	s_nop 0
	global_load_lds_dwordx4 v[226:227], off
	s_waitcnt vmcnt(8)
	s_waitcnt lgkmcnt(0)
	s_setprio 1
	s_barrier
	v_mfma_f32_16x16x32_bf16 v[128:131], v[136:139], v[188:191], v[128:131]
	v_mfma_f32_16x16x32_bf16 v[124:127], v[144:147], v[188:191], v[124:127]
	v_mfma_f32_16x16x32_bf16 v[112:115], v[136:139], v[202:205], v[112:115]
	v_mfma_f32_16x16x32_bf16 v[108:111], v[144:147], v[202:205], v[108:111]
	v_mfma_f32_16x16x32_bf16 v[96:99], v[136:139], v[210:213], v[96:99]
	v_mfma_f32_16x16x32_bf16 v[92:95], v[144:147], v[210:213], v[92:95]
	v_mfma_f32_16x16x32_bf16 v[80:83], v[136:139], v[218:221], v[80:83]
	v_mfma_f32_16x16x32_bf16 v[76:79], v[144:147], v[218:221], v[76:79]
	v_mfma_f32_16x16x32_bf16 v[128:131], v[140:143], v[192:195], v[128:131]
	v_mfma_f32_16x16x32_bf16 v[124:127], v[148:151], v[192:195], v[124:127]
	v_mfma_f32_16x16x32_bf16 v[112:115], v[140:143], v[206:209], v[112:115]
	v_mfma_f32_16x16x32_bf16 v[108:111], v[148:151], v[206:209], v[108:111]
	v_mfma_f32_16x16x32_bf16 v[96:99], v[140:143], v[214:217], v[96:99]
	v_mfma_f32_16x16x32_bf16 v[92:95], v[148:151], v[214:217], v[92:95]
	v_mfma_f32_16x16x32_bf16 v[80:83], v[140:143], v[222:225], v[80:83]
	v_mfma_f32_16x16x32_bf16 v[76:79], v[148:151], v[222:225], v[76:79]
	s_setprio 0
	s_setprio 1
	v_mfma_f32_16x16x32_bf16 v[120:123], v[152:155], v[188:191], v[120:123]
	v_mfma_f32_16x16x32_bf16 v[116:119], v[180:183], v[188:191], v[116:119]
	v_mfma_f32_16x16x32_bf16 v[104:107], v[152:155], v[202:205], v[104:107]
	v_mfma_f32_16x16x32_bf16 v[100:103], v[180:183], v[202:205], v[100:103]
	v_mfma_f32_16x16x32_bf16 v[88:91], v[152:155], v[210:213], v[88:91]
	v_mfma_f32_16x16x32_bf16 v[84:87], v[180:183], v[210:213], v[84:87]
	v_mfma_f32_16x16x32_bf16 v[72:75], v[152:155], v[218:221], v[72:75]
	v_mfma_f32_16x16x32_bf16 v[68:71], v[180:183], v[218:221], v[68:71]
	v_mfma_f32_16x16x32_bf16 v[120:123], v[176:179], v[192:195], v[120:123]
	v_mfma_f32_16x16x32_bf16 v[116:119], v[184:187], v[192:195], v[116:119]
	v_mfma_f32_16x16x32_bf16 v[104:107], v[176:179], v[206:209], v[104:107]
	v_mfma_f32_16x16x32_bf16 v[100:103], v[184:187], v[206:209], v[100:103]
	v_mfma_f32_16x16x32_bf16 v[88:91], v[176:179], v[214:217], v[88:91]
	v_mfma_f32_16x16x32_bf16 v[84:87], v[184:187], v[214:217], v[84:87]
	v_mfma_f32_16x16x32_bf16 v[72:75], v[176:179], v[222:225], v[72:75]
	v_mfma_f32_16x16x32_bf16 v[68:71], v[184:187], v[222:225], v[68:71]
	s_setprio 0
	s_barrier
	s_mov_b32 m0, s60
	v_lshl_add_u64 v[226:227], s[40:41], 0, v[158:159]
	s_add_u32 s6, s40, 0x2b0000
	ds_read_b128 v[188:191], v198 offset:16384
	ds_read_b128 v[192:195], v198 offset:17408
	ds_read_b128 v[202:205], v198 offset:18432
	ds_read_b128 v[206:209], v198 offset:19456
	ds_read_b128 v[210:213], v198 offset:20480
	ds_read_b128 v[214:217], v198 offset:21504
	ds_read_b128 v[218:221], v198 offset:22528
	ds_read_b128 v[222:225], v198 offset:23552
	global_load_lds_dwordx4 v[226:227], off
	v_lshl_add_u64 v[228:229], s[40:41], 0, v[162:163]
	s_mov_b32 m0, s61
	s_addc_u32 s7, s41, 0
	global_load_lds_dwordx4 v[228:229], off
	v_lshl_add_u64 v[230:231], s[6:7], 0, v[158:159]
	s_mov_b32 m0, s62
	v_lshl_add_u64 v[232:233], s[42:43], 0, v[160:161]
	global_load_lds_dwordx4 v[230:231], off
	v_lshl_add_u64 v[230:231], s[6:7], 0, v[162:163]
	s_mov_b32 m0, s63
	s_nop 0
	global_load_lds_dwordx4 v[230:231], off
	v_lshl_add_u64 v[230:231], s[42:43], 0, v[156:157]
	s_mov_b32 m0, s46
	s_nop 0
	global_load_lds_dwordx4 v[230:231], off
	s_mov_b32 m0, s47
	s_nop 0
	global_load_lds_dwordx4 v[232:233], off
	s_waitcnt vmcnt(8)
	s_waitcnt lgkmcnt(0)
	s_setprio 1
	s_barrier
	v_mfma_f32_16x16x32_bf16 v[64:67], v[136:139], v[188:191], v[64:67]
	v_mfma_f32_16x16x32_bf16 v[60:63], v[144:147], v[188:191], v[60:63]
	v_mfma_f32_16x16x32_bf16 v[48:51], v[136:139], v[202:205], v[48:51]
	v_mfma_f32_16x16x32_bf16 v[44:47], v[144:147], v[202:205], v[44:47]
	v_mfma_f32_16x16x32_bf16 v[32:35], v[136:139], v[210:213], v[32:35]
	v_mfma_f32_16x16x32_bf16 v[28:31], v[144:147], v[210:213], v[28:31]
	v_mfma_f32_16x16x32_bf16 v[16:19], v[136:139], v[218:221], v[16:19]
	v_mfma_f32_16x16x32_bf16 v[12:15], v[144:147], v[218:221], v[12:15]
	v_mfma_f32_16x16x32_bf16 v[64:67], v[140:143], v[192:195], v[64:67]
	v_mfma_f32_16x16x32_bf16 v[60:63], v[148:151], v[192:195], v[60:63]
	v_mfma_f32_16x16x32_bf16 v[48:51], v[140:143], v[206:209], v[48:51]
	v_mfma_f32_16x16x32_bf16 v[44:47], v[148:151], v[206:209], v[44:47]
	v_mfma_f32_16x16x32_bf16 v[32:35], v[140:143], v[214:217], v[32:35]
	v_mfma_f32_16x16x32_bf16 v[28:31], v[148:151], v[214:217], v[28:31]
	v_mfma_f32_16x16x32_bf16 v[16:19], v[140:143], v[222:225], v[16:19]
	v_mfma_f32_16x16x32_bf16 v[12:15], v[148:151], v[222:225], v[12:15]
	s_setprio 0
	s_setprio 1
	v_mfma_f32_16x16x32_bf16 v[56:59], v[152:155], v[188:191], v[56:59]
	v_mfma_f32_16x16x32_bf16 v[52:55], v[180:183], v[188:191], v[52:55]
	v_mfma_f32_16x16x32_bf16 v[40:43], v[152:155], v[202:205], v[40:43]
	v_mfma_f32_16x16x32_bf16 v[36:39], v[180:183], v[202:205], v[36:39]
	v_mfma_f32_16x16x32_bf16 v[24:27], v[152:155], v[210:213], v[24:27]
	v_mfma_f32_16x16x32_bf16 v[20:23], v[180:183], v[210:213], v[20:23]
	v_mfma_f32_16x16x32_bf16 v[8:11], v[152:155], v[218:221], v[8:11]
	v_mfma_f32_16x16x32_bf16 v[4:7], v[180:183], v[218:221], v[4:7]
	v_mfma_f32_16x16x32_bf16 v[56:59], v[176:179], v[192:195], v[56:59]
	v_mfma_f32_16x16x32_bf16 v[52:55], v[184:187], v[192:195], v[52:55]
	v_mfma_f32_16x16x32_bf16 v[40:43], v[176:179], v[206:209], v[40:43]
	v_mfma_f32_16x16x32_bf16 v[36:39], v[184:187], v[206:209], v[36:39]
	v_mfma_f32_16x16x32_bf16 v[24:27], v[176:179], v[214:217], v[24:27]
	v_mfma_f32_16x16x32_bf16 v[20:23], v[184:187], v[214:217], v[20:23]
	v_mfma_f32_16x16x32_bf16 v[8:11], v[176:179], v[222:225], v[8:11]
	v_mfma_f32_16x16x32_bf16 v[4:7], v[184:187], v[222:225], v[4:7]
	s_setprio 0
	s_barrier
	s_add_i32 s0, 0, 0x18000
	s_add_i32 s68, 0, 0x1c000
	v_add_u32_e32 v148, s0, v3
	v_add_u32_e32 v170, s68, v3
	ds_read_b128 v[136:139], v148
	ds_read_b128 v[140:143], v148 offset:1024
	ds_read_b128 v[144:147], v148 offset:2048
	ds_read_b128 v[148:151], v148 offset:3072
	ds_read_b128 v[152:155], v170
	ds_read_b128 v[176:179], v170 offset:1024
	ds_read_b128 v[180:183], v170 offset:2048
	ds_read_b128 v[184:187], v170 offset:3072
	s_add_u32 s6, s42, 0x2b0000
	s_addc_u32 s7, s43, 0
	s_mov_b32 m0, s48
	v_lshl_add_u64 v[234:235], s[6:7], 0, v[156:157]
	ds_read_b128 v[188:191], v198 offset:32768
	ds_read_b128 v[192:195], v198 offset:33792
	ds_read_b128 v[202:205], v198 offset:34816
	ds_read_b128 v[206:209], v198 offset:35840
	ds_read_b128 v[210:213], v198 offset:36864
	ds_read_b128 v[214:217], v198 offset:37888
	ds_read_b128 v[218:221], v198 offset:38912
	ds_read_b128 v[222:225], v198 offset:39936
	global_load_lds_dwordx4 v[234:235], off
	v_lshl_add_u64 v[234:235], s[6:7], 0, v[160:161]
	s_mov_b32 m0, s49
	s_nop 0
	global_load_lds_dwordx4 v[234:235], off
	s_waitcnt vmcnt(8)
	s_waitcnt lgkmcnt(0)
	s_setprio 1
	s_barrier
	v_mfma_f32_16x16x32_bf16 v[128:131], v[136:139], v[188:191], v[128:131]
	v_mfma_f32_16x16x32_bf16 v[124:127], v[144:147], v[188:191], v[124:127]
	v_mfma_f32_16x16x32_bf16 v[112:115], v[136:139], v[202:205], v[112:115]
	v_mfma_f32_16x16x32_bf16 v[108:111], v[144:147], v[202:205], v[108:111]
	v_mfma_f32_16x16x32_bf16 v[96:99], v[136:139], v[210:213], v[96:99]
	v_mfma_f32_16x16x32_bf16 v[92:95], v[144:147], v[210:213], v[92:95]
	v_mfma_f32_16x16x32_bf16 v[80:83], v[136:139], v[218:221], v[80:83]
	v_mfma_f32_16x16x32_bf16 v[76:79], v[144:147], v[218:221], v[76:79]
	v_mfma_f32_16x16x32_bf16 v[128:131], v[140:143], v[192:195], v[128:131]
	v_mfma_f32_16x16x32_bf16 v[124:127], v[148:151], v[192:195], v[124:127]
	v_mfma_f32_16x16x32_bf16 v[112:115], v[140:143], v[206:209], v[112:115]
	v_mfma_f32_16x16x32_bf16 v[108:111], v[148:151], v[206:209], v[108:111]
	v_mfma_f32_16x16x32_bf16 v[96:99], v[140:143], v[214:217], v[96:99]
	v_mfma_f32_16x16x32_bf16 v[92:95], v[148:151], v[214:217], v[92:95]
	v_mfma_f32_16x16x32_bf16 v[80:83], v[140:143], v[222:225], v[80:83]
	v_mfma_f32_16x16x32_bf16 v[76:79], v[148:151], v[222:225], v[76:79]
	s_setprio 0
	s_setprio 1
	v_mfma_f32_16x16x32_bf16 v[120:123], v[152:155], v[188:191], v[120:123]
	v_mfma_f32_16x16x32_bf16 v[116:119], v[180:183], v[188:191], v[116:119]
	v_mfma_f32_16x16x32_bf16 v[104:107], v[152:155], v[202:205], v[104:107]
	v_mfma_f32_16x16x32_bf16 v[100:103], v[180:183], v[202:205], v[100:103]
	v_mfma_f32_16x16x32_bf16 v[88:91], v[152:155], v[210:213], v[88:91]
	v_mfma_f32_16x16x32_bf16 v[84:87], v[180:183], v[210:213], v[84:87]
	v_mfma_f32_16x16x32_bf16 v[72:75], v[152:155], v[218:221], v[72:75]
	v_mfma_f32_16x16x32_bf16 v[68:71], v[180:183], v[218:221], v[68:71]
	v_mfma_f32_16x16x32_bf16 v[120:123], v[176:179], v[192:195], v[120:123]
	v_mfma_f32_16x16x32_bf16 v[116:119], v[184:187], v[192:195], v[116:119]
	v_mfma_f32_16x16x32_bf16 v[104:107], v[176:179], v[206:209], v[104:107]
	v_mfma_f32_16x16x32_bf16 v[100:103], v[184:187], v[206:209], v[100:103]
	v_mfma_f32_16x16x32_bf16 v[88:91], v[176:179], v[214:217], v[88:91]
	v_mfma_f32_16x16x32_bf16 v[84:87], v[184:187], v[214:217], v[84:87]
	v_mfma_f32_16x16x32_bf16 v[72:75], v[176:179], v[222:225], v[72:75]
	v_mfma_f32_16x16x32_bf16 v[68:71], v[184:187], v[222:225], v[68:71]
	s_setprio 0
	s_barrier
	s_add_i32 s0, s0, s45
	v_lshl_add_u64 v[226:227], v[226:227], 0, s[28:29]
	s_mov_b32 m0, s0
	ds_read_b128 v[188:191], v198 offset:49152
	ds_read_b128 v[192:195], v198 offset:50176
	ds_read_b128 v[202:205], v198 offset:51200
	ds_read_b128 v[206:209], v198 offset:52224
	ds_read_b128 v[210:213], v198 offset:53248
	ds_read_b128 v[214:217], v198 offset:54272
	ds_read_b128 v[218:221], v198 offset:55296
	ds_read_b128 v[222:225], v198 offset:56320
	global_load_lds_dwordx4 v[226:227], off
	s_add_i32 m0, s0, 0x2000
	s_add_u32 s6, s40, 0x2b0080
	v_lshl_add_u64 v[226:227], v[228:229], 0, s[28:29]
	s_addc_u32 s7, s41, 0
	s_add_i32 s0, s68, s45
	global_load_lds_dwordx4 v[226:227], off
	v_lshl_add_u64 v[226:227], s[6:7], 0, v[158:159]
	s_mov_b32 m0, s0
	s_nop 0
	global_load_lds_dwordx4 v[226:227], off
	v_lshl_add_u64 v[226:227], s[6:7], 0, v[162:163]
	s_add_i32 m0, s0, 0x2000
	s_nop 0
	global_load_lds_dwordx4 v[226:227], off
	v_lshl_add_u64 v[226:227], v[230:231], 0, s[28:29]
	s_mov_b32 m0, s54
	s_nop 0
	global_load_lds_dwordx4 v[226:227], off
	v_lshl_add_u64 v[226:227], v[232:233], 0, s[28:29]
	s_mov_b32 m0, s55
	s_nop 0
	global_load_lds_dwordx4 v[226:227], off
	s_waitcnt vmcnt(8)
	s_waitcnt lgkmcnt(0)
	s_setprio 1
	s_barrier
	v_mfma_f32_16x16x32_bf16 v[64:67], v[136:139], v[188:191], v[64:67]
	v_mfma_f32_16x16x32_bf16 v[60:63], v[144:147], v[188:191], v[60:63]
	s_add_i32 s67, s67, 2
	v_mfma_f32_16x16x32_bf16 v[48:51], v[136:139], v[202:205], v[48:51]
	s_mov_b64 s[6:7], s[8:9]
	v_mfma_f32_16x16x32_bf16 v[44:47], v[144:147], v[202:205], v[44:47]
	s_add_u32 s8, s6, 0x100
	v_mfma_f32_16x16x32_bf16 v[32:35], v[136:139], v[210:213], v[32:35]
	s_addc_u32 s9, s7, 0
	v_mfma_f32_16x16x32_bf16 v[28:31], v[144:147], v[210:213], v[28:31]
	s_add_u32 s0, s65, s6
	v_mfma_f32_16x16x32_bf16 v[16:19], v[136:139], v[218:221], v[16:19]
	s_addc_u32 s40, s66, s7
	v_mfma_f32_16x16x32_bf16 v[12:15], v[144:147], v[218:221], v[12:15]
	s_cmpk_eq_i32 s67, 0xa8
	v_mfma_f32_16x16x32_bf16 v[64:67], v[140:143], v[192:195], v[64:67]
	s_cselect_b32 s43, s50, s40
	v_mfma_f32_16x16x32_bf16 v[60:63], v[148:151], v[192:195], v[60:63]
	s_cselect_b32 s40, 0, s8
	v_mfma_f32_16x16x32_bf16 v[48:51], v[140:143], v[206:209], v[48:51]
	s_cselect_b32 s42, s51, s0
	v_mfma_f32_16x16x32_bf16 v[44:47], v[148:151], v[206:209], v[44:47]
	s_cselect_b32 s0, 0, s9
	v_mfma_f32_16x16x32_bf16 v[32:35], v[140:143], v[214:217], v[32:35]
	s_add_u32 s40, s16, s40
	v_mfma_f32_16x16x32_bf16 v[28:31], v[148:151], v[214:217], v[28:31]
	s_addc_u32 s41, s17, s0
	v_mfma_f32_16x16x32_bf16 v[16:19], v[140:143], v[222:225], v[16:19]
	s_mov_b32 m0, s58
	v_mfma_f32_16x16x32_bf16 v[12:15], v[148:151], v[222:225], v[12:15]
	s_cmpk_gt_u32 s67, 0xa9
	s_setprio 0
	s_setprio 1
	v_mfma_f32_16x16x32_bf16 v[56:59], v[152:155], v[188:191], v[56:59]
	v_mfma_f32_16x16x32_bf16 v[52:55], v[180:183], v[188:191], v[52:55]
	v_mfma_f32_16x16x32_bf16 v[40:43], v[152:155], v[202:205], v[40:43]
	v_mfma_f32_16x16x32_bf16 v[36:39], v[180:183], v[202:205], v[36:39]
	v_mfma_f32_16x16x32_bf16 v[24:27], v[152:155], v[210:213], v[24:27]
	v_mfma_f32_16x16x32_bf16 v[20:23], v[180:183], v[210:213], v[20:23]
	v_mfma_f32_16x16x32_bf16 v[8:11], v[152:155], v[218:221], v[8:11]
	v_mfma_f32_16x16x32_bf16 v[4:7], v[180:183], v[218:221], v[4:7]
	v_mfma_f32_16x16x32_bf16 v[56:59], v[176:179], v[192:195], v[56:59]
	v_mfma_f32_16x16x32_bf16 v[52:55], v[184:187], v[192:195], v[52:55]
	v_mfma_f32_16x16x32_bf16 v[40:43], v[176:179], v[206:209], v[40:43]
	v_mfma_f32_16x16x32_bf16 v[36:39], v[184:187], v[206:209], v[36:39]
	v_mfma_f32_16x16x32_bf16 v[24:27], v[176:179], v[214:217], v[24:27]
	v_mfma_f32_16x16x32_bf16 v[20:23], v[184:187], v[214:217], v[20:23]
	v_mfma_f32_16x16x32_bf16 v[8:11], v[176:179], v[222:225], v[8:11]
	v_mfma_f32_16x16x32_bf16 v[4:7], v[184:187], v[222:225], v[4:7]
	s_setprio 0
	s_barrier
	s_cbranch_scc0 .LBB0_1703
	s_and_b64 vcc, exec, s[30:31]
	s_cbranch_vccz .LBB0_1706
	s_barrier
